# on top of v008: FFN-up K-loop LDS address VALU folded into ds_read offsets; redundant lgkmcnt(0) after the super-phase barrier dropped
# baseline (speedup 1.0000x reference)
; #define PG8_STAGE(bufoff, gbase, voff) do { _Pragma("unroll") for (int _i = 0; _i < 2; ++_i) \
;         __builtin_amdgcn_global_load_lds((const unsigned*)((const char*)(gbase) + (voff)[_i]), (PG8_LAS unsigned*)(lds + (bufoff) + ldsw + _i * 8192), 16, 0, 0); } while (0)
; #define PG8_LDA(dst, b, h) do { _Pragma("unroll") for (int m = 0; m < 4; ++m) _Pragma("unroll") for (int k = 0; k < 2; ++k) dst[m][k] = *(const PG8_LAS bf16x8*)(lds + PG8_SA(b, h) + aoff + m * 2048 + k * 1024); } while (0)
; #define PG8_LDB(dst, b, h) do { _Pragma("unroll") for (int n = 0; n < 2; ++n) _Pragma("unroll") for (int k = 0; k < 2; ++k) dst[n][k] = *(const PG8_LAS bf16x8*)(lds + PG8_SB(b, h) + boff + n * 2048 + k * 1024); } while (0)
; #define PG8_MMA(ai, bj, At, Bt) do { __builtin_amdgcn_s_setprio(1); _Pragma("unroll") for (int m = 0; m < 4; ++m) _Pragma("unroll") for (int n = 0; n < 2; ++n) _Pragma("unroll") for (int k = 0; k < 2; ++k) \
;         acc[ai][bj][m][n] = __builtin_amdgcn_mfma_f32_16x16x32_bf16(Bt[n][k], At[m][k], acc[ai][bj][m][n], 0, 0, 0); __builtin_amdgcn_s_setprio(0); } while (0)
; #define PG8_WAIT_V(n) asm volatile("s_waitcnt vmcnt(" #n ")" ::: "memory")
; #define PG8_WAIT_L(n) asm volatile("s_waitcnt lgkmcnt(" #n ")" ::: "memory")
; template <class Epi, class Sched, bool ALIGN_EPI = false, bool SP2 = false>
; __device__ __forceinline__ void gemm_phase(PG8_LAS unsigned char* lds, const Gemm g, const Sched& S, const Epi& E, const int tid) {
;     ...
;             const bool last = (t == nt - 2);
;             const char* a1 = cA + (size_t)(t + 1) * kstep;
;             const char* a2 = last ? nA : cA + (size_t)(t + 2) * kstep; const char* b2 = last ? nB : cB + (size_t)(t + 2) * kstep;
;             const char* a3 = a2 + kstep; const char* b3 = b2 + kstep;
;             if (last && has_next) S.a_ready(nxt);
;             if constexpr (SP2) {
;             PG8_LDB(B0, 0, 0); PG8_LDB(B1, 0, 1); PG8_SCHED; PG8_LDA(At, 0, 0); PG8_STAGE(PG8_SA(1, 1), a1 + hstep, voffA);
;             PG8_WAIT_V(8); PG8_WAIT_L(0); PG8_BAR; PG8_MMA(0, 0, At, B0); PG8_MMA(0, 1, At, B1); PG8_BAR; PG8_SCHED;
;             PG8_LDA(At, 0, 1); PG8_STAGE(PG8_SB(0, 0), b2, voffB); PG8_STAGE(PG8_SB(0, 1), b2 + hstep, voffB); PG8_STAGE(PG8_SA(0, 0), a2, voffA);
;             PG8_WAIT_V(8); PG8_WAIT_L(0); PG8_BAR; PG8_MMA(1, 0, At, B0); PG8_MMA(1, 1, At, B1); PG8_BAR; PG8_SCHED;
.LBB0_120:
	ds_read_b128 v[122:125], v191
	ds_read_b128 v[126:129], v192
	ds_read_b128 v[138:141], v193
	ds_read_b128 v[142:145], v194
	ds_read_b128 v[146:149], v195
	ds_read_b128 v[150:153], v196
	ds_read_b128 v[164:167], v197
	ds_read_b128 v[168:171], v198
	s_add_u32 s43, s30, 0xfffc0080
	s_addc_u32 s45, s31, -1
	s_cmp_eq_u32 s27, 12
	s_cselect_b32 s87, s5, s45
	s_cselect_b32 s86, s15, s43
	s_cselect_b32 s85, s20, s26
	s_cselect_b32 s84, s21, s24
	s_mov_b32 m0, s38
	v_lshl_add_u64 v[188:189], s[30:31], 0, v[160:161]
	ds_read_b128 v[172:175], v190
	ds_read_b128 v[176:179], v190 offset:1024
	ds_read_b128 v[180:183], v190 offset:2048
	ds_read_b128 v[184:187], v190 offset:3072
	ds_read_b128 v[214:217], v190 offset:4096
	ds_read_b128 v[218:221], v190 offset:5120
	ds_read_b128 v[222:225], v190 offset:6144
	ds_read_b128 v[226:229], v190 offset:7168
	global_load_lds_dwordx4 v[188:189], off
	v_lshl_add_u64 v[188:189], s[30:31], 0, v[162:163]
	s_mov_b32 m0, s0
	s_nop 0
	global_load_lds_dwordx4 v[188:189], off
	s_waitcnt vmcnt(8)
	s_waitcnt lgkmcnt(0)
	s_barrier
	v_mfma_f32_16x16x32_bf16 v[134:137], v[122:125], v[172:175], v[134:137]
	v_mfma_f32_16x16x32_bf16 v[134:137], v[126:129], v[176:179], v[134:137]
	v_mfma_f32_16x16x32_bf16 v[130:133], v[138:141], v[172:175], v[130:133]
	v_mfma_f32_16x16x32_bf16 v[130:133], v[142:145], v[176:179], v[130:133]
	v_mfma_f32_16x16x32_bf16 v[118:121], v[122:125], v[180:183], v[118:121]
	v_mfma_f32_16x16x32_bf16 v[118:121], v[126:129], v[184:187], v[118:121]
	v_mfma_f32_16x16x32_bf16 v[114:117], v[138:141], v[180:183], v[114:117]
	v_mfma_f32_16x16x32_bf16 v[114:117], v[142:145], v[184:187], v[114:117]
	v_mfma_f32_16x16x32_bf16 v[110:113], v[122:125], v[214:217], v[110:113]
	v_mfma_f32_16x16x32_bf16 v[110:113], v[126:129], v[218:221], v[110:113]
	v_mfma_f32_16x16x32_bf16 v[106:109], v[138:141], v[214:217], v[106:109]
	v_mfma_f32_16x16x32_bf16 v[106:109], v[142:145], v[218:221], v[106:109]
	v_mfma_f32_16x16x32_bf16 v[102:105], v[122:125], v[222:225], v[102:105]
	v_mfma_f32_16x16x32_bf16 v[102:105], v[126:129], v[226:229], v[102:105]
	v_mfma_f32_16x16x32_bf16 v[98:101], v[138:141], v[222:225], v[98:101]
	v_mfma_f32_16x16x32_bf16 v[98:101], v[142:145], v[226:229], v[98:101]
	v_mfma_f32_16x16x32_bf16 v[62:65], v[146:149], v[172:175], v[62:65]
	v_mfma_f32_16x16x32_bf16 v[62:65], v[150:153], v[176:179], v[62:65]
	v_mfma_f32_16x16x32_bf16 v[58:61], v[164:167], v[172:175], v[58:61]
	v_mfma_f32_16x16x32_bf16 v[58:61], v[168:171], v[176:179], v[58:61]
	v_mfma_f32_16x16x32_bf16 v[54:57], v[146:149], v[180:183], v[54:57]
	v_mfma_f32_16x16x32_bf16 v[54:57], v[150:153], v[184:187], v[54:57]
	v_mfma_f32_16x16x32_bf16 v[50:53], v[164:167], v[180:183], v[50:53]
	v_mfma_f32_16x16x32_bf16 v[50:53], v[168:171], v[184:187], v[50:53]
	v_mfma_f32_16x16x32_bf16 v[46:49], v[146:149], v[214:217], v[46:49]
	v_mfma_f32_16x16x32_bf16 v[46:49], v[150:153], v[218:221], v[46:49]
	v_mfma_f32_16x16x32_bf16 v[42:45], v[164:167], v[214:217], v[42:45]
	v_mfma_f32_16x16x32_bf16 v[42:45], v[168:171], v[218:221], v[42:45]
	v_mfma_f32_16x16x32_bf16 v[38:41], v[146:149], v[222:225], v[38:41]
	v_mfma_f32_16x16x32_bf16 v[38:41], v[150:153], v[226:229], v[38:41]
	v_mfma_f32_16x16x32_bf16 v[34:37], v[164:167], v[222:225], v[34:37]
	v_mfma_f32_16x16x32_bf16 v[34:37], v[168:171], v[226:229], v[34:37]
	s_barrier
	s_mov_b32 m0, s6
	v_lshl_add_u64 v[188:189], s[84:85], 0, v[0:1]
	s_add_u32 s50, s84, 0x40000
	ds_read_b128 v[172:175], v190 offset:16384
	ds_read_b128 v[176:179], v190 offset:17408
	ds_read_b128 v[180:183], v190 offset:18432
	ds_read_b128 v[184:187], v190 offset:19456
	ds_read_b128 v[214:217], v190 offset:20480
	ds_read_b128 v[218:221], v190 offset:21504
	ds_read_b128 v[222:225], v190 offset:22528
	ds_read_b128 v[226:229], v190 offset:23552
	global_load_lds_dwordx4 v[188:189], off
	v_lshl_add_u64 v[208:209], s[84:85], 0, v[154:155]
	s_mov_b32 m0, s8
	s_addc_u32 s51, s85, 0
	global_load_lds_dwordx4 v[208:209], off
	v_lshl_add_u64 v[210:211], s[50:51], 0, v[0:1]
	s_mov_b32 m0, s9
	v_lshl_add_u64 v[212:213], s[86:87], 0, v[156:157]
	global_load_lds_dwordx4 v[210:211], off
	v_lshl_add_u64 v[210:211], s[50:51], 0, v[154:155]
	s_mov_b32 m0, s14
	s_nop 0
	global_load_lds_dwordx4 v[210:211], off
	v_lshl_add_u64 v[210:211], s[86:87], 0, v[158:159]
	s_mov_b32 m0, s17
	s_nop 0
	global_load_lds_dwordx4 v[210:211], off
	s_mov_b32 m0, s34
	s_nop 0
	global_load_lds_dwordx4 v[212:213], off
	s_waitcnt vmcnt(8)
	s_waitcnt lgkmcnt(0)
	s_barrier
	v_mfma_f32_16x16x32_bf16 v[94:97], v[122:125], v[172:175], v[94:97]
	v_mfma_f32_16x16x32_bf16 v[94:97], v[126:129], v[176:179], v[94:97]
	v_mfma_f32_16x16x32_bf16 v[90:93], v[138:141], v[172:175], v[90:93]
	v_mfma_f32_16x16x32_bf16 v[90:93], v[142:145], v[176:179], v[90:93]
	v_mfma_f32_16x16x32_bf16 v[86:89], v[122:125], v[180:183], v[86:89]
	v_mfma_f32_16x16x32_bf16 v[86:89], v[126:129], v[184:187], v[86:89]
	v_mfma_f32_16x16x32_bf16 v[82:85], v[138:141], v[180:183], v[82:85]
	v_mfma_f32_16x16x32_bf16 v[82:85], v[142:145], v[184:187], v[82:85]
	v_mfma_f32_16x16x32_bf16 v[78:81], v[122:125], v[214:217], v[78:81]
	v_mfma_f32_16x16x32_bf16 v[78:81], v[126:129], v[218:221], v[78:81]
	v_mfma_f32_16x16x32_bf16 v[74:77], v[138:141], v[214:217], v[74:77]
	v_mfma_f32_16x16x32_bf16 v[74:77], v[142:145], v[218:221], v[74:77]
	v_mfma_f32_16x16x32_bf16 v[70:73], v[122:125], v[222:225], v[70:73]
	v_mfma_f32_16x16x32_bf16 v[70:73], v[126:129], v[226:229], v[70:73]
	v_mfma_f32_16x16x32_bf16 v[66:69], v[138:141], v[222:225], v[66:69]
	v_mfma_f32_16x16x32_bf16 v[66:69], v[142:145], v[226:229], v[66:69]
	v_mfma_f32_16x16x32_bf16 v[30:33], v[146:149], v[172:175], v[30:33]
	v_mfma_f32_16x16x32_bf16 v[30:33], v[150:153], v[176:179], v[30:33]
	v_mfma_f32_16x16x32_bf16 v[26:29], v[164:167], v[172:175], v[26:29]
	v_mfma_f32_16x16x32_bf16 v[26:29], v[168:171], v[176:179], v[26:29]
	v_mfma_f32_16x16x32_bf16 v[22:25], v[146:149], v[180:183], v[22:25]
	v_mfma_f32_16x16x32_bf16 v[22:25], v[150:153], v[184:187], v[22:25]
	v_mfma_f32_16x16x32_bf16 v[18:21], v[164:167], v[180:183], v[18:21]
	v_mfma_f32_16x16x32_bf16 v[18:21], v[168:171], v[184:187], v[18:21]
	v_mfma_f32_16x16x32_bf16 v[14:17], v[146:149], v[214:217], v[14:17]
	v_mfma_f32_16x16x32_bf16 v[14:17], v[150:153], v[218:221], v[14:17]
	v_mfma_f32_16x16x32_bf16 v[10:13], v[164:167], v[214:217], v[10:13]
	v_mfma_f32_16x16x32_bf16 v[10:13], v[168:171], v[218:221], v[10:13]
	v_mfma_f32_16x16x32_bf16 v[6:9], v[146:149], v[222:225], v[6:9]
	v_mfma_f32_16x16x32_bf16 v[6:9], v[150:153], v[226:229], v[6:9]
	v_mfma_f32_16x16x32_bf16 v[2:5], v[164:167], v[222:225], v[2:5]
	v_mfma_f32_16x16x32_bf16 v[2:5], v[168:171], v[226:229], v[2:5]
	s_barrier
; #define PG8_STAGE(bufoff, gbase, voff) do { _Pragma("unroll") for (int _i = 0; _i < 2; ++_i) \
;         __builtin_amdgcn_global_load_lds((const unsigned*)((const char*)(gbase) + (voff)[_i]), (PG8_LAS unsigned*)(lds + (bufoff) + ldsw + _i * 8192), 16, 0, 0); } while (0)
; #define PG8_LDA(dst, b, h) do { _Pragma("unroll") for (int m = 0; m < 4; ++m) _Pragma("unroll") for (int k = 0; k < 2; ++k) dst[m][k] = *(const PG8_LAS bf16x8*)(lds + PG8_SA(b, h) + aoff + m * 2048 + k * 1024); } while (0)
; #define PG8_LDB(dst, b, h) do { _Pragma("unroll") for (int n = 0; n < 2; ++n) _Pragma("unroll") for (int k = 0; k < 2; ++k) dst[n][k] = *(const PG8_LAS bf16x8*)(lds + PG8_SB(b, h) + boff + n * 2048 + k * 1024); } while (0)
; #define PG8_MMA(ai, bj, At, Bt) do { __builtin_amdgcn_s_setprio(1); _Pragma("unroll") for (int m = 0; m < 4; ++m) _Pragma("unroll") for (int n = 0; n < 2; ++n) _Pragma("unroll") for (int k = 0; k < 2; ++k) \
;         acc[ai][bj][m][n] = __builtin_amdgcn_mfma_f32_16x16x32_bf16(Bt[n][k], At[m][k], acc[ai][bj][m][n], 0, 0, 0); __builtin_amdgcn_s_setprio(0); } while (0)
; #define PG8_WAIT_V(n) asm volatile("s_waitcnt vmcnt(" #n ")" ::: "memory")
; #define PG8_WAIT_L(n) asm volatile("s_waitcnt lgkmcnt(" #n ")" ::: "memory")
; #define PG8_BAR __builtin_amdgcn_s_barrier()
; #define PG8_SCHED __builtin_amdgcn_sched_barrier(0)
; template <class Epi, class Sched, bool ALIGN_EPI = false, bool SP2 = false>
; __device__ __forceinline__ void gemm_phase(PG8_LAS unsigned char* lds, const Gemm g, const Sched& S, const Epi& E, const int tid) {
;     ...
;             PG8_LDB(B0, 1, 0); PG8_LDB(B1, 1, 1); PG8_SCHED; PG8_LDA(At, 1, 0); PG8_STAGE(PG8_SA(0, 1), a2 + hstep, voffA);
;             PG8_WAIT_V(8); PG8_WAIT_L(0); PG8_BAR; PG8_MMA(0, 0, At, B0); PG8_MMA(0, 1, At, B1); PG8_BAR; PG8_SCHED;
;             PG8_LDA(At, 1, 1); PG8_STAGE(PG8_SB(1, 0), b3, voffB); PG8_STAGE(PG8_SB(1, 1), b3 + hstep, voffB); PG8_STAGE(PG8_SA(1, 0), a3, voffA);
;             PG8_WAIT_V(8); PG8_WAIT_L(0); PG8_BAR; PG8_MMA(1, 0, At, B0); PG8_MMA(1, 1, At, B1); PG8_BAR; PG8_SCHED;
;     ...
;         if constexpr (ALIGN_EPI) { if (wr == 0) PG8_BAR; }
	ds_read_b128 v[122:125], v199
	ds_read_b128 v[126:129], v200
	ds_read_b128 v[138:141], v201
	ds_read_b128 v[142:145], v202
	ds_read_b128 v[146:149], v203
	ds_read_b128 v[150:153], v204
	ds_read_b128 v[164:167], v205
	ds_read_b128 v[168:171], v206
	s_add_u32 s50, s86, 0x40000
	s_addc_u32 s51, s87, 0
	s_mov_b32 m0, s35
	v_lshl_add_u64 v[230:231], s[50:51], 0, v[158:159]
	ds_read_b128 v[172:175], v190 offset:32768
	ds_read_b128 v[176:179], v190 offset:33792
	ds_read_b128 v[180:183], v190 offset:34816
	ds_read_b128 v[184:187], v190 offset:35840
	ds_read_b128 v[214:217], v190 offset:36864
	ds_read_b128 v[218:221], v190 offset:37888
	ds_read_b128 v[222:225], v190 offset:38912
	ds_read_b128 v[226:229], v190 offset:39936
	global_load_lds_dwordx4 v[230:231], off
	v_lshl_add_u64 v[230:231], s[50:51], 0, v[156:157]
	s_mov_b32 m0, s88
	s_nop 0
	global_load_lds_dwordx4 v[230:231], off
	s_waitcnt vmcnt(8)
	s_waitcnt lgkmcnt(0)
	s_barrier
	v_mfma_f32_16x16x32_bf16 v[134:137], v[122:125], v[172:175], v[134:137]
	v_mfma_f32_16x16x32_bf16 v[134:137], v[126:129], v[176:179], v[134:137]
	v_mfma_f32_16x16x32_bf16 v[130:133], v[138:141], v[172:175], v[130:133]
	v_mfma_f32_16x16x32_bf16 v[130:133], v[142:145], v[176:179], v[130:133]
	v_mfma_f32_16x16x32_bf16 v[118:121], v[122:125], v[180:183], v[118:121]
	v_mfma_f32_16x16x32_bf16 v[118:121], v[126:129], v[184:187], v[118:121]
	v_mfma_f32_16x16x32_bf16 v[114:117], v[138:141], v[180:183], v[114:117]
	v_mfma_f32_16x16x32_bf16 v[114:117], v[142:145], v[184:187], v[114:117]
	v_mfma_f32_16x16x32_bf16 v[110:113], v[122:125], v[214:217], v[110:113]
	v_mfma_f32_16x16x32_bf16 v[110:113], v[126:129], v[218:221], v[110:113]
	v_mfma_f32_16x16x32_bf16 v[106:109], v[138:141], v[214:217], v[106:109]
	v_mfma_f32_16x16x32_bf16 v[106:109], v[142:145], v[218:221], v[106:109]
	v_mfma_f32_16x16x32_bf16 v[102:105], v[122:125], v[222:225], v[102:105]
	v_mfma_f32_16x16x32_bf16 v[102:105], v[126:129], v[226:229], v[102:105]
	v_mfma_f32_16x16x32_bf16 v[98:101], v[138:141], v[222:225], v[98:101]
	v_mfma_f32_16x16x32_bf16 v[98:101], v[142:145], v[226:229], v[98:101]
	v_mfma_f32_16x16x32_bf16 v[62:65], v[146:149], v[172:175], v[62:65]
	v_mfma_f32_16x16x32_bf16 v[62:65], v[150:153], v[176:179], v[62:65]
	v_mfma_f32_16x16x32_bf16 v[58:61], v[164:167], v[172:175], v[58:61]
	v_mfma_f32_16x16x32_bf16 v[58:61], v[168:171], v[176:179], v[58:61]
	v_mfma_f32_16x16x32_bf16 v[54:57], v[146:149], v[180:183], v[54:57]
	v_mfma_f32_16x16x32_bf16 v[54:57], v[150:153], v[184:187], v[54:57]
	v_mfma_f32_16x16x32_bf16 v[50:53], v[164:167], v[180:183], v[50:53]
	v_mfma_f32_16x16x32_bf16 v[50:53], v[168:171], v[184:187], v[50:53]
	v_mfma_f32_16x16x32_bf16 v[46:49], v[146:149], v[214:217], v[46:49]
	v_mfma_f32_16x16x32_bf16 v[46:49], v[150:153], v[218:221], v[46:49]
	v_mfma_f32_16x16x32_bf16 v[42:45], v[164:167], v[214:217], v[42:45]
	v_mfma_f32_16x16x32_bf16 v[42:45], v[168:171], v[218:221], v[42:45]
	v_mfma_f32_16x16x32_bf16 v[38:41], v[146:149], v[222:225], v[38:41]
	v_mfma_f32_16x16x32_bf16 v[38:41], v[150:153], v[226:229], v[38:41]
	v_mfma_f32_16x16x32_bf16 v[34:37], v[164:167], v[222:225], v[34:37]
	v_mfma_f32_16x16x32_bf16 v[34:37], v[168:171], v[226:229], v[34:37]
	s_barrier
	s_mov_b32 m0, s89
	v_lshl_add_u64 v[188:189], v[188:189], 0, s[12:13]
	s_add_u32 s50, s84, 0x40080
	ds_read_b128 v[172:175], v190 offset:49152
	ds_read_b128 v[176:179], v190 offset:50176
	ds_read_b128 v[180:183], v190 offset:51200
	ds_read_b128 v[184:187], v190 offset:52224
	ds_read_b128 v[214:217], v190 offset:53248
	ds_read_b128 v[218:221], v190 offset:54272
	ds_read_b128 v[222:225], v190 offset:55296
	ds_read_b128 v[226:229], v190 offset:56320
	global_load_lds_dwordx4 v[188:189], off
	v_lshl_add_u64 v[188:189], v[208:209], 0, s[12:13]
	s_mov_b32 m0, s90
	s_addc_u32 s51, s85, 0
	global_load_lds_dwordx4 v[188:189], off
	v_lshl_add_u64 v[188:189], s[50:51], 0, v[0:1]
	s_mov_b32 m0, s41
	s_nop 0
	global_load_lds_dwordx4 v[188:189], off
	v_lshl_add_u64 v[188:189], s[50:51], 0, v[154:155]
	s_mov_b32 m0, s40
	s_nop 0
	global_load_lds_dwordx4 v[188:189], off
	v_lshl_add_u64 v[188:189], v[210:211], 0, s[12:13]
	s_mov_b32 m0, s91
	s_nop 0
	global_load_lds_dwordx4 v[188:189], off
	v_lshl_add_u64 v[188:189], v[212:213], 0, s[12:13]
	s_mov_b32 m0, s1
	s_nop 0
	global_load_lds_dwordx4 v[188:189], off
	s_waitcnt vmcnt(8)
	s_waitcnt lgkmcnt(0)
	s_barrier
	v_mfma_f32_16x16x32_bf16 v[94:97], v[122:125], v[172:175], v[94:97]
	v_mfma_f32_16x16x32_bf16 v[94:97], v[126:129], v[176:179], v[94:97]
	v_mfma_f32_16x16x32_bf16 v[90:93], v[138:141], v[172:175], v[90:93]
	v_mfma_f32_16x16x32_bf16 v[90:93], v[142:145], v[176:179], v[90:93]
	v_mfma_f32_16x16x32_bf16 v[86:89], v[122:125], v[180:183], v[86:89]
	v_mfma_f32_16x16x32_bf16 v[86:89], v[126:129], v[184:187], v[86:89]
	v_mfma_f32_16x16x32_bf16 v[82:85], v[138:141], v[180:183], v[82:85]
	v_mfma_f32_16x16x32_bf16 v[82:85], v[142:145], v[184:187], v[82:85]
	v_mfma_f32_16x16x32_bf16 v[78:81], v[122:125], v[214:217], v[78:81]
	v_mfma_f32_16x16x32_bf16 v[78:81], v[126:129], v[218:221], v[78:81]
	v_mfma_f32_16x16x32_bf16 v[74:77], v[138:141], v[214:217], v[74:77]
	v_mfma_f32_16x16x32_bf16 v[74:77], v[142:145], v[218:221], v[74:77]
	v_mfma_f32_16x16x32_bf16 v[70:73], v[122:125], v[222:225], v[70:73]
	v_mfma_f32_16x16x32_bf16 v[70:73], v[126:129], v[226:229], v[70:73]
	v_mfma_f32_16x16x32_bf16 v[66:69], v[138:141], v[222:225], v[66:69]
	v_mfma_f32_16x16x32_bf16 v[66:69], v[142:145], v[226:229], v[66:69]
	v_mfma_f32_16x16x32_bf16 v[30:33], v[146:149], v[172:175], v[30:33]
	v_mfma_f32_16x16x32_bf16 v[30:33], v[150:153], v[176:179], v[30:33]
	v_mfma_f32_16x16x32_bf16 v[26:29], v[164:167], v[172:175], v[26:29]
	v_mfma_f32_16x16x32_bf16 v[26:29], v[168:171], v[176:179], v[26:29]
	v_mfma_f32_16x16x32_bf16 v[22:25], v[146:149], v[180:183], v[22:25]
	v_mfma_f32_16x16x32_bf16 v[22:25], v[150:153], v[184:187], v[22:25]
	v_mfma_f32_16x16x32_bf16 v[18:21], v[164:167], v[180:183], v[18:21]
	v_mfma_f32_16x16x32_bf16 v[18:21], v[168:171], v[184:187], v[18:21]
	v_mfma_f32_16x16x32_bf16 v[14:17], v[146:149], v[214:217], v[14:17]
	v_mfma_f32_16x16x32_bf16 v[14:17], v[150:153], v[218:221], v[14:17]
	v_mfma_f32_16x16x32_bf16 v[10:13], v[164:167], v[214:217], v[10:13]
	v_mfma_f32_16x16x32_bf16 v[10:13], v[168:171], v[218:221], v[10:13]
	v_mfma_f32_16x16x32_bf16 v[6:9], v[146:149], v[222:225], v[6:9]
	v_mfma_f32_16x16x32_bf16 v[6:9], v[150:153], v[226:229], v[6:9]
	v_mfma_f32_16x16x32_bf16 v[2:5], v[164:167], v[222:225], v[2:5]
	v_mfma_f32_16x16x32_bf16 v[2:5], v[168:171], v[226:229], v[2:5]
	s_barrier
	s_add_i32 s27, s27, 2
	s_add_u32 s30, s30, 0x100
	s_addc_u32 s31, s31, 0
	s_add_u32 s24, s24, 0x100
	s_addc_u32 s26, s26, 0
	s_cmp_gt_u32 s27, 13
	s_cbranch_scc0 .LBB0_120
	v_readlane_b32 s20, v255, 54
	v_readlane_b32 s21, v255, 55
	s_and_b64 vcc, exec, s[20:21]
	s_cbranch_vccz .LBB0_123
	s_barrier

; #define PG8_STAGE(bufoff, gbase, voff) do { _Pragma("unroll") for (int _i = 0; _i < 2; ++_i) \
;         __builtin_amdgcn_global_load_lds((const unsigned*)((const char*)(gbase) + (voff)[_i]), (PG8_LAS unsigned*)(lds + (bufoff) + ldsw + _i * 8192), 16, 0, 0); } while (0)
; #define PG8_LDA(dst, b, h) do { _Pragma("unroll") for (int m = 0; m < 4; ++m) _Pragma("unroll") for (int k = 0; k < 2; ++k) dst[m][k] = *(const PG8_LAS bf16x8*)(lds + PG8_SA(b, h) + aoff + m * 2048 + k * 1024); } while (0)
; #define PG8_LDB(dst, b, h) do { _Pragma("unroll") for (int n = 0; n < 2; ++n) _Pragma("unroll") for (int k = 0; k < 2; ++k) dst[n][k] = *(const PG8_LAS bf16x8*)(lds + PG8_SB(b, h) + boff + n * 2048 + k * 1024); } while (0)
; #define PG8_MMA(ai, bj, At, Bt) do { __builtin_amdgcn_s_setprio(1); _Pragma("unroll") for (int m = 0; m < 4; ++m) _Pragma("unroll") for (int n = 0; n < 2; ++n) _Pragma("unroll") for (int k = 0; k < 2; ++k) \
;         acc[ai][bj][m][n] = __builtin_amdgcn_mfma_f32_16x16x32_bf16(Bt[n][k], At[m][k], acc[ai][bj][m][n], 0, 0, 0); __builtin_amdgcn_s_setprio(0); } while (0)
; #define PG8_WAIT_V(n) asm volatile("s_waitcnt vmcnt(" #n ")" ::: "memory")
; #define PG8_WAIT_L(n) asm volatile("s_waitcnt lgkmcnt(" #n ")" ::: "memory")
; template <class Epi, class Sched, bool ALIGN_EPI = false, bool SP2 = false>
; __device__ __forceinline__ void gemm_phase(PG8_LAS unsigned char* lds, const Gemm g, const Sched& S, const Epi& E, const int tid) {
;     ...
;             const bool last = (t == nt - 2);
;             const char* a1 = cA + (size_t)(t + 1) * kstep;
;             const char* a2 = last ? nA : cA + (size_t)(t + 2) * kstep; const char* b2 = last ? nB : cB + (size_t)(t + 2) * kstep;
;             const char* a3 = a2 + kstep; const char* b3 = b2 + kstep;
;             if (last && has_next) S.a_ready(nxt);
;             if constexpr (SP2) {
;             PG8_LDB(B0, 0, 0); PG8_LDB(B1, 0, 1); PG8_SCHED; PG8_LDA(At, 0, 0); PG8_STAGE(PG8_SA(1, 1), a1 + hstep, voffA);
;             PG8_WAIT_V(8); PG8_WAIT_L(0); PG8_BAR; PG8_MMA(0, 0, At, B0); PG8_MMA(0, 1, At, B1); PG8_BAR; PG8_SCHED;
;             PG8_LDA(At, 0, 1); PG8_STAGE(PG8_SB(0, 0), b2, voffB); PG8_STAGE(PG8_SB(0, 1), b2 + hstep, voffB); PG8_STAGE(PG8_SA(0, 0), a2, voffA);
;             PG8_WAIT_V(8); PG8_WAIT_L(0); PG8_BAR; PG8_MMA(1, 0, At, B0); PG8_MMA(1, 1, At, B1); PG8_BAR; PG8_SCHED;
.LBB0_355:
	v_or_b32_e32 v98, 0x10000, v187
	v_add_u32_e32 v102, 0x10400, v187
	v_add_u32_e32 v130, 0x10800, v187
	v_add_u32_e32 v142, 0x10c00, v187
	v_or_b32_e32 v146, 0x14000, v187
	v_add_u32_e32 v160, 0x14400, v187
	v_add_u32_e32 v164, 0x14800, v187
	v_add_u32_e32 v168, 0x14c00, v187
	ds_read_b128 v[98:101], v98
	ds_read_b128 v[102:105], v102
	ds_read_b128 v[130:133], v130
	ds_read_b128 v[142:145], v142
	ds_read_b128 v[146:149], v146
	ds_read_b128 v[160:163], v160
	ds_read_b128 v[164:167], v164
	ds_read_b128 v[168:171], v168
	s_add_u32 s26, s30, 0xfffc0080
	s_addc_u32 s27, s31, -1
	s_cmp_eq_u32 s24, 12
	s_cselect_b32 s87, s4, s27
	s_cselect_b32 s86, s5, s26
	s_cselect_b32 s85, s15, s21
	s_cselect_b32 s84, s17, s20
	v_lshl_add_u64 v[180:181], s[30:31], 0, v[156:157]
	s_add_i32 m0, s6, 0xc000
	ds_read_b128 v[172:175], v186
	ds_read_b128 v[176:179], v186 offset:1024
	ds_read_b128 v[188:191], v186 offset:2048
	ds_read_b128 v[192:195], v186 offset:3072
	ds_read_b128 v[196:199], v186 offset:4096
	ds_read_b128 v[200:203], v186 offset:5120
	ds_read_b128 v[204:207], v186 offset:6144
	ds_read_b128 v[214:217], v186 offset:7168
	global_load_lds_dwordx4 v[180:181], off
	v_lshl_add_u64 v[180:181], s[30:31], 0, v[158:159]
	s_add_i32 m0, s6, 0xe000
	s_nop 0
	global_load_lds_dwordx4 v[180:181], off
	s_waitcnt vmcnt(8)
	s_waitcnt lgkmcnt(0)
	s_barrier
	v_mfma_f32_16x16x32_bf16 v[138:141], v[98:101], v[172:175], v[138:141]
	v_mfma_f32_16x16x32_bf16 v[138:141], v[102:105], v[176:179], v[138:141]
	v_mfma_f32_16x16x32_bf16 v[134:137], v[130:133], v[172:175], v[134:137]
	v_mfma_f32_16x16x32_bf16 v[134:137], v[142:145], v[176:179], v[134:137]
	v_mfma_f32_16x16x32_bf16 v[126:129], v[98:101], v[188:191], v[126:129]
	v_mfma_f32_16x16x32_bf16 v[126:129], v[102:105], v[192:195], v[126:129]
	v_mfma_f32_16x16x32_bf16 v[122:125], v[130:133], v[188:191], v[122:125]
	v_mfma_f32_16x16x32_bf16 v[122:125], v[142:145], v[192:195], v[122:125]
	v_mfma_f32_16x16x32_bf16 v[118:121], v[98:101], v[196:199], v[118:121]
	v_mfma_f32_16x16x32_bf16 v[118:121], v[102:105], v[200:203], v[118:121]
	v_mfma_f32_16x16x32_bf16 v[114:117], v[130:133], v[196:199], v[114:117]
	v_mfma_f32_16x16x32_bf16 v[114:117], v[142:145], v[200:203], v[114:117]
	v_mfma_f32_16x16x32_bf16 v[110:113], v[98:101], v[204:207], v[110:113]
	v_mfma_f32_16x16x32_bf16 v[110:113], v[102:105], v[214:217], v[110:113]
	v_mfma_f32_16x16x32_bf16 v[106:109], v[130:133], v[204:207], v[106:109]
	v_mfma_f32_16x16x32_bf16 v[106:109], v[142:145], v[214:217], v[106:109]
	v_mfma_f32_16x16x32_bf16 v[62:65], v[146:149], v[172:175], v[62:65]
	v_mfma_f32_16x16x32_bf16 v[62:65], v[160:163], v[176:179], v[62:65]
	v_mfma_f32_16x16x32_bf16 v[58:61], v[164:167], v[172:175], v[58:61]
	v_mfma_f32_16x16x32_bf16 v[58:61], v[168:171], v[176:179], v[58:61]
	v_mfma_f32_16x16x32_bf16 v[54:57], v[146:149], v[188:191], v[54:57]
	v_mfma_f32_16x16x32_bf16 v[54:57], v[160:163], v[192:195], v[54:57]
	v_mfma_f32_16x16x32_bf16 v[50:53], v[164:167], v[188:191], v[50:53]
	v_mfma_f32_16x16x32_bf16 v[50:53], v[168:171], v[192:195], v[50:53]
	v_mfma_f32_16x16x32_bf16 v[46:49], v[146:149], v[196:199], v[46:49]
	v_mfma_f32_16x16x32_bf16 v[46:49], v[160:163], v[200:203], v[46:49]
	v_mfma_f32_16x16x32_bf16 v[42:45], v[164:167], v[196:199], v[42:45]
	v_mfma_f32_16x16x32_bf16 v[42:45], v[168:171], v[200:203], v[42:45]
	v_mfma_f32_16x16x32_bf16 v[38:41], v[146:149], v[204:207], v[38:41]
	v_mfma_f32_16x16x32_bf16 v[38:41], v[160:163], v[214:217], v[38:41]
	v_mfma_f32_16x16x32_bf16 v[34:37], v[164:167], v[204:207], v[34:37]
	v_mfma_f32_16x16x32_bf16 v[34:37], v[168:171], v[214:217], v[34:37]
	s_barrier
	s_mov_b32 m0, s35
	v_lshl_add_u64 v[180:181], s[84:85], 0, v[0:1]
	s_add_u32 s26, s84, 0x40000
	ds_read_b128 v[172:175], v186 offset:16384
	ds_read_b128 v[176:179], v186 offset:17408
	ds_read_b128 v[188:191], v186 offset:18432
	ds_read_b128 v[192:195], v186 offset:19456
	ds_read_b128 v[196:199], v186 offset:20480
	ds_read_b128 v[200:203], v186 offset:21504
	ds_read_b128 v[204:207], v186 offset:22528
	ds_read_b128 v[214:217], v186 offset:23552
	global_load_lds_dwordx4 v[180:181], off
	v_lshl_add_u64 v[182:183], s[84:85], 0, v[150:151]
	s_mov_b32 m0, s88
	s_addc_u32 s27, s85, 0
	global_load_lds_dwordx4 v[182:183], off
	v_lshl_add_u64 v[184:185], s[26:27], 0, v[0:1]
	s_mov_b32 m0, s89
	v_lshl_add_u64 v[218:219], s[86:87], 0, v[152:153]
	global_load_lds_dwordx4 v[184:185], off
	v_lshl_add_u64 v[184:185], s[26:27], 0, v[150:151]
	s_mov_b32 m0, s90
	s_nop 0
	global_load_lds_dwordx4 v[184:185], off
	v_lshl_add_u64 v[184:185], s[86:87], 0, v[154:155]
	s_mov_b32 m0, s6
	s_nop 0
	global_load_lds_dwordx4 v[184:185], off
	s_mov_b32 m0, s91
	s_nop 0
	global_load_lds_dwordx4 v[218:219], off
	s_waitcnt vmcnt(8)
	s_waitcnt lgkmcnt(0)
	s_barrier
; #define PG8_STAGE(bufoff, gbase, voff) do { _Pragma("unroll") for (int _i = 0; _i < 2; ++_i) \
;         __builtin_amdgcn_global_load_lds((const unsigned*)((const char*)(gbase) + (voff)[_i]), (PG8_LAS unsigned*)(lds + (bufoff) + ldsw + _i * 8192), 16, 0, 0); } while (0)
; #define PG8_LDA(dst, b, h) do { _Pragma("unroll") for (int m = 0; m < 4; ++m) _Pragma("unroll") for (int k = 0; k < 2; ++k) dst[m][k] = *(const PG8_LAS bf16x8*)(lds + PG8_SA(b, h) + aoff + m * 2048 + k * 1024); } while (0)
; #define PG8_LDB(dst, b, h) do { _Pragma("unroll") for (int n = 0; n < 2; ++n) _Pragma("unroll") for (int k = 0; k < 2; ++k) dst[n][k] = *(const PG8_LAS bf16x8*)(lds + PG8_SB(b, h) + boff + n * 2048 + k * 1024); } while (0)
; #define PG8_MMA(ai, bj, At, Bt) do { __builtin_amdgcn_s_setprio(1); _Pragma("unroll") for (int m = 0; m < 4; ++m) _Pragma("unroll") for (int n = 0; n < 2; ++n) _Pragma("unroll") for (int k = 0; k < 2; ++k) \
;         acc[ai][bj][m][n] = __builtin_amdgcn_mfma_f32_16x16x32_bf16(Bt[n][k], At[m][k], acc[ai][bj][m][n], 0, 0, 0); __builtin_amdgcn_s_setprio(0); } while (0)
; #define PG8_WAIT_V(n) asm volatile("s_waitcnt vmcnt(" #n ")" ::: "memory")
; #define PG8_WAIT_L(n) asm volatile("s_waitcnt lgkmcnt(" #n ")" ::: "memory")
; #define PG8_BAR __builtin_amdgcn_s_barrier()
; #define PG8_SCHED __builtin_amdgcn_sched_barrier(0)
; template <class Epi, class Sched, bool ALIGN_EPI = false, bool SP2 = false>
; __device__ __forceinline__ void gemm_phase(PG8_LAS unsigned char* lds, const Gemm g, const Sched& S, const Epi& E, const int tid) {
;     ...
;             PG8_WAIT_V(8); PG8_WAIT_L(0); PG8_BAR; PG8_MMA(1, 0, At, B0); PG8_MMA(1, 1, At, B1); PG8_BAR; PG8_SCHED;
;             PG8_LDB(B0, 1, 0); PG8_LDB(B1, 1, 1); PG8_SCHED; PG8_LDA(At, 1, 0); PG8_STAGE(PG8_SA(0, 1), a2 + hstep, voffA);
;             PG8_WAIT_V(8); PG8_WAIT_L(0); PG8_BAR; PG8_MMA(0, 0, At, B0); PG8_MMA(0, 1, At, B1); PG8_BAR; PG8_SCHED;
	v_mfma_f32_16x16x32_bf16 v[94:97], v[98:101], v[172:175], v[94:97]
	v_mfma_f32_16x16x32_bf16 v[94:97], v[102:105], v[176:179], v[94:97]
	v_mfma_f32_16x16x32_bf16 v[90:93], v[130:133], v[172:175], v[90:93]
	v_mfma_f32_16x16x32_bf16 v[90:93], v[142:145], v[176:179], v[90:93]
	v_mfma_f32_16x16x32_bf16 v[86:89], v[98:101], v[188:191], v[86:89]
	v_mfma_f32_16x16x32_bf16 v[86:89], v[102:105], v[192:195], v[86:89]
	v_mfma_f32_16x16x32_bf16 v[82:85], v[130:133], v[188:191], v[82:85]
	v_mfma_f32_16x16x32_bf16 v[82:85], v[142:145], v[192:195], v[82:85]
	v_mfma_f32_16x16x32_bf16 v[78:81], v[98:101], v[196:199], v[78:81]
	v_mfma_f32_16x16x32_bf16 v[78:81], v[102:105], v[200:203], v[78:81]
	v_mfma_f32_16x16x32_bf16 v[74:77], v[130:133], v[196:199], v[74:77]
	v_mfma_f32_16x16x32_bf16 v[74:77], v[142:145], v[200:203], v[74:77]
	v_mfma_f32_16x16x32_bf16 v[70:73], v[98:101], v[204:207], v[70:73]
	v_mfma_f32_16x16x32_bf16 v[70:73], v[102:105], v[214:217], v[70:73]
	v_mfma_f32_16x16x32_bf16 v[66:69], v[130:133], v[204:207], v[66:69]
	v_mfma_f32_16x16x32_bf16 v[66:69], v[142:145], v[214:217], v[66:69]
	v_mfma_f32_16x16x32_bf16 v[30:33], v[146:149], v[172:175], v[30:33]
	v_mfma_f32_16x16x32_bf16 v[30:33], v[160:163], v[176:179], v[30:33]
	v_mfma_f32_16x16x32_bf16 v[26:29], v[164:167], v[172:175], v[26:29]
	v_mfma_f32_16x16x32_bf16 v[26:29], v[168:171], v[176:179], v[26:29]
	v_mfma_f32_16x16x32_bf16 v[22:25], v[146:149], v[188:191], v[22:25]
	v_mfma_f32_16x16x32_bf16 v[22:25], v[160:163], v[192:195], v[22:25]
	v_mfma_f32_16x16x32_bf16 v[18:21], v[164:167], v[188:191], v[18:21]
	v_mfma_f32_16x16x32_bf16 v[18:21], v[168:171], v[192:195], v[18:21]
	v_mfma_f32_16x16x32_bf16 v[14:17], v[146:149], v[196:199], v[14:17]
	v_mfma_f32_16x16x32_bf16 v[14:17], v[160:163], v[200:203], v[14:17]
	v_mfma_f32_16x16x32_bf16 v[10:13], v[164:167], v[196:199], v[10:13]
	v_mfma_f32_16x16x32_bf16 v[10:13], v[168:171], v[200:203], v[10:13]
	v_mfma_f32_16x16x32_bf16 v[6:9], v[146:149], v[204:207], v[6:9]
	v_mfma_f32_16x16x32_bf16 v[6:9], v[160:163], v[214:217], v[6:9]
	v_mfma_f32_16x16x32_bf16 v[2:5], v[164:167], v[204:207], v[2:5]
	v_mfma_f32_16x16x32_bf16 v[2:5], v[168:171], v[214:217], v[2:5]
	s_barrier
	v_or_b32_e32 v98, 0x18000, v187
	v_add_u32_e32 v102, 0x18400, v187
	v_add_u32_e32 v130, 0x18800, v187
	v_add_u32_e32 v142, 0x18c00, v187
	v_or_b32_e32 v146, 0x1c000, v187
	v_add_u32_e32 v160, 0x1c400, v187
	v_add_u32_e32 v164, 0x1c800, v187
	v_add_u32_e32 v168, 0x1cc00, v187
	ds_read_b128 v[98:101], v98
	ds_read_b128 v[102:105], v102
	ds_read_b128 v[130:133], v130
	ds_read_b128 v[142:145], v142
	ds_read_b128 v[146:149], v146
	ds_read_b128 v[160:163], v160
	ds_read_b128 v[164:167], v164
	ds_read_b128 v[168:171], v168
	s_add_u32 s26, s86, 0x40000
	s_addc_u32 s27, s87, 0
	s_mov_b32 m0, s42
	v_lshl_add_u64 v[220:221], s[26:27], 0, v[154:155]
	ds_read_b128 v[172:175], v186 offset:32768
	ds_read_b128 v[176:179], v186 offset:33792
	ds_read_b128 v[188:191], v186 offset:34816
	ds_read_b128 v[192:195], v186 offset:35840
	ds_read_b128 v[196:199], v186 offset:36864
	ds_read_b128 v[200:203], v186 offset:37888
	ds_read_b128 v[204:207], v186 offset:38912
	ds_read_b128 v[214:217], v186 offset:39936
	global_load_lds_dwordx4 v[220:221], off
	v_lshl_add_u64 v[220:221], s[26:27], 0, v[152:153]
	s_mov_b32 m0, s43
	s_nop 0
	global_load_lds_dwordx4 v[220:221], off
	s_waitcnt vmcnt(8)
	s_waitcnt lgkmcnt(0)
	s_barrier
	v_mfma_f32_16x16x32_bf16 v[138:141], v[98:101], v[172:175], v[138:141]
	v_mfma_f32_16x16x32_bf16 v[138:141], v[102:105], v[176:179], v[138:141]
	v_mfma_f32_16x16x32_bf16 v[134:137], v[130:133], v[172:175], v[134:137]
	v_mfma_f32_16x16x32_bf16 v[134:137], v[142:145], v[176:179], v[134:137]
	v_mfma_f32_16x16x32_bf16 v[126:129], v[98:101], v[188:191], v[126:129]
	v_mfma_f32_16x16x32_bf16 v[126:129], v[102:105], v[192:195], v[126:129]
	v_mfma_f32_16x16x32_bf16 v[122:125], v[130:133], v[188:191], v[122:125]
	v_mfma_f32_16x16x32_bf16 v[122:125], v[142:145], v[192:195], v[122:125]
	v_mfma_f32_16x16x32_bf16 v[118:121], v[98:101], v[196:199], v[118:121]
	v_mfma_f32_16x16x32_bf16 v[118:121], v[102:105], v[200:203], v[118:121]
	v_mfma_f32_16x16x32_bf16 v[114:117], v[130:133], v[196:199], v[114:117]
	v_mfma_f32_16x16x32_bf16 v[114:117], v[142:145], v[200:203], v[114:117]
	v_mfma_f32_16x16x32_bf16 v[110:113], v[98:101], v[204:207], v[110:113]
	v_mfma_f32_16x16x32_bf16 v[110:113], v[102:105], v[214:217], v[110:113]
	v_mfma_f32_16x16x32_bf16 v[106:109], v[130:133], v[204:207], v[106:109]
	v_mfma_f32_16x16x32_bf16 v[106:109], v[142:145], v[214:217], v[106:109]
	v_mfma_f32_16x16x32_bf16 v[62:65], v[146:149], v[172:175], v[62:65]
	v_mfma_f32_16x16x32_bf16 v[62:65], v[160:163], v[176:179], v[62:65]
	v_mfma_f32_16x16x32_bf16 v[58:61], v[164:167], v[172:175], v[58:61]
	v_mfma_f32_16x16x32_bf16 v[58:61], v[168:171], v[176:179], v[58:61]
	v_mfma_f32_16x16x32_bf16 v[54:57], v[146:149], v[188:191], v[54:57]
	v_mfma_f32_16x16x32_bf16 v[54:57], v[160:163], v[192:195], v[54:57]
	v_mfma_f32_16x16x32_bf16 v[50:53], v[164:167], v[188:191], v[50:53]
	v_mfma_f32_16x16x32_bf16 v[50:53], v[168:171], v[192:195], v[50:53]
	v_mfma_f32_16x16x32_bf16 v[46:49], v[146:149], v[196:199], v[46:49]
	v_mfma_f32_16x16x32_bf16 v[46:49], v[160:163], v[200:203], v[46:49]
	v_mfma_f32_16x16x32_bf16 v[42:45], v[164:167], v[196:199], v[42:45]
	v_mfma_f32_16x16x32_bf16 v[42:45], v[168:171], v[200:203], v[42:45]
	v_mfma_f32_16x16x32_bf16 v[38:41], v[146:149], v[204:207], v[38:41]
	v_mfma_f32_16x16x32_bf16 v[38:41], v[160:163], v[214:217], v[38:41]
	v_mfma_f32_16x16x32_bf16 v[34:37], v[164:167], v[204:207], v[34:37]
	v_mfma_f32_16x16x32_bf16 v[34:37], v[168:171], v[214:217], v[34:37]
	s_barrier
; #define PG8_STAGE(bufoff, gbase, voff) do { _Pragma("unroll") for (int _i = 0; _i < 2; ++_i) \
;         __builtin_amdgcn_global_load_lds((const unsigned*)((const char*)(gbase) + (voff)[_i]), (PG8_LAS unsigned*)(lds + (bufoff) + ldsw + _i * 8192), 16, 0, 0); } while (0)
; #define PG8_LDA(dst, b, h) do { _Pragma("unroll") for (int m = 0; m < 4; ++m) _Pragma("unroll") for (int k = 0; k < 2; ++k) dst[m][k] = *(const PG8_LAS bf16x8*)(lds + PG8_SA(b, h) + aoff + m * 2048 + k * 1024); } while (0)
; #define PG8_MMA(ai, bj, At, Bt) do { __builtin_amdgcn_s_setprio(1); _Pragma("unroll") for (int m = 0; m < 4; ++m) _Pragma("unroll") for (int n = 0; n < 2; ++n) _Pragma("unroll") for (int k = 0; k < 2; ++k) \
;         acc[ai][bj][m][n] = __builtin_amdgcn_mfma_f32_16x16x32_bf16(Bt[n][k], At[m][k], acc[ai][bj][m][n], 0, 0, 0); __builtin_amdgcn_s_setprio(0); } while (0)
; #define PG8_WAIT_V(n) asm volatile("s_waitcnt vmcnt(" #n ")" ::: "memory")
; #define PG8_WAIT_L(n) asm volatile("s_waitcnt lgkmcnt(" #n ")" ::: "memory")
; #define PG8_BAR __builtin_amdgcn_s_barrier()
; #define PG8_SCHED __builtin_amdgcn_sched_barrier(0)
; template <class Epi, class Sched, bool ALIGN_EPI = false, bool SP2 = false>
; __device__ __forceinline__ void gemm_phase(PG8_LAS unsigned char* lds, const Gemm g, const Sched& S, const Epi& E, const int tid) {
;     ...
;             PG8_LDA(At, 1, 1); PG8_STAGE(PG8_SB(1, 0), b3, voffB); PG8_STAGE(PG8_SB(1, 1), b3 + hstep, voffB); PG8_STAGE(PG8_SA(1, 0), a3, voffA);
;             PG8_WAIT_V(8); PG8_WAIT_L(0); PG8_BAR; PG8_MMA(1, 0, At, B0); PG8_MMA(1, 1, At, B1); PG8_BAR; PG8_SCHED;
;     ...
;         if constexpr (ALIGN_EPI) { if (wr == 0) PG8_BAR; }
	s_mov_b32 m0, s40
	v_lshl_add_u64 v[180:181], v[180:181], 0, s[12:13]
	s_add_u32 s26, s84, 0x40080
	ds_read_b128 v[172:175], v186 offset:49152
	ds_read_b128 v[176:179], v186 offset:50176
	ds_read_b128 v[188:191], v186 offset:51200
	ds_read_b128 v[192:195], v186 offset:52224
	ds_read_b128 v[196:199], v186 offset:53248
	ds_read_b128 v[200:203], v186 offset:54272
	ds_read_b128 v[204:207], v186 offset:55296
	ds_read_b128 v[214:217], v186 offset:56320
	global_load_lds_dwordx4 v[180:181], off
	v_lshl_add_u64 v[180:181], v[182:183], 0, s[12:13]
	s_mov_b32 m0, s41
	s_addc_u32 s27, s85, 0
	global_load_lds_dwordx4 v[180:181], off
	v_lshl_add_u64 v[180:181], s[26:27], 0, v[0:1]
	s_mov_b32 m0, s34
	s_nop 0
	global_load_lds_dwordx4 v[180:181], off
	v_lshl_add_u64 v[180:181], s[26:27], 0, v[150:151]
	s_mov_b32 m0, s8
	s_nop 0
	global_load_lds_dwordx4 v[180:181], off
	v_lshl_add_u64 v[180:181], v[184:185], 0, s[12:13]
	s_mov_b32 m0, s1
	s_nop 0
	global_load_lds_dwordx4 v[180:181], off
	v_lshl_add_u64 v[180:181], v[218:219], 0, s[12:13]
	s_mov_b32 m0, s14
	s_nop 0
	global_load_lds_dwordx4 v[180:181], off
	s_waitcnt vmcnt(8)
	s_waitcnt lgkmcnt(0)
	s_barrier
	v_mfma_f32_16x16x32_bf16 v[94:97], v[98:101], v[172:175], v[94:97]
	v_mfma_f32_16x16x32_bf16 v[94:97], v[102:105], v[176:179], v[94:97]
	v_mfma_f32_16x16x32_bf16 v[90:93], v[130:133], v[172:175], v[90:93]
	v_mfma_f32_16x16x32_bf16 v[90:93], v[142:145], v[176:179], v[90:93]
	v_mfma_f32_16x16x32_bf16 v[86:89], v[98:101], v[188:191], v[86:89]
	v_mfma_f32_16x16x32_bf16 v[86:89], v[102:105], v[192:195], v[86:89]
	v_mfma_f32_16x16x32_bf16 v[82:85], v[130:133], v[188:191], v[82:85]
	v_mfma_f32_16x16x32_bf16 v[82:85], v[142:145], v[192:195], v[82:85]
	v_mfma_f32_16x16x32_bf16 v[78:81], v[98:101], v[196:199], v[78:81]
	v_mfma_f32_16x16x32_bf16 v[78:81], v[102:105], v[200:203], v[78:81]
	v_mfma_f32_16x16x32_bf16 v[74:77], v[130:133], v[196:199], v[74:77]
	v_mfma_f32_16x16x32_bf16 v[74:77], v[142:145], v[200:203], v[74:77]
	v_mfma_f32_16x16x32_bf16 v[70:73], v[98:101], v[204:207], v[70:73]
	v_mfma_f32_16x16x32_bf16 v[70:73], v[102:105], v[214:217], v[70:73]
	v_mfma_f32_16x16x32_bf16 v[66:69], v[130:133], v[204:207], v[66:69]
	v_mfma_f32_16x16x32_bf16 v[66:69], v[142:145], v[214:217], v[66:69]
	v_mfma_f32_16x16x32_bf16 v[30:33], v[146:149], v[172:175], v[30:33]
	v_mfma_f32_16x16x32_bf16 v[30:33], v[160:163], v[176:179], v[30:33]
	v_mfma_f32_16x16x32_bf16 v[26:29], v[164:167], v[172:175], v[26:29]
	v_mfma_f32_16x16x32_bf16 v[26:29], v[168:171], v[176:179], v[26:29]
	v_mfma_f32_16x16x32_bf16 v[22:25], v[146:149], v[188:191], v[22:25]
	v_mfma_f32_16x16x32_bf16 v[22:25], v[160:163], v[192:195], v[22:25]
	v_mfma_f32_16x16x32_bf16 v[18:21], v[164:167], v[188:191], v[18:21]
	v_mfma_f32_16x16x32_bf16 v[18:21], v[168:171], v[192:195], v[18:21]
	v_mfma_f32_16x16x32_bf16 v[14:17], v[146:149], v[196:199], v[14:17]
	v_mfma_f32_16x16x32_bf16 v[14:17], v[160:163], v[200:203], v[14:17]
	v_mfma_f32_16x16x32_bf16 v[10:13], v[164:167], v[196:199], v[10:13]
	v_mfma_f32_16x16x32_bf16 v[10:13], v[168:171], v[200:203], v[10:13]
	v_mfma_f32_16x16x32_bf16 v[6:9], v[146:149], v[204:207], v[6:9]
	v_mfma_f32_16x16x32_bf16 v[6:9], v[160:163], v[214:217], v[6:9]
	v_mfma_f32_16x16x32_bf16 v[2:5], v[164:167], v[204:207], v[2:5]
	v_mfma_f32_16x16x32_bf16 v[2:5], v[168:171], v[214:217], v[2:5]
	s_barrier
	s_add_i32 s24, s24, 2
	s_add_u32 s30, s30, 0x100
	s_addc_u32 s31, s31, 0
	s_add_u32 s20, s20, 0x100
	s_addc_u32 s21, s21, 0
	s_cmp_gt_u32 s24, 13
	s_cbranch_scc0 .LBB0_355
	v_readlane_b32 s4, v255, 54
	v_readlane_b32 s5, v255, 55
	s_and_b64 vcc, exec, s[4:5]
	s_cbranch_vccz .LBB0_358
	s_barrier

; #define PG8_STAGE(bufoff, gbase, voff) do { _Pragma("unroll") for (int _i = 0; _i < 2; ++_i) \
;         __builtin_amdgcn_global_load_lds((const unsigned*)((const char*)(gbase) + (voff)[_i]), (PG8_LAS unsigned*)(lds + (bufoff) + ldsw + _i * 8192), 16, 0, 0); } while (0)
; #define PG8_LDA(dst, b, h) do { _Pragma("unroll") for (int m = 0; m < 4; ++m) _Pragma("unroll") for (int k = 0; k < 2; ++k) dst[m][k] = *(const PG8_LAS bf16x8*)(lds + PG8_SA(b, h) + aoff + m * 2048 + k * 1024); } while (0)
; #define PG8_LDB(dst, b, h) do { _Pragma("unroll") for (int n = 0; n < 2; ++n) _Pragma("unroll") for (int k = 0; k < 2; ++k) dst[n][k] = *(const PG8_LAS bf16x8*)(lds + PG8_SB(b, h) + boff + n * 2048 + k * 1024); } while (0)
; #define PG8_WAIT_V(n) asm volatile("s_waitcnt vmcnt(" #n ")" ::: "memory")
; #define PG8_WAIT_L(n) asm volatile("s_waitcnt lgkmcnt(" #n ")" ::: "memory")
; #define PG8_BAR __builtin_amdgcn_s_barrier()
; #define PG8_SCHED __builtin_amdgcn_sched_barrier(0)
; template <class Epi, class Sched, bool ALIGN_EPI = false, bool SP2 = false>
; __device__ __forceinline__ void gemm_phase(PG8_LAS unsigned char* lds, const Gemm g, const Sched& S, const Epi& E, const int tid) {
;     ...
;         const char* nA = has_next ? (const char*)g.A + (size_t)nxt.pm * tstep : cA; const char* nB = has_next ? (const char*)g.Bt + (size_t)nxt.pn * tstep : cB;
;         for (int t = 0; t < nt; t += 2) {
;             const bool last = (t == nt - 2);
;             const char* a1 = cA + (size_t)(t + 1) * kstep;
;             const char* a2 = last ? nA : cA + (size_t)(t + 2) * kstep; const char* b2 = last ? nB : cB + (size_t)(t + 2) * kstep;
;             const char* a3 = a2 + kstep; const char* b3 = b2 + kstep;
;             if (last && has_next) S.a_ready(nxt);
;             if constexpr (SP2) {
;             PG8_LDB(B0, 0, 0); PG8_LDB(B1, 0, 1); PG8_SCHED; PG8_LDA(At, 0, 0); PG8_STAGE(PG8_SA(1, 1), a1 + hstep, voffA);
;             PG8_WAIT_V(8); PG8_WAIT_L(0); PG8_BAR; PG8_MMA(0, 0, At, B0); PG8_MMA(0, 1, At, B1); PG8_BAR; PG8_SCHED;
;             PG8_LDA(At, 0, 1); PG8_STAGE(PG8_SB(0, 0), b2, voffB); PG8_STAGE(PG8_SB(0, 1), b2 + hstep, voffB); PG8_STAGE(PG8_SA(0, 0), a2, voffA);
;             PG8_WAIT_V(8); PG8_WAIT_L(0); PG8_BAR; PG8_MMA(1, 0, At, B0); PG8_MMA(1, 1, At, B1); PG8_BAR; PG8_SCHED;
.LBB0_370:
	s_ashr_i32 s43, s42, 31
	s_lshl_b64 s[44:45], s[42:43], 17
	v_readlane_b32 s41, v253, 63
	s_add_u32 s44, s41, s44
	v_readlane_b32 s41, v254, 0
	s_addc_u32 s45, s41, s45
	s_and_b64 s[46:47], s[36:37], exec
	v_or_b32_e32 v208, 0x10000, v139
	v_add_u32_e32 v210, 0x10800, v139
	v_or_b32_e32 v212, 0x14000, v139
	v_add_u32_e32 v218, 0x14800, v139
	s_cselect_b32 s87, s45, s89
	s_cselect_b32 s86, s44, s88
	s_ashr_i32 s41, s40, 31
	v_add_u32_e32 v209, 0x10400, v139
	ds_read_b128 v[2:5], v208
	ds_read_b128 v[6:9], v209
	v_add_u32_e32 v211, 0x10c00, v139
	ds_read_b128 v[10:13], v210
	ds_read_b128 v[14:17], v211
	v_add_u32_e32 v213, 0x14400, v139
	ds_read_b128 v[18:21], v212
	ds_read_b128 v[22:25], v213
	v_add_u32_e32 v219, 0x14c00, v139
	ds_read_b128 v[26:29], v218
	ds_read_b128 v[30:33], v219
	s_lshl_b64 s[46:47], s[40:41], 17
	v_readlane_b32 s50, v253, 59
	v_readlane_b32 s51, v253, 60
	s_add_u32 s46, s50, s46
	s_addc_u32 s47, s51, s47
	s_and_b64 s[50:51], s[36:37], exec
	s_cselect_b32 s85, s47, s91
	s_cselect_b32 s84, s46, s90
	s_add_u32 s50, s88, 0x10080
	s_addc_u32 s51, s89, 0
	s_add_i32 s43, s0, 0xc000
	v_lshl_add_u64 v[66:67], s[50:51], 0, v[134:135]
	s_mov_b32 m0, s43
	s_add_i32 s41, s0, 0xe000
	ds_read_b128 v[34:37], v138
	ds_read_b128 v[38:41], v138 offset:1024
	ds_read_b128 v[42:45], v138 offset:2048
	ds_read_b128 v[46:49], v138 offset:3072
	ds_read_b128 v[50:53], v138 offset:4096
	ds_read_b128 v[54:57], v138 offset:5120
	ds_read_b128 v[58:61], v138 offset:6144
	ds_read_b128 v[62:65], v138 offset:7168
	global_load_lds_dwordx4 v[66:67], off
	v_lshl_add_u64 v[66:67], s[50:51], 0, v[132:133]
	s_mov_b32 m0, s41
	s_nop 0
	global_load_lds_dwordx4 v[66:67], off
	s_waitcnt vmcnt(8)
	s_waitcnt lgkmcnt(0)
	s_barrier
	v_mfma_f32_16x16x32_bf16 v[66:69], v[2:5], v[34:37], 0
	v_mfma_f32_16x16x32_bf16 v[70:73], v[10:13], v[34:37], 0
	v_mfma_f32_16x16x32_bf16 v[74:77], v[2:5], v[42:45], 0
	v_mfma_f32_16x16x32_bf16 v[78:81], v[10:13], v[42:45], 0
	v_mfma_f32_16x16x32_bf16 v[82:85], v[2:5], v[50:53], 0
	v_mfma_f32_16x16x32_bf16 v[86:89], v[10:13], v[50:53], 0
	v_mfma_f32_16x16x32_bf16 v[90:93], v[2:5], v[58:61], 0
	v_mfma_f32_16x16x32_bf16 v[94:97], v[10:13], v[58:61], 0
	v_mfma_f32_16x16x32_bf16 v[66:69], v[6:9], v[38:41], v[66:69]
	v_mfma_f32_16x16x32_bf16 v[70:73], v[14:17], v[38:41], v[70:73]
	v_mfma_f32_16x16x32_bf16 v[74:77], v[6:9], v[46:49], v[74:77]
	v_mfma_f32_16x16x32_bf16 v[78:81], v[14:17], v[46:49], v[78:81]
	v_mfma_f32_16x16x32_bf16 v[82:85], v[6:9], v[54:57], v[82:85]
	v_mfma_f32_16x16x32_bf16 v[86:89], v[14:17], v[54:57], v[86:89]
	v_mfma_f32_16x16x32_bf16 v[90:93], v[6:9], v[62:65], v[90:93]
	v_mfma_f32_16x16x32_bf16 v[94:97], v[14:17], v[62:65], v[94:97]
	v_mfma_f32_16x16x32_bf16 v[98:101], v[18:21], v[34:37], 0
	v_mfma_f32_16x16x32_bf16 v[34:37], v[26:29], v[34:37], 0
	v_mfma_f32_16x16x32_bf16 v[98:101], v[22:25], v[38:41], v[98:101]
	v_mfma_f32_16x16x32_bf16 v[34:37], v[30:33], v[38:41], v[34:37]
	v_mfma_f32_16x16x32_bf16 v[38:41], v[18:21], v[42:45], 0
	v_mfma_f32_16x16x32_bf16 v[42:45], v[26:29], v[42:45], 0
	v_mfma_f32_16x16x32_bf16 v[38:41], v[22:25], v[46:49], v[38:41]
	v_mfma_f32_16x16x32_bf16 v[42:45], v[30:33], v[46:49], v[42:45]
	v_mfma_f32_16x16x32_bf16 v[46:49], v[18:21], v[50:53], 0
	v_mfma_f32_16x16x32_bf16 v[50:53], v[26:29], v[50:53], 0
	v_mfma_f32_16x16x32_bf16 v[46:49], v[22:25], v[54:57], v[46:49]
	v_mfma_f32_16x16x32_bf16 v[50:53], v[30:33], v[54:57], v[50:53]
	v_mfma_f32_16x16x32_bf16 v[54:57], v[18:21], v[58:61], 0
	v_mfma_f32_16x16x32_bf16 v[58:61], v[26:29], v[58:61], 0
	v_mfma_f32_16x16x32_bf16 v[54:57], v[22:25], v[62:65], v[54:57]
	v_mfma_f32_16x16x32_bf16 v[58:61], v[30:33], v[62:65], v[58:61]
	s_barrier
	v_lshl_add_u64 v[136:137], s[90:91], 0, v[0:1]
	s_mov_b64 s[92:93], 0x100
	s_mov_b32 m0, s1
	v_lshl_add_u64 v[140:141], v[136:137], 0, s[92:93]
	v_lshl_add_u64 v[180:181], s[90:91], 0, v[130:131]
	s_add_u32 s50, s90, 0x10100
	ds_read_b128 v[62:65], v138 offset:16384
	ds_read_b128 v[102:105], v138 offset:17408
	ds_read_b128 v[106:109], v138 offset:18432
	ds_read_b128 v[110:113], v138 offset:19456
	ds_read_b128 v[114:117], v138 offset:20480
	ds_read_b128 v[118:121], v138 offset:21504
	ds_read_b128 v[122:125], v138 offset:22528
	ds_read_b128 v[126:129], v138 offset:23552
	global_load_lds_dwordx4 v[140:141], off
	v_lshl_add_u64 v[140:141], v[180:181], 0, s[92:93]
	s_mov_b32 m0, s2
	s_addc_u32 s51, s91, 0
	global_load_lds_dwordx4 v[140:141], off
	v_lshl_add_u64 v[140:141], s[50:51], 0, v[0:1]
	s_mov_b32 m0, s4
	v_lshl_add_u64 v[182:183], s[88:89], 0, v[134:135]
	global_load_lds_dwordx4 v[140:141], off
	v_lshl_add_u64 v[140:141], s[50:51], 0, v[130:131]
	s_mov_b32 m0, s5
	v_lshl_add_u64 v[214:215], s[88:89], 0, v[132:133]
	global_load_lds_dwordx4 v[140:141], off
	v_lshl_add_u64 v[140:141], v[182:183], 0, s[92:93]
	s_mov_b32 m0, s0
	s_nop 0
	global_load_lds_dwordx4 v[140:141], off
	v_lshl_add_u64 v[140:141], v[214:215], 0, s[92:93]
	s_mov_b32 m0, s6
	s_nop 0
	global_load_lds_dwordx4 v[140:141], off
	s_waitcnt vmcnt(8)
	s_waitcnt lgkmcnt(0)
	s_barrier
; #define PG8_STAGE(bufoff, gbase, voff) do { _Pragma("unroll") for (int _i = 0; _i < 2; ++_i) \
;         __builtin_amdgcn_global_load_lds((const unsigned*)((const char*)(gbase) + (voff)[_i]), (PG8_LAS unsigned*)(lds + (bufoff) + ldsw + _i * 8192), 16, 0, 0); } while (0)
; #define PG8_LDA(dst, b, h) do { _Pragma("unroll") for (int m = 0; m < 4; ++m) _Pragma("unroll") for (int k = 0; k < 2; ++k) dst[m][k] = *(const PG8_LAS bf16x8*)(lds + PG8_SA(b, h) + aoff + m * 2048 + k * 1024); } while (0)
; #define PG8_LDB(dst, b, h) do { _Pragma("unroll") for (int n = 0; n < 2; ++n) _Pragma("unroll") for (int k = 0; k < 2; ++k) dst[n][k] = *(const PG8_LAS bf16x8*)(lds + PG8_SB(b, h) + boff + n * 2048 + k * 1024); } while (0)
; #define PG8_MMA(ai, bj, At, Bt) do { __builtin_amdgcn_s_setprio(1); _Pragma("unroll") for (int m = 0; m < 4; ++m) _Pragma("unroll") for (int n = 0; n < 2; ++n) _Pragma("unroll") for (int k = 0; k < 2; ++k) \
;         acc[ai][bj][m][n] = __builtin_amdgcn_mfma_f32_16x16x32_bf16(Bt[n][k], At[m][k], acc[ai][bj][m][n], 0, 0, 0); __builtin_amdgcn_s_setprio(0); } while (0)
; #define PG8_WAIT_V(n) asm volatile("s_waitcnt vmcnt(" #n ")" ::: "memory")
; #define PG8_WAIT_L(n) asm volatile("s_waitcnt lgkmcnt(" #n ")" ::: "memory")
; #define PG8_BAR __builtin_amdgcn_s_barrier()
; #define PG8_SCHED __builtin_amdgcn_sched_barrier(0)
; template <class Epi, class Sched, bool ALIGN_EPI = false, bool SP2 = false>
; __device__ __forceinline__ void gemm_phase(PG8_LAS unsigned char* lds, const Gemm g, const Sched& S, const Epi& E, const int tid) {
;     ...
;             PG8_WAIT_V(8); PG8_WAIT_L(0); PG8_BAR; PG8_MMA(1, 0, At, B0); PG8_MMA(1, 1, At, B1); PG8_BAR; PG8_SCHED;
;             PG8_LDB(B0, 1, 0); PG8_LDB(B1, 1, 1); PG8_SCHED; PG8_LDA(At, 1, 0); PG8_STAGE(PG8_SA(0, 1), a2 + hstep, voffA);
;             PG8_WAIT_V(8); PG8_WAIT_L(0); PG8_BAR; PG8_MMA(0, 0, At, B0); PG8_MMA(0, 1, At, B1); PG8_BAR; PG8_SCHED;
	v_mfma_f32_16x16x32_bf16 v[140:143], v[2:5], v[62:65], 0
	v_mfma_f32_16x16x32_bf16 v[148:151], v[2:5], v[106:109], 0
	v_mfma_f32_16x16x32_bf16 v[156:159], v[2:5], v[114:117], 0
	v_mfma_f32_16x16x32_bf16 v[2:5], v[2:5], v[122:125], 0
	v_mfma_f32_16x16x32_bf16 v[140:143], v[6:9], v[102:105], v[140:143]
	v_mfma_f32_16x16x32_bf16 v[148:151], v[6:9], v[110:113], v[148:151]
	v_mfma_f32_16x16x32_bf16 v[156:159], v[6:9], v[118:121], v[156:159]
	v_mfma_f32_16x16x32_bf16 v[2:5], v[6:9], v[126:129], v[2:5]
	v_mfma_f32_16x16x32_bf16 v[6:9], v[10:13], v[122:125], 0
	v_mfma_f32_16x16x32_bf16 v[144:147], v[10:13], v[62:65], 0
	v_mfma_f32_16x16x32_bf16 v[152:155], v[10:13], v[106:109], 0
	v_mfma_f32_16x16x32_bf16 v[160:163], v[10:13], v[114:117], 0
	v_mfma_f32_16x16x32_bf16 v[6:9], v[14:17], v[126:129], v[6:9]
	v_mfma_f32_16x16x32_bf16 v[144:147], v[14:17], v[102:105], v[144:147]
	v_mfma_f32_16x16x32_bf16 v[152:155], v[14:17], v[110:113], v[152:155]
	v_mfma_f32_16x16x32_bf16 v[160:163], v[14:17], v[118:121], v[160:163]
	v_mfma_f32_16x16x32_bf16 v[10:13], v[18:21], v[62:65], 0
	v_mfma_f32_16x16x32_bf16 v[14:17], v[26:29], v[62:65], 0
	v_mfma_f32_16x16x32_bf16 v[10:13], v[22:25], v[102:105], v[10:13]
	v_mfma_f32_16x16x32_bf16 v[14:17], v[30:33], v[102:105], v[14:17]
	v_mfma_f32_16x16x32_bf16 v[62:65], v[18:21], v[106:109], 0
	v_mfma_f32_16x16x32_bf16 v[102:105], v[26:29], v[106:109], 0
	v_mfma_f32_16x16x32_bf16 v[106:109], v[18:21], v[114:117], 0
	v_mfma_f32_16x16x32_bf16 v[18:21], v[18:21], v[122:125], 0
	v_mfma_f32_16x16x32_bf16 v[62:65], v[22:25], v[110:113], v[62:65]
	v_mfma_f32_16x16x32_bf16 v[102:105], v[30:33], v[110:113], v[102:105]
	v_mfma_f32_16x16x32_bf16 v[106:109], v[22:25], v[118:121], v[106:109]
	v_mfma_f32_16x16x32_bf16 v[110:113], v[26:29], v[114:117], 0
	v_mfma_f32_16x16x32_bf16 v[18:21], v[22:25], v[126:129], v[18:21]
	v_mfma_f32_16x16x32_bf16 v[22:25], v[26:29], v[122:125], 0
	v_mfma_f32_16x16x32_bf16 v[110:113], v[30:33], v[118:121], v[110:113]
	v_mfma_f32_16x16x32_bf16 v[22:25], v[30:33], v[126:129], v[22:25]
	s_barrier
	v_or_b32_e32 v222, 0x18000, v139
	v_add_u32_e32 v224, 0x18800, v139
	v_or_b32_e32 v226, 0x1c000, v139
	v_add_u32_e32 v228, 0x1c800, v139
	v_add_u32_e32 v223, 0x18400, v139
	ds_read_b128 v[26:29], v222
	ds_read_b128 v[30:33], v223
	v_add_u32_e32 v225, 0x18c00, v139
	ds_read_b128 v[114:117], v224
	ds_read_b128 v[118:121], v225
	v_add_u32_e32 v227, 0x1c400, v139
	ds_read_b128 v[122:125], v226
	ds_read_b128 v[126:129], v227
	v_add_u32_e32 v230, 0x1cc00, v139
	ds_read_b128 v[164:167], v228
	ds_read_b128 v[168:171], v230
	s_add_u32 s50, s88, 0x10100
	s_addc_u32 s51, s89, 0
	s_mov_b32 m0, s8
	v_lshl_add_u64 v[216:217], s[50:51], 0, v[134:135]
	ds_read_b128 v[172:175], v138 offset:32768
	ds_read_b128 v[176:179], v138 offset:33792
	ds_read_b128 v[184:187], v138 offset:34816
	ds_read_b128 v[188:191], v138 offset:35840
	ds_read_b128 v[192:195], v138 offset:36864
	ds_read_b128 v[196:199], v138 offset:37888
	ds_read_b128 v[200:203], v138 offset:38912
	ds_read_b128 v[204:207], v138 offset:39936
	global_load_lds_dwordx4 v[216:217], off
	v_lshl_add_u64 v[216:217], s[50:51], 0, v[132:133]
	s_mov_b32 m0, s9
	s_nop 0
	global_load_lds_dwordx4 v[216:217], off
	s_waitcnt vmcnt(8)
	s_waitcnt lgkmcnt(0)
	s_barrier
	v_mfma_f32_16x16x32_bf16 v[66:69], v[26:29], v[172:175], v[66:69]
	v_mfma_f32_16x16x32_bf16 v[66:69], v[30:33], v[176:179], v[66:69]
	v_mfma_f32_16x16x32_bf16 v[70:73], v[114:117], v[172:175], v[70:73]
	v_mfma_f32_16x16x32_bf16 v[70:73], v[118:121], v[176:179], v[70:73]
	v_mfma_f32_16x16x32_bf16 v[74:77], v[26:29], v[184:187], v[74:77]
	v_mfma_f32_16x16x32_bf16 v[74:77], v[30:33], v[188:191], v[74:77]
	v_mfma_f32_16x16x32_bf16 v[78:81], v[114:117], v[184:187], v[78:81]
	v_mfma_f32_16x16x32_bf16 v[78:81], v[118:121], v[188:191], v[78:81]
	v_mfma_f32_16x16x32_bf16 v[82:85], v[26:29], v[192:195], v[82:85]
	v_mfma_f32_16x16x32_bf16 v[82:85], v[30:33], v[196:199], v[82:85]
	v_mfma_f32_16x16x32_bf16 v[86:89], v[114:117], v[192:195], v[86:89]
	v_mfma_f32_16x16x32_bf16 v[86:89], v[118:121], v[196:199], v[86:89]
	v_mfma_f32_16x16x32_bf16 v[90:93], v[26:29], v[200:203], v[90:93]
	v_mfma_f32_16x16x32_bf16 v[90:93], v[30:33], v[204:207], v[90:93]
	v_mfma_f32_16x16x32_bf16 v[94:97], v[114:117], v[200:203], v[94:97]
	v_mfma_f32_16x16x32_bf16 v[94:97], v[118:121], v[204:207], v[94:97]
	v_mfma_f32_16x16x32_bf16 v[98:101], v[122:125], v[172:175], v[98:101]
	v_mfma_f32_16x16x32_bf16 v[98:101], v[126:129], v[176:179], v[98:101]
	v_mfma_f32_16x16x32_bf16 v[34:37], v[164:167], v[172:175], v[34:37]
	v_mfma_f32_16x16x32_bf16 v[34:37], v[168:171], v[176:179], v[34:37]
	v_mfma_f32_16x16x32_bf16 v[38:41], v[122:125], v[184:187], v[38:41]
	v_mfma_f32_16x16x32_bf16 v[38:41], v[126:129], v[188:191], v[38:41]
	v_mfma_f32_16x16x32_bf16 v[42:45], v[164:167], v[184:187], v[42:45]
	v_mfma_f32_16x16x32_bf16 v[42:45], v[168:171], v[188:191], v[42:45]
	v_mfma_f32_16x16x32_bf16 v[46:49], v[122:125], v[192:195], v[46:49]
	v_mfma_f32_16x16x32_bf16 v[46:49], v[126:129], v[196:199], v[46:49]
	v_mfma_f32_16x16x32_bf16 v[50:53], v[164:167], v[192:195], v[50:53]
	v_mfma_f32_16x16x32_bf16 v[50:53], v[168:171], v[196:199], v[50:53]
	v_mfma_f32_16x16x32_bf16 v[54:57], v[122:125], v[200:203], v[54:57]
	v_mfma_f32_16x16x32_bf16 v[54:57], v[126:129], v[204:207], v[54:57]
	v_mfma_f32_16x16x32_bf16 v[58:61], v[164:167], v[200:203], v[58:61]
	v_mfma_f32_16x16x32_bf16 v[58:61], v[168:171], v[204:207], v[58:61]
	s_barrier
; #define PG8_STAGE(bufoff, gbase, voff) do { _Pragma("unroll") for (int _i = 0; _i < 2; ++_i) \
;         __builtin_amdgcn_global_load_lds((const unsigned*)((const char*)(gbase) + (voff)[_i]), (PG8_LAS unsigned*)(lds + (bufoff) + ldsw + _i * 8192), 16, 0, 0); } while (0)
; #define PG8_LDA(dst, b, h) do { _Pragma("unroll") for (int m = 0; m < 4; ++m) _Pragma("unroll") for (int k = 0; k < 2; ++k) dst[m][k] = *(const PG8_LAS bf16x8*)(lds + PG8_SA(b, h) + aoff + m * 2048 + k * 1024); } while (0)
; #define PG8_LDB(dst, b, h) do { _Pragma("unroll") for (int n = 0; n < 2; ++n) _Pragma("unroll") for (int k = 0; k < 2; ++k) dst[n][k] = *(const PG8_LAS bf16x8*)(lds + PG8_SB(b, h) + boff + n * 2048 + k * 1024); } while (0)
; #define PG8_MMA(ai, bj, At, Bt) do { __builtin_amdgcn_s_setprio(1); _Pragma("unroll") for (int m = 0; m < 4; ++m) _Pragma("unroll") for (int n = 0; n < 2; ++n) _Pragma("unroll") for (int k = 0; k < 2; ++k) \
;         acc[ai][bj][m][n] = __builtin_amdgcn_mfma_f32_16x16x32_bf16(Bt[n][k], At[m][k], acc[ai][bj][m][n], 0, 0, 0); __builtin_amdgcn_s_setprio(0); } while (0)
; #define PG8_BAR __builtin_amdgcn_s_barrier()
; template <class Epi, class Sched, bool ALIGN_EPI = false, bool SP2 = false>
; __device__ __forceinline__ void gemm_phase(PG8_LAS unsigned char* lds, const Gemm g, const Sched& S, const Epi& E, const int tid) {
;     ...
;             PG8_LDB(B0, 0, 0); PG8_LDB(B1, 0, 1); PG8_SCHED; PG8_LDA(At, 0, 0); PG8_STAGE(PG8_SA(1, 1), a1 + hstep, voffA);
;             PG8_WAIT_V(8); PG8_WAIT_L(0); PG8_BAR; PG8_MMA(0, 0, At, B0); PG8_MMA(0, 1, At, B1); PG8_BAR; PG8_SCHED;
;             PG8_LDA(At, 0, 1); PG8_STAGE(PG8_SB(0, 0), b2, voffB); PG8_STAGE(PG8_SB(0, 1), b2 + hstep, voffB); PG8_STAGE(PG8_SA(0, 0), a2, voffA);
;             PG8_WAIT_V(8); PG8_WAIT_L(0); PG8_BAR; PG8_MMA(1, 0, At, B0); PG8_MMA(1, 1, At, B1); PG8_BAR; PG8_SCHED;
;             PG8_LDB(B0, 1, 0); PG8_LDB(B1, 1, 1); PG8_SCHED; PG8_LDA(At, 1, 0); PG8_STAGE(PG8_SA(0, 1), a2 + hstep, voffA);
;             PG8_WAIT_V(8); PG8_WAIT_L(0); PG8_BAR; PG8_MMA(0, 0, At, B0); PG8_MMA(0, 1, At, B1); PG8_BAR; PG8_SCHED;
;             PG8_LDA(At, 1, 1); PG8_STAGE(PG8_SB(1, 0), b3, voffB); PG8_STAGE(PG8_SB(1, 1), b3 + hstep, voffB); PG8_STAGE(PG8_SA(1, 0), a3, voffA);
;             PG8_WAIT_V(8); PG8_WAIT_L(0); PG8_BAR; PG8_MMA(1, 0, At, B0); PG8_MMA(1, 1, At, B1); PG8_BAR; PG8_SCHED;
	s_mov_b64 s[92:93], 0x180
	s_mov_b32 m0, s17
	v_lshl_add_u64 v[136:137], v[136:137], 0, s[92:93]
	s_add_u32 s50, s90, 0x10180
	ds_read_b128 v[172:175], v138 offset:49152
	ds_read_b128 v[176:179], v138 offset:50176
	ds_read_b128 v[184:187], v138 offset:51200
	ds_read_b128 v[188:191], v138 offset:52224
	ds_read_b128 v[192:195], v138 offset:53248
	ds_read_b128 v[196:199], v138 offset:54272
	ds_read_b128 v[200:203], v138 offset:55296
	ds_read_b128 v[204:207], v138 offset:56320
	global_load_lds_dwordx4 v[136:137], off
	v_lshl_add_u64 v[136:137], v[180:181], 0, s[92:93]
	s_mov_b32 m0, s20
	s_addc_u32 s51, s91, 0
	global_load_lds_dwordx4 v[136:137], off
	v_lshl_add_u64 v[136:137], s[50:51], 0, v[0:1]
	s_mov_b32 m0, s26
	s_nop 0
	global_load_lds_dwordx4 v[136:137], off
	v_lshl_add_u64 v[136:137], s[50:51], 0, v[130:131]
	s_mov_b32 m0, s27
	s_nop 0
	global_load_lds_dwordx4 v[136:137], off
	v_lshl_add_u64 v[136:137], v[182:183], 0, s[92:93]
	s_mov_b32 m0, s21
	s_nop 0
	global_load_lds_dwordx4 v[136:137], off
	v_lshl_add_u64 v[136:137], v[214:215], 0, s[92:93]
	s_mov_b32 m0, s24
	s_nop 0
	global_load_lds_dwordx4 v[136:137], off
	s_waitcnt vmcnt(8)
	s_waitcnt lgkmcnt(0)
	s_barrier
	v_mfma_f32_16x16x32_bf16 v[2:5], v[26:29], v[200:203], v[2:5]
	v_mfma_f32_16x16x32_bf16 v[2:5], v[30:33], v[204:207], v[2:5]
	v_mfma_f32_16x16x32_bf16 v[6:9], v[114:117], v[200:203], v[6:9]
	v_mfma_f32_16x16x32_bf16 v[6:9], v[118:121], v[204:207], v[6:9]
	v_mfma_f32_16x16x32_bf16 v[140:143], v[26:29], v[172:175], v[140:143]
	v_mfma_f32_16x16x32_bf16 v[140:143], v[30:33], v[176:179], v[140:143]
	v_mfma_f32_16x16x32_bf16 v[144:147], v[114:117], v[172:175], v[144:147]
	v_mfma_f32_16x16x32_bf16 v[144:147], v[118:121], v[176:179], v[144:147]
	v_mfma_f32_16x16x32_bf16 v[148:151], v[26:29], v[184:187], v[148:151]
	v_mfma_f32_16x16x32_bf16 v[148:151], v[30:33], v[188:191], v[148:151]
	v_mfma_f32_16x16x32_bf16 v[152:155], v[114:117], v[184:187], v[152:155]
	v_mfma_f32_16x16x32_bf16 v[152:155], v[118:121], v[188:191], v[152:155]
	v_mfma_f32_16x16x32_bf16 v[156:159], v[26:29], v[192:195], v[156:159]
	v_mfma_f32_16x16x32_bf16 v[156:159], v[30:33], v[196:199], v[156:159]
	v_mfma_f32_16x16x32_bf16 v[160:163], v[114:117], v[192:195], v[160:163]
	v_mfma_f32_16x16x32_bf16 v[160:163], v[118:121], v[196:199], v[160:163]
	v_mfma_f32_16x16x32_bf16 v[10:13], v[122:125], v[172:175], v[10:13]
	v_mfma_f32_16x16x32_bf16 v[14:17], v[164:167], v[172:175], v[14:17]
	v_mfma_f32_16x16x32_bf16 v[26:29], v[122:125], v[184:187], v[62:65]
	v_mfma_f32_16x16x32_bf16 v[30:33], v[164:167], v[184:187], v[102:105]
	v_mfma_f32_16x16x32_bf16 v[62:65], v[122:125], v[192:195], v[106:109]
	v_mfma_f32_16x16x32_bf16 v[102:105], v[164:167], v[192:195], v[110:113]
	v_mfma_f32_16x16x32_bf16 v[18:21], v[122:125], v[200:203], v[18:21]
	v_mfma_f32_16x16x32_bf16 v[22:25], v[164:167], v[200:203], v[22:25]
	v_mfma_f32_16x16x32_bf16 v[10:13], v[126:129], v[176:179], v[10:13]
	v_mfma_f32_16x16x32_bf16 v[14:17], v[168:171], v[176:179], v[14:17]
	v_mfma_f32_16x16x32_bf16 v[26:29], v[126:129], v[188:191], v[26:29]
	v_mfma_f32_16x16x32_bf16 v[30:33], v[168:171], v[188:191], v[30:33]
	v_mfma_f32_16x16x32_bf16 v[62:65], v[126:129], v[196:199], v[62:65]
	v_mfma_f32_16x16x32_bf16 v[102:105], v[168:171], v[196:199], v[102:105]
	v_mfma_f32_16x16x32_bf16 v[18:21], v[126:129], v[204:207], v[18:21]
	v_mfma_f32_16x16x32_bf16 v[22:25], v[168:171], v[204:207], v[22:25]
	s_barrier
	ds_read_b128 v[106:109], v208
	ds_read_b128 v[110:113], v209
	ds_read_b128 v[114:117], v210
	ds_read_b128 v[118:121], v211
	ds_read_b128 v[122:125], v212
	ds_read_b128 v[126:129], v213
	ds_read_b128 v[164:167], v218
	ds_read_b128 v[168:171], v219
	s_add_u32 s50, s88, 0x10180
	s_addc_u32 s51, s89, 0
	s_mov_b32 m0, s43
	v_lshl_add_u64 v[136:137], s[50:51], 0, v[134:135]
	ds_read_b128 v[172:175], v138
	ds_read_b128 v[176:179], v138 offset:1024
	ds_read_b128 v[184:187], v138 offset:2048
	ds_read_b128 v[188:191], v138 offset:3072
	ds_read_b128 v[192:195], v138 offset:4096
	ds_read_b128 v[196:199], v138 offset:5120
	ds_read_b128 v[200:203], v138 offset:6144
	ds_read_b128 v[204:207], v138 offset:7168
	global_load_lds_dwordx4 v[136:137], off
	v_lshl_add_u64 v[136:137], s[50:51], 0, v[132:133]
	s_mov_b32 m0, s41
	s_nop 0
	global_load_lds_dwordx4 v[136:137], off
	s_waitcnt vmcnt(8)
	s_waitcnt lgkmcnt(0)
	s_barrier
	v_mfma_f32_16x16x32_bf16 v[66:69], v[106:109], v[172:175], v[66:69]
	v_mfma_f32_16x16x32_bf16 v[70:73], v[114:117], v[172:175], v[70:73]
	v_mfma_f32_16x16x32_bf16 v[74:77], v[106:109], v[184:187], v[74:77]
	v_mfma_f32_16x16x32_bf16 v[78:81], v[114:117], v[184:187], v[78:81]
	v_mfma_f32_16x16x32_bf16 v[82:85], v[106:109], v[192:195], v[82:85]
	v_mfma_f32_16x16x32_bf16 v[86:89], v[114:117], v[192:195], v[86:89]
	v_mfma_f32_16x16x32_bf16 v[90:93], v[106:109], v[200:203], v[90:93]
	v_mfma_f32_16x16x32_bf16 v[66:69], v[110:113], v[176:179], v[66:69]
	v_mfma_f32_16x16x32_bf16 v[70:73], v[118:121], v[176:179], v[70:73]
	v_mfma_f32_16x16x32_bf16 v[74:77], v[110:113], v[188:191], v[74:77]
	v_mfma_f32_16x16x32_bf16 v[78:81], v[118:121], v[188:191], v[78:81]
	v_mfma_f32_16x16x32_bf16 v[82:85], v[110:113], v[196:199], v[82:85]
	v_mfma_f32_16x16x32_bf16 v[86:89], v[118:121], v[196:199], v[86:89]
	v_mfma_f32_16x16x32_bf16 v[90:93], v[110:113], v[204:207], v[90:93]
	v_mfma_f32_16x16x32_bf16 v[94:97], v[114:117], v[200:203], v[94:97]
	v_mfma_f32_16x16x32_bf16 v[214:217], v[118:121], v[204:207], v[94:97]
	v_mfma_f32_16x16x32_bf16 v[94:97], v[122:125], v[172:175], v[98:101]
	v_mfma_f32_16x16x32_bf16 v[34:37], v[164:167], v[172:175], v[34:37]
	v_mfma_f32_16x16x32_bf16 v[38:41], v[122:125], v[184:187], v[38:41]
	v_mfma_f32_16x16x32_bf16 v[42:45], v[164:167], v[184:187], v[42:45]
	v_mfma_f32_16x16x32_bf16 v[46:49], v[122:125], v[192:195], v[46:49]
	v_mfma_f32_16x16x32_bf16 v[50:53], v[164:167], v[192:195], v[50:53]
	v_mfma_f32_16x16x32_bf16 v[54:57], v[122:125], v[200:203], v[54:57]
	v_mfma_f32_16x16x32_bf16 v[98:101], v[126:129], v[176:179], v[94:97]
	v_mfma_f32_16x16x32_bf16 v[34:37], v[168:171], v[176:179], v[34:37]
	v_mfma_f32_16x16x32_bf16 v[38:41], v[126:129], v[188:191], v[38:41]
	v_mfma_f32_16x16x32_bf16 v[42:45], v[168:171], v[188:191], v[42:45]
	v_mfma_f32_16x16x32_bf16 v[46:49], v[126:129], v[196:199], v[46:49]
	v_mfma_f32_16x16x32_bf16 v[50:53], v[168:171], v[196:199], v[50:53]
	v_mfma_f32_16x16x32_bf16 v[172:175], v[126:129], v[204:207], v[54:57]
	v_mfma_f32_16x16x32_bf16 v[54:57], v[164:167], v[200:203], v[58:61]
	v_mfma_f32_16x16x32_bf16 v[176:179], v[168:171], v[204:207], v[54:57]
	s_barrier
; #define PG8_STAGE(bufoff, gbase, voff) do { _Pragma("unroll") for (int _i = 0; _i < 2; ++_i) \
;         __builtin_amdgcn_global_load_lds((const unsigned*)((const char*)(gbase) + (voff)[_i]), (PG8_LAS unsigned*)(lds + (bufoff) + ldsw + _i * 8192), 16, 0, 0); } while (0)
; #define PG8_LDA(dst, b, h) do { _Pragma("unroll") for (int m = 0; m < 4; ++m) _Pragma("unroll") for (int k = 0; k < 2; ++k) dst[m][k] = *(const PG8_LAS bf16x8*)(lds + PG8_SA(b, h) + aoff + m * 2048 + k * 1024); } while (0)
; #define PG8_LDB(dst, b, h) do { _Pragma("unroll") for (int n = 0; n < 2; ++n) _Pragma("unroll") for (int k = 0; k < 2; ++k) dst[n][k] = *(const PG8_LAS bf16x8*)(lds + PG8_SB(b, h) + boff + n * 2048 + k * 1024); } while (0)
; #define PG8_MMA(ai, bj, At, Bt) do { __builtin_amdgcn_s_setprio(1); _Pragma("unroll") for (int m = 0; m < 4; ++m) _Pragma("unroll") for (int n = 0; n < 2; ++n) _Pragma("unroll") for (int k = 0; k < 2; ++k) \
;         acc[ai][bj][m][n] = __builtin_amdgcn_mfma_f32_16x16x32_bf16(Bt[n][k], At[m][k], acc[ai][bj][m][n], 0, 0, 0); __builtin_amdgcn_s_setprio(0); } while (0)
; #define PG8_WAIT_V(n) asm volatile("s_waitcnt vmcnt(" #n ")" ::: "memory")
; #define PG8_WAIT_L(n) asm volatile("s_waitcnt lgkmcnt(" #n ")" ::: "memory")
; #define PG8_BAR __builtin_amdgcn_s_barrier()
; #define PG8_SCHED __builtin_amdgcn_sched_barrier(0)
; template <class Epi, class Sched, bool ALIGN_EPI = false, bool SP2 = false>
; __device__ __forceinline__ void gemm_phase(PG8_LAS unsigned char* lds, const Gemm g, const Sched& S, const Epi& E, const int tid) {
;     ...
;             PG8_LDA(At, 0, 1); PG8_STAGE(PG8_SB(0, 0), b2, voffB); PG8_STAGE(PG8_SB(0, 1), b2 + hstep, voffB); PG8_STAGE(PG8_SA(0, 0), a2, voffA);
;             PG8_WAIT_V(8); PG8_WAIT_L(0); PG8_BAR; PG8_MMA(1, 0, At, B0); PG8_MMA(1, 1, At, B1); PG8_BAR; PG8_SCHED;
;             PG8_LDB(B0, 1, 0); PG8_LDB(B1, 1, 1); PG8_SCHED; PG8_LDA(At, 1, 0); PG8_STAGE(PG8_SA(0, 1), a2 + hstep, voffA);
;             PG8_WAIT_V(8); PG8_WAIT_L(0); PG8_BAR; PG8_MMA(0, 0, At, B0); PG8_MMA(0, 1, At, B1); PG8_BAR; PG8_SCHED;
	s_mov_b32 m0, s1
	v_lshl_add_u64 v[136:137], s[84:85], 0, v[0:1]
	s_add_u32 s50, s84, 0x10000
	s_nop 1
	ds_read_b128 v[54:57], v138 offset:16384
	ds_read_b128 v[58:61], v138 offset:17408
	ds_read_b128 v[94:97], v138 offset:18432
	ds_read_b128 v[184:187], v138 offset:19456
	ds_read_b128 v[188:191], v138 offset:20480
	ds_read_b128 v[192:195], v138 offset:21504
	ds_read_b128 v[196:199], v138 offset:22528
	ds_read_b128 v[200:203], v138 offset:23552
	global_load_lds_dwordx4 v[136:137], off
	v_lshl_add_u64 v[208:209], s[84:85], 0, v[130:131]
	s_mov_b32 m0, s2
	s_addc_u32 s51, s85, 0
	global_load_lds_dwordx4 v[208:209], off
	v_lshl_add_u64 v[180:181], s[50:51], 0, v[0:1]
	s_mov_b32 m0, s4
	v_lshl_add_u64 v[210:211], s[86:87], 0, v[134:135]
	global_load_lds_dwordx4 v[180:181], off
	v_lshl_add_u64 v[180:181], s[50:51], 0, v[130:131]
	s_mov_b32 m0, s5
	v_lshl_add_u64 v[212:213], s[86:87], 0, v[132:133]
	global_load_lds_dwordx4 v[180:181], off
	s_mov_b32 m0, s0
	s_nop 0
	global_load_lds_dwordx4 v[210:211], off
	s_mov_b32 m0, s6
	s_nop 0
	global_load_lds_dwordx4 v[212:213], off
	s_waitcnt vmcnt(8)
	s_waitcnt lgkmcnt(0)
	s_barrier
	v_mfma_f32_16x16x32_bf16 v[2:5], v[106:109], v[196:199], v[2:5]
	v_mfma_f32_16x16x32_bf16 v[2:5], v[110:113], v[200:203], v[2:5]
	v_mfma_f32_16x16x32_bf16 v[6:9], v[114:117], v[196:199], v[6:9]
	v_mfma_f32_16x16x32_bf16 v[6:9], v[118:121], v[200:203], v[6:9]
	v_mfma_f32_16x16x32_bf16 v[140:143], v[106:109], v[54:57], v[140:143]
	v_mfma_f32_16x16x32_bf16 v[140:143], v[110:113], v[58:61], v[140:143]
	v_mfma_f32_16x16x32_bf16 v[144:147], v[114:117], v[54:57], v[144:147]
	v_mfma_f32_16x16x32_bf16 v[144:147], v[118:121], v[58:61], v[144:147]
	v_mfma_f32_16x16x32_bf16 v[148:151], v[106:109], v[94:97], v[148:151]
	v_mfma_f32_16x16x32_bf16 v[148:151], v[110:113], v[184:187], v[148:151]
	v_mfma_f32_16x16x32_bf16 v[152:155], v[114:117], v[94:97], v[152:155]
	v_mfma_f32_16x16x32_bf16 v[152:155], v[118:121], v[184:187], v[152:155]
	v_mfma_f32_16x16x32_bf16 v[156:159], v[106:109], v[188:191], v[156:159]
	v_mfma_f32_16x16x32_bf16 v[156:159], v[110:113], v[192:195], v[156:159]
	v_mfma_f32_16x16x32_bf16 v[160:163], v[114:117], v[188:191], v[160:163]
	v_mfma_f32_16x16x32_bf16 v[160:163], v[118:121], v[192:195], v[160:163]
	v_mfma_f32_16x16x32_bf16 v[14:17], v[164:167], v[54:57], v[14:17]
	v_mfma_f32_16x16x32_bf16 v[204:207], v[168:171], v[58:61], v[14:17]
	v_mfma_f32_16x16x32_bf16 v[14:17], v[122:125], v[94:97], v[26:29]
	v_mfma_f32_16x16x32_bf16 v[26:29], v[126:129], v[184:187], v[14:17]
	v_mfma_f32_16x16x32_bf16 v[14:17], v[164:167], v[94:97], v[30:33]
	v_mfma_f32_16x16x32_bf16 v[184:187], v[168:171], v[184:187], v[14:17]
	v_mfma_f32_16x16x32_bf16 v[14:17], v[122:125], v[188:191], v[62:65]
	v_mfma_f32_16x16x32_bf16 v[218:221], v[126:129], v[192:195], v[14:17]
	v_mfma_f32_16x16x32_bf16 v[14:17], v[164:167], v[188:191], v[102:105]
	v_mfma_f32_16x16x32_bf16 v[10:13], v[122:125], v[54:57], v[10:13]
	v_mfma_f32_16x16x32_bf16 v[188:191], v[168:171], v[192:195], v[14:17]
	v_mfma_f32_16x16x32_bf16 v[14:17], v[122:125], v[196:199], v[18:21]
	v_mfma_f32_16x16x32_bf16 v[10:13], v[126:129], v[58:61], v[10:13]
	v_mfma_f32_16x16x32_bf16 v[192:195], v[126:129], v[200:203], v[14:17]
	v_mfma_f32_16x16x32_bf16 v[14:17], v[164:167], v[196:199], v[22:25]
	v_mfma_f32_16x16x32_bf16 v[164:167], v[168:171], v[200:203], v[14:17]
	s_barrier
	s_nop 4
	ds_read_b128 v[14:17], v222
	ds_read_b128 v[18:21], v223
	ds_read_b128 v[168:171], v224
	ds_read_b128 v[196:199], v225
	ds_read_b128 v[200:203], v226
	ds_read_b128 v[222:225], v227
	ds_read_b128 v[226:229], v228
	ds_read_b128 v[230:233], v230
	s_add_u32 s50, s86, 0x10000
	s_addc_u32 s51, s87, 0
	s_mov_b32 m0, s8
	v_lshl_add_u64 v[54:55], s[50:51], 0, v[134:135]
	ds_read_b128 v[22:25], v138 offset:32768
	ds_read_b128 v[30:33], v138 offset:33792
	ds_read_b128 v[58:61], v138 offset:34816
	ds_read_b128 v[234:237], v138 offset:35840
	ds_read_b128 v[238:241], v138 offset:36864
	ds_read_b128 v[242:245], v138 offset:37888
	ds_read_b128 v[246:249], v138 offset:38912
	ds_read_b128 v[180:183], v138 offset:39936
	global_load_lds_dwordx4 v[54:55], off
	v_lshl_add_u64 v[54:55], s[50:51], 0, v[132:133]
	s_mov_b32 m0, s9
	s_nop 0
	global_load_lds_dwordx4 v[54:55], off
	s_waitcnt vmcnt(8)
	s_waitcnt lgkmcnt(0)
	s_barrier
; #define PG8_STAGE(bufoff, gbase, voff) do { _Pragma("unroll") for (int _i = 0; _i < 2; ++_i) \
;         __builtin_amdgcn_global_load_lds((const unsigned*)((const char*)(gbase) + (voff)[_i]), (PG8_LAS unsigned*)(lds + (bufoff) + ldsw + _i * 8192), 16, 0, 0); } while (0)
; #define PG8_LDA(dst, b, h) do { _Pragma("unroll") for (int m = 0; m < 4; ++m) _Pragma("unroll") for (int k = 0; k < 2; ++k) dst[m][k] = *(const PG8_LAS bf16x8*)(lds + PG8_SA(b, h) + aoff + m * 2048 + k * 1024); } while (0)
; #define PG8_MMA(ai, bj, At, Bt) do { __builtin_amdgcn_s_setprio(1); _Pragma("unroll") for (int m = 0; m < 4; ++m) _Pragma("unroll") for (int n = 0; n < 2; ++n) _Pragma("unroll") for (int k = 0; k < 2; ++k) \
;         acc[ai][bj][m][n] = __builtin_amdgcn_mfma_f32_16x16x32_bf16(Bt[n][k], At[m][k], acc[ai][bj][m][n], 0, 0, 0); __builtin_amdgcn_s_setprio(0); } while (0)
; #define PG8_WAIT_V(n) asm volatile("s_waitcnt vmcnt(" #n ")" ::: "memory")
; #define PG8_WAIT_L(n) asm volatile("s_waitcnt lgkmcnt(" #n ")" ::: "memory")
; #define PG8_BAR __builtin_amdgcn_s_barrier()
; #define PG8_SCHED __builtin_amdgcn_sched_barrier(0)
; template <class Epi, class Sched, bool ALIGN_EPI = false, bool SP2 = false>
; __device__ __forceinline__ void gemm_phase(PG8_LAS unsigned char* lds, const Gemm g, const Sched& S, const Epi& E, const int tid) {
;     ...
;             PG8_WAIT_V(8); PG8_WAIT_L(0); PG8_BAR; PG8_MMA(0, 0, At, B0); PG8_MMA(0, 1, At, B1); PG8_BAR; PG8_SCHED;
;             PG8_LDA(At, 1, 1); PG8_STAGE(PG8_SB(1, 0), b3, voffB); PG8_STAGE(PG8_SB(1, 1), b3 + hstep, voffB); PG8_STAGE(PG8_SA(1, 0), a3, voffA);
;             PG8_WAIT_V(8); PG8_WAIT_L(0); PG8_BAR; PG8_MMA(1, 0, At, B0); PG8_MMA(1, 1, At, B1); PG8_BAR; PG8_SCHED;
	v_mfma_f32_16x16x32_bf16 v[54:57], v[14:17], v[22:25], v[66:69]
	v_mfma_f32_16x16x32_bf16 v[122:125], v[18:21], v[30:33], v[54:57]
	v_mfma_f32_16x16x32_bf16 v[54:57], v[168:171], v[22:25], v[70:73]
	v_mfma_f32_16x16x32_bf16 v[114:117], v[196:199], v[30:33], v[54:57]
	v_mfma_f32_16x16x32_bf16 v[54:57], v[14:17], v[58:61], v[74:77]
	v_mfma_f32_16x16x32_bf16 v[110:113], v[18:21], v[234:237], v[54:57]
	v_mfma_f32_16x16x32_bf16 v[54:57], v[168:171], v[58:61], v[78:81]
	v_mfma_f32_16x16x32_bf16 v[102:105], v[196:199], v[234:237], v[54:57]
	v_mfma_f32_16x16x32_bf16 v[54:57], v[14:17], v[238:241], v[82:85]
	v_mfma_f32_16x16x32_bf16 v[94:97], v[18:21], v[242:245], v[54:57]
	v_mfma_f32_16x16x32_bf16 v[54:57], v[168:171], v[238:241], v[86:89]
	v_mfma_f32_16x16x32_bf16 v[86:89], v[196:199], v[242:245], v[54:57]
	v_mfma_f32_16x16x32_bf16 v[54:57], v[14:17], v[246:249], v[90:93]
	v_mfma_f32_16x16x32_bf16 v[62:65], v[18:21], v[180:183], v[54:57]
	v_mfma_f32_16x16x32_bf16 v[54:57], v[168:171], v[246:249], v[214:217]
	v_mfma_f32_16x16x32_bf16 v[54:57], v[196:199], v[180:183], v[54:57]
	v_mfma_f32_16x16x32_bf16 v[66:69], v[200:203], v[22:25], v[98:101]
	v_mfma_f32_16x16x32_bf16 v[22:25], v[226:229], v[22:25], v[34:37]
	v_mfma_f32_16x16x32_bf16 v[118:121], v[230:233], v[30:33], v[22:25]
	v_mfma_f32_16x16x32_bf16 v[22:25], v[200:203], v[58:61], v[38:41]
	v_mfma_f32_16x16x32_bf16 v[106:109], v[222:225], v[234:237], v[22:25]
	v_mfma_f32_16x16x32_bf16 v[22:25], v[226:229], v[58:61], v[42:45]
	v_mfma_f32_16x16x32_bf16 v[98:101], v[230:233], v[234:237], v[22:25]
	v_mfma_f32_16x16x32_bf16 v[22:25], v[200:203], v[238:241], v[46:49]
	v_mfma_f32_16x16x32_bf16 v[90:93], v[222:225], v[242:245], v[22:25]
	v_mfma_f32_16x16x32_bf16 v[22:25], v[226:229], v[238:241], v[50:53]
	v_mfma_f32_16x16x32_bf16 v[82:85], v[230:233], v[242:245], v[22:25]
	v_mfma_f32_16x16x32_bf16 v[22:25], v[200:203], v[246:249], v[172:175]
	v_mfma_f32_16x16x32_bf16 v[58:61], v[222:225], v[180:183], v[22:25]
	v_mfma_f32_16x16x32_bf16 v[22:25], v[226:229], v[246:249], v[176:179]
	v_mfma_f32_16x16x32_bf16 v[126:129], v[222:225], v[30:33], v[66:69]
	v_mfma_f32_16x16x32_bf16 v[50:53], v[230:233], v[180:183], v[22:25]
	s_barrier
	s_mov_b32 m0, s17
	s_nop 2
	v_lshl_add_u64 v[22:23], v[136:137], 0, s[12:13]
	s_add_u32 s50, s84, 0x10080
	ds_read_b128 v[34:37], v138 offset:49152
	ds_read_b128 v[42:45], v138 offset:50176
	ds_read_b128 v[172:175], v138 offset:51200
	ds_read_b128 v[176:179], v138 offset:52224
	ds_read_b128 v[180:183], v138 offset:53248
	ds_read_b128 v[214:217], v138 offset:54272
	ds_read_b128 v[234:237], v138 offset:55296
	ds_read_b128 v[238:241], v138 offset:56320
	global_load_lds_dwordx4 v[22:23], off
	v_lshl_add_u64 v[22:23], v[208:209], 0, s[12:13]
	s_mov_b32 m0, s20
	s_addc_u32 s51, s85, 0
	global_load_lds_dwordx4 v[22:23], off
	v_lshl_add_u64 v[22:23], s[50:51], 0, v[0:1]
	s_mov_b32 m0, s26
	s_nop 0
	global_load_lds_dwordx4 v[22:23], off
	v_lshl_add_u64 v[22:23], s[50:51], 0, v[130:131]
	s_mov_b32 m0, s27
	s_nop 0
	global_load_lds_dwordx4 v[22:23], off
	v_lshl_add_u64 v[22:23], v[210:211], 0, s[12:13]
	s_mov_b32 m0, s21
	s_nop 0
	global_load_lds_dwordx4 v[22:23], off
	v_lshl_add_u64 v[22:23], v[212:213], 0, s[12:13]
	s_mov_b32 m0, s24
	s_nop 0
	global_load_lds_dwordx4 v[22:23], off
	s_waitcnt vmcnt(8)
	s_waitcnt lgkmcnt(0)
	s_barrier
	v_mfma_f32_16x16x32_bf16 v[22:25], v[14:17], v[34:37], v[140:143]
	v_mfma_f32_16x16x32_bf16 v[78:81], v[18:21], v[42:45], v[22:25]
	v_mfma_f32_16x16x32_bf16 v[22:25], v[168:171], v[34:37], v[144:147]
	v_mfma_f32_16x16x32_bf16 v[70:73], v[196:199], v[42:45], v[22:25]
	v_mfma_f32_16x16x32_bf16 v[22:25], v[14:17], v[172:175], v[148:151]
	v_mfma_f32_16x16x32_bf16 v[46:49], v[18:21], v[176:179], v[22:25]
	v_mfma_f32_16x16x32_bf16 v[22:25], v[168:171], v[172:175], v[152:155]
	v_mfma_f32_16x16x32_bf16 v[38:41], v[196:199], v[176:179], v[22:25]
	v_mfma_f32_16x16x32_bf16 v[22:25], v[14:17], v[180:183], v[156:159]
	v_mfma_f32_16x16x32_bf16 v[2:5], v[14:17], v[234:237], v[2:5]
	v_mfma_f32_16x16x32_bf16 v[30:33], v[18:21], v[214:217], v[22:25]
	v_mfma_f32_16x16x32_bf16 v[22:25], v[168:171], v[180:183], v[160:163]
	v_mfma_f32_16x16x32_bf16 v[14:17], v[18:21], v[238:241], v[2:5]
	v_mfma_f32_16x16x32_bf16 v[2:5], v[168:171], v[234:237], v[6:9]
	v_mfma_f32_16x16x32_bf16 v[22:25], v[196:199], v[214:217], v[22:25]
	v_mfma_f32_16x16x32_bf16 v[6:9], v[196:199], v[238:241], v[2:5]
	v_mfma_f32_16x16x32_bf16 v[2:5], v[200:203], v[34:37], v[10:13]
	v_mfma_f32_16x16x32_bf16 v[74:77], v[222:225], v[42:45], v[2:5]
	v_mfma_f32_16x16x32_bf16 v[2:5], v[226:229], v[34:37], v[204:207]
	v_mfma_f32_16x16x32_bf16 v[66:69], v[230:233], v[42:45], v[2:5]
	v_mfma_f32_16x16x32_bf16 v[2:5], v[200:203], v[172:175], v[26:29]
	v_mfma_f32_16x16x32_bf16 v[42:45], v[222:225], v[176:179], v[2:5]
	v_mfma_f32_16x16x32_bf16 v[2:5], v[226:229], v[172:175], v[184:187]
	v_mfma_f32_16x16x32_bf16 v[34:37], v[230:233], v[176:179], v[2:5]
	v_mfma_f32_16x16x32_bf16 v[2:5], v[200:203], v[180:183], v[218:221]
	v_mfma_f32_16x16x32_bf16 v[26:29], v[222:225], v[214:217], v[2:5]
	v_mfma_f32_16x16x32_bf16 v[2:5], v[226:229], v[180:183], v[188:191]
	v_mfma_f32_16x16x32_bf16 v[18:21], v[230:233], v[214:217], v[2:5]
	v_mfma_f32_16x16x32_bf16 v[2:5], v[200:203], v[234:237], v[192:195]
	v_mfma_f32_16x16x32_bf16 v[10:13], v[222:225], v[238:241], v[2:5]
	v_mfma_f32_16x16x32_bf16 v[2:5], v[226:229], v[234:237], v[164:167]
	v_mfma_f32_16x16x32_bf16 v[2:5], v[230:233], v[238:241], v[2:5]
	s_barrier
	s_andn2_b64 vcc, exec, s[30:31]
	s_cbranch_vccnz .LBB0_372
	s_barrier

; #define PG8_STAGE(bufoff, gbase, voff) do { _Pragma("unroll") for (int _i = 0; _i < 2; ++_i) \
;         __builtin_amdgcn_global_load_lds((const unsigned*)((const char*)(gbase) + (voff)[_i]), (PG8_LAS unsigned*)(lds + (bufoff) + ldsw + _i * 8192), 16, 0, 0); } while (0)
; #define PG8_LDA(dst, b, h) do { _Pragma("unroll") for (int m = 0; m < 4; ++m) _Pragma("unroll") for (int k = 0; k < 2; ++k) dst[m][k] = *(const PG8_LAS bf16x8*)(lds + PG8_SA(b, h) + aoff + m * 2048 + k * 1024); } while (0)
; #define PG8_LDB(dst, b, h) do { _Pragma("unroll") for (int n = 0; n < 2; ++n) _Pragma("unroll") for (int k = 0; k < 2; ++k) dst[n][k] = *(const PG8_LAS bf16x8*)(lds + PG8_SB(b, h) + boff + n * 2048 + k * 1024); } while (0)
; #define PG8_MMA(ai, bj, At, Bt) do { __builtin_amdgcn_s_setprio(1); _Pragma("unroll") for (int m = 0; m < 4; ++m) _Pragma("unroll") for (int n = 0; n < 2; ++n) _Pragma("unroll") for (int k = 0; k < 2; ++k) \
;         acc[ai][bj][m][n] = __builtin_amdgcn_mfma_f32_16x16x32_bf16(Bt[n][k], At[m][k], acc[ai][bj][m][n], 0, 0, 0); __builtin_amdgcn_s_setprio(0); } while (0)
; #define PG8_BAR __builtin_amdgcn_s_barrier()
; template <class Epi, class Sched, bool ALIGN_EPI = false, bool SP2 = false>
; __device__ __forceinline__ void gemm_phase(PG8_LAS unsigned char* lds, const Gemm g, const Sched& S, const Epi& E, const int tid) {
;     ...
;             PG8_LDB(B0, 0, 0); PG8_LDB(B1, 0, 1); PG8_SCHED; PG8_LDA(At, 0, 0); PG8_STAGE(PG8_SA(1, 1), a1 + hstep, voffA);
;             PG8_WAIT_V(8); PG8_WAIT_L(0); PG8_BAR; PG8_MMA(0, 0, At, B0); PG8_MMA(0, 1, At, B1); PG8_BAR; PG8_SCHED;
;             PG8_LDA(At, 0, 1); PG8_STAGE(PG8_SB(0, 0), b2, voffB); PG8_STAGE(PG8_SB(0, 1), b2 + hstep, voffB); PG8_STAGE(PG8_SA(0, 0), a2, voffA);
;             PG8_WAIT_V(8); PG8_WAIT_L(0); PG8_BAR; PG8_MMA(1, 0, At, B0); PG8_MMA(1, 1, At, B1); PG8_BAR; PG8_SCHED;
;             PG8_LDB(B0, 1, 0); PG8_LDB(B1, 1, 1); PG8_SCHED; PG8_LDA(At, 1, 0); PG8_STAGE(PG8_SA(0, 1), a2 + hstep, voffA);
;             PG8_WAIT_V(8); PG8_WAIT_L(0); PG8_BAR; PG8_MMA(0, 0, At, B0); PG8_MMA(0, 1, At, B1); PG8_BAR; PG8_SCHED;
;             PG8_LDA(At, 1, 1); PG8_STAGE(PG8_SB(1, 0), b3, voffB); PG8_STAGE(PG8_SB(1, 1), b3 + hstep, voffB); PG8_STAGE(PG8_SA(1, 0), a3, voffA);
;             PG8_WAIT_V(8); PG8_WAIT_L(0); PG8_BAR; PG8_MMA(1, 0, At, B0); PG8_MMA(1, 1, At, B1); PG8_BAR; PG8_SCHED;
.LBB0_388:
	v_or_b32_e32 v0, 0x10000, v179
	v_add_u32_e32 v11, 0x10800, v179
	v_or_b32_e32 v13, 0x14000, v179
	v_add_u32_e32 v15, 0x14800, v179
	v_add_u32_e32 v10, 0x10400, v179
	ds_read_b128 v[18:21], v0
	ds_read_b128 v[22:25], v10
	v_add_u32_e32 v12, 0x10c00, v179
	ds_read_b128 v[26:29], v11
	ds_read_b128 v[30:33], v12
	v_add_u32_e32 v14, 0x14400, v179
	ds_read_b128 v[34:37], v13
	ds_read_b128 v[38:41], v14
	v_add_u32_e32 v16, 0x14c00, v179
	ds_read_b128 v[42:45], v15
	ds_read_b128 v[46:49], v16
	s_add_u32 s20, s30, 0x18080
	s_addc_u32 s21, s31, 0
	s_add_i32 s5, s1, 0xc000
	v_lshl_add_u64 v[74:75], s[20:21], 0, v[168:169]
	s_mov_b32 m0, s5
	s_add_i32 s4, s1, 0xe000
	ds_read_b128 v[2:5], v178
	ds_read_b128 v[6:9], v178 offset:1024
	ds_read_b128 v[50:53], v178 offset:2048
	ds_read_b128 v[54:57], v178 offset:3072
	ds_read_b128 v[58:61], v178 offset:4096
	ds_read_b128 v[62:65], v178 offset:5120
	ds_read_b128 v[66:69], v178 offset:6144
	ds_read_b128 v[70:73], v178 offset:7168
	global_load_lds_dwordx4 v[74:75], off
	v_lshl_add_u64 v[74:75], s[20:21], 0, v[164:165]
	s_mov_b32 m0, s4
	s_nop 0
	global_load_lds_dwordx4 v[74:75], off
	s_waitcnt vmcnt(8)
	s_waitcnt lgkmcnt(0)
	s_barrier
	v_mfma_f32_16x16x32_bf16 v[74:77], v[18:21], v[2:5], 0
	v_mfma_f32_16x16x32_bf16 v[78:81], v[26:29], v[2:5], 0
	v_mfma_f32_16x16x32_bf16 v[82:85], v[18:21], v[50:53], 0
	v_mfma_f32_16x16x32_bf16 v[86:89], v[26:29], v[50:53], 0
	v_mfma_f32_16x16x32_bf16 v[90:93], v[18:21], v[58:61], 0
	v_mfma_f32_16x16x32_bf16 v[94:97], v[26:29], v[58:61], 0
	v_mfma_f32_16x16x32_bf16 v[98:101], v[18:21], v[66:69], 0
	v_mfma_f32_16x16x32_bf16 v[102:105], v[26:29], v[66:69], 0
	v_mfma_f32_16x16x32_bf16 v[74:77], v[22:25], v[6:9], v[74:77]
	v_mfma_f32_16x16x32_bf16 v[78:81], v[30:33], v[6:9], v[78:81]
	v_mfma_f32_16x16x32_bf16 v[82:85], v[22:25], v[54:57], v[82:85]
	v_mfma_f32_16x16x32_bf16 v[86:89], v[30:33], v[54:57], v[86:89]
	v_mfma_f32_16x16x32_bf16 v[90:93], v[22:25], v[62:65], v[90:93]
	v_mfma_f32_16x16x32_bf16 v[94:97], v[30:33], v[62:65], v[94:97]
	v_mfma_f32_16x16x32_bf16 v[98:101], v[22:25], v[70:73], v[98:101]
	v_mfma_f32_16x16x32_bf16 v[102:105], v[30:33], v[70:73], v[102:105]
	v_mfma_f32_16x16x32_bf16 v[106:109], v[34:37], v[2:5], 0
	v_mfma_f32_16x16x32_bf16 v[2:5], v[42:45], v[2:5], 0
	v_mfma_f32_16x16x32_bf16 v[110:113], v[46:49], v[6:9], v[2:5]
	v_mfma_f32_16x16x32_bf16 v[2:5], v[34:37], v[50:53], 0
	v_mfma_f32_16x16x32_bf16 v[114:117], v[38:41], v[54:57], v[2:5]
	v_mfma_f32_16x16x32_bf16 v[2:5], v[42:45], v[50:53], 0
	v_mfma_f32_16x16x32_bf16 v[50:53], v[46:49], v[54:57], v[2:5]
	v_mfma_f32_16x16x32_bf16 v[2:5], v[34:37], v[58:61], 0
	v_mfma_f32_16x16x32_bf16 v[54:57], v[38:41], v[62:65], v[2:5]
	v_mfma_f32_16x16x32_bf16 v[2:5], v[42:45], v[58:61], 0
	v_mfma_f32_16x16x32_bf16 v[58:61], v[46:49], v[62:65], v[2:5]
	v_mfma_f32_16x16x32_bf16 v[2:5], v[34:37], v[66:69], 0
	v_mfma_f32_16x16x32_bf16 v[62:65], v[38:41], v[70:73], v[2:5]
	v_mfma_f32_16x16x32_bf16 v[2:5], v[42:45], v[66:69], 0
	v_mfma_f32_16x16x32_bf16 v[106:109], v[38:41], v[6:9], v[106:109]
	v_mfma_f32_16x16x32_bf16 v[66:69], v[46:49], v[70:73], v[2:5]
	s_barrier
	s_nop 3
	v_lshl_add_u64 v[2:3], s[46:47], 0, v[166:167]
	s_mov_b64 s[26:27], 0x100
	s_mov_b32 m0, s8
	v_lshl_add_u64 v[4:5], v[2:3], 0, s[26:27]
	ds_read_b128 v[70:73], v178 offset:16384
	ds_read_b128 v[118:121], v178 offset:17408
	ds_read_b128 v[122:125], v178 offset:18432
	ds_read_b128 v[126:129], v178 offset:19456
	ds_read_b128 v[130:133], v178 offset:20480
	ds_read_b128 v[134:137], v178 offset:21504
	ds_read_b128 v[138:141], v178 offset:22528
	ds_read_b128 v[142:145], v178 offset:23552
	global_load_lds_dwordx4 v[4:5], off
	v_lshl_add_u64 v[4:5], s[46:47], 0, v[162:163]
	s_add_u32 s20, s46, 0x18100
	v_lshl_add_u64 v[6:7], v[4:5], 0, s[26:27]
	s_mov_b32 m0, s9
	s_addc_u32 s21, s47, 0
	global_load_lds_dwordx4 v[6:7], off
	v_lshl_add_u64 v[6:7], s[20:21], 0, v[166:167]
	s_mov_b32 m0, s14
	s_nop 0
	global_load_lds_dwordx4 v[6:7], off
	v_lshl_add_u64 v[6:7], s[20:21], 0, v[162:163]
	s_mov_b32 m0, s34
	s_nop 0
	global_load_lds_dwordx4 v[6:7], off
	v_lshl_add_u64 v[6:7], s[30:31], 0, v[168:169]
	v_lshl_add_u64 v[8:9], v[6:7], 0, s[26:27]
	s_mov_b32 m0, s1
	s_nop 0
	global_load_lds_dwordx4 v[8:9], off
	v_lshl_add_u64 v[8:9], s[30:31], 0, v[164:165]
	v_lshl_add_u64 v[146:147], v[8:9], 0, s[26:27]
	s_mov_b32 m0, s35
	s_nop 0
	global_load_lds_dwordx4 v[146:147], off
	s_waitcnt vmcnt(8)
	s_waitcnt lgkmcnt(0)
	s_barrier
	v_mfma_f32_16x16x32_bf16 v[146:149], v[18:21], v[70:73], 0
	v_mfma_f32_16x16x32_bf16 v[154:157], v[18:21], v[122:125], 0
	v_mfma_f32_16x16x32_bf16 v[170:173], v[18:21], v[130:133], 0
	v_mfma_f32_16x16x32_bf16 v[18:21], v[18:21], v[138:141], 0
	v_mfma_f32_16x16x32_bf16 v[180:183], v[22:25], v[142:145], v[18:21]
	v_mfma_f32_16x16x32_bf16 v[18:21], v[26:29], v[138:141], 0
	v_mfma_f32_16x16x32_bf16 v[150:153], v[26:29], v[70:73], 0
	v_mfma_f32_16x16x32_bf16 v[158:161], v[26:29], v[122:125], 0
	v_mfma_f32_16x16x32_bf16 v[174:177], v[26:29], v[130:133], 0
	v_mfma_f32_16x16x32_bf16 v[26:29], v[30:33], v[142:145], v[18:21]
	v_mfma_f32_16x16x32_bf16 v[146:149], v[22:25], v[118:121], v[146:149]
	v_mfma_f32_16x16x32_bf16 v[150:153], v[30:33], v[118:121], v[150:153]
	v_mfma_f32_16x16x32_bf16 v[154:157], v[22:25], v[126:129], v[154:157]
	v_mfma_f32_16x16x32_bf16 v[158:161], v[30:33], v[126:129], v[158:161]
	v_mfma_f32_16x16x32_bf16 v[170:173], v[22:25], v[134:137], v[170:173]
	v_mfma_f32_16x16x32_bf16 v[174:177], v[30:33], v[134:137], v[174:177]
	v_mfma_f32_16x16x32_bf16 v[18:21], v[34:37], v[70:73], 0
	v_mfma_f32_16x16x32_bf16 v[30:33], v[38:41], v[118:121], v[18:21]
	v_mfma_f32_16x16x32_bf16 v[18:21], v[42:45], v[70:73], 0
	v_mfma_f32_16x16x32_bf16 v[70:73], v[46:49], v[118:121], v[18:21]
	v_mfma_f32_16x16x32_bf16 v[18:21], v[34:37], v[122:125], 0
	v_mfma_f32_16x16x32_bf16 v[118:121], v[38:41], v[126:129], v[18:21]
	v_mfma_f32_16x16x32_bf16 v[18:21], v[42:45], v[122:125], 0
	v_mfma_f32_16x16x32_bf16 v[122:125], v[46:49], v[126:129], v[18:21]
	v_mfma_f32_16x16x32_bf16 v[18:21], v[34:37], v[130:133], 0
	v_mfma_f32_16x16x32_bf16 v[126:129], v[38:41], v[134:137], v[18:21]
	v_mfma_f32_16x16x32_bf16 v[18:21], v[42:45], v[130:133], 0
	v_mfma_f32_16x16x32_bf16 v[130:133], v[46:49], v[134:137], v[18:21]
	v_mfma_f32_16x16x32_bf16 v[18:21], v[34:37], v[138:141], 0
	v_mfma_f32_16x16x32_bf16 v[34:37], v[38:41], v[142:145], v[18:21]
	v_mfma_f32_16x16x32_bf16 v[18:21], v[42:45], v[138:141], 0
	v_mfma_f32_16x16x32_bf16 v[38:41], v[46:49], v[142:145], v[18:21]
	s_barrier
; #define PG8_STAGE(bufoff, gbase, voff) do { _Pragma("unroll") for (int _i = 0; _i < 2; ++_i) \
;         __builtin_amdgcn_global_load_lds((const unsigned*)((const char*)(gbase) + (voff)[_i]), (PG8_LAS unsigned*)(lds + (bufoff) + ldsw + _i * 8192), 16, 0, 0); } while (0)
; #define PG8_LDA(dst, b, h) do { _Pragma("unroll") for (int m = 0; m < 4; ++m) _Pragma("unroll") for (int k = 0; k < 2; ++k) dst[m][k] = *(const PG8_LAS bf16x8*)(lds + PG8_SA(b, h) + aoff + m * 2048 + k * 1024); } while (0)
; #define PG8_LDB(dst, b, h) do { _Pragma("unroll") for (int n = 0; n < 2; ++n) _Pragma("unroll") for (int k = 0; k < 2; ++k) dst[n][k] = *(const PG8_LAS bf16x8*)(lds + PG8_SB(b, h) + boff + n * 2048 + k * 1024); } while (0)
; #define PG8_MMA(ai, bj, At, Bt) do { __builtin_amdgcn_s_setprio(1); _Pragma("unroll") for (int m = 0; m < 4; ++m) _Pragma("unroll") for (int n = 0; n < 2; ++n) _Pragma("unroll") for (int k = 0; k < 2; ++k) \
;         acc[ai][bj][m][n] = __builtin_amdgcn_mfma_f32_16x16x32_bf16(Bt[n][k], At[m][k], acc[ai][bj][m][n], 0, 0, 0); __builtin_amdgcn_s_setprio(0); } while (0)
; #define PG8_WAIT_V(n) asm volatile("s_waitcnt vmcnt(" #n ")" ::: "memory")
; #define PG8_WAIT_L(n) asm volatile("s_waitcnt lgkmcnt(" #n ")" ::: "memory")
; #define PG8_BAR __builtin_amdgcn_s_barrier()
; #define PG8_SCHED __builtin_amdgcn_sched_barrier(0)
; template <class Epi, class Sched, bool ALIGN_EPI = false, bool SP2 = false>
; __device__ __forceinline__ void gemm_phase(PG8_LAS unsigned char* lds, const Gemm g, const Sched& S, const Epi& E, const int tid) {
;     ...
;             PG8_LDB(B0, 1, 0); PG8_LDB(B1, 1, 1); PG8_SCHED; PG8_LDA(At, 1, 0); PG8_STAGE(PG8_SA(0, 1), a2 + hstep, voffA);
;             PG8_WAIT_V(8); PG8_WAIT_L(0); PG8_BAR; PG8_MMA(0, 0, At, B0); PG8_MMA(0, 1, At, B1); PG8_BAR; PG8_SCHED;
;             PG8_LDA(At, 1, 1); PG8_STAGE(PG8_SB(1, 0), b3, voffB); PG8_STAGE(PG8_SB(1, 1), b3 + hstep, voffB); PG8_STAGE(PG8_SA(1, 0), a3, voffA);
;             PG8_WAIT_V(8); PG8_WAIT_L(0); PG8_BAR; PG8_MMA(1, 0, At, B0); PG8_MMA(1, 1, At, B1); PG8_BAR; PG8_SCHED;
	v_or_b32_e32 v17, 0x18000, v179
	s_nop 3
	v_add_u32_e32 v19, 0x18800, v179
	v_or_b32_e32 v21, 0x1c000, v179
	v_add_u32_e32 v23, 0x1c800, v179
	v_add_u32_e32 v18, 0x18400, v179
	ds_read_b128 v[42:45], v17
	ds_read_b128 v[46:49], v18
	v_add_u32_e32 v20, 0x18c00, v179
	ds_read_b128 v[134:137], v19
	ds_read_b128 v[138:141], v20
	v_add_u32_e32 v22, 0x1c400, v179
	ds_read_b128 v[142:145], v21
	ds_read_b128 v[184:187], v22
	v_add_u32_e32 v24, 0x1cc00, v179
	ds_read_b128 v[188:191], v23
	ds_read_b128 v[192:195], v24
	s_add_u32 s20, s30, 0x18100
	s_addc_u32 s21, s31, 0
	s_mov_b32 m0, s84
	v_lshl_add_u64 v[208:209], s[20:21], 0, v[168:169]
	ds_read_b128 v[196:199], v178 offset:32768
	ds_read_b128 v[200:203], v178 offset:33792
	ds_read_b128 v[204:207], v178 offset:34816
	ds_read_b128 v[214:217], v178 offset:35840
	ds_read_b128 v[218:221], v178 offset:36864
	ds_read_b128 v[222:225], v178 offset:37888
	ds_read_b128 v[226:229], v178 offset:38912
	ds_read_b128 v[230:233], v178 offset:39936
	global_load_lds_dwordx4 v[208:209], off
	v_lshl_add_u64 v[208:209], s[20:21], 0, v[164:165]
	s_mov_b32 m0, s85
	s_nop 0
	global_load_lds_dwordx4 v[208:209], off
	s_waitcnt vmcnt(8)
	s_waitcnt lgkmcnt(0)
	s_barrier
	v_mfma_f32_16x16x32_bf16 v[74:77], v[42:45], v[196:199], v[74:77]
	v_mfma_f32_16x16x32_bf16 v[74:77], v[46:49], v[200:203], v[74:77]
	v_mfma_f32_16x16x32_bf16 v[78:81], v[134:137], v[196:199], v[78:81]
	v_mfma_f32_16x16x32_bf16 v[78:81], v[138:141], v[200:203], v[78:81]
	v_mfma_f32_16x16x32_bf16 v[82:85], v[42:45], v[204:207], v[82:85]
	v_mfma_f32_16x16x32_bf16 v[82:85], v[46:49], v[214:217], v[82:85]
	v_mfma_f32_16x16x32_bf16 v[86:89], v[134:137], v[204:207], v[86:89]
	v_mfma_f32_16x16x32_bf16 v[86:89], v[138:141], v[214:217], v[86:89]
	v_mfma_f32_16x16x32_bf16 v[90:93], v[42:45], v[218:221], v[90:93]
	v_mfma_f32_16x16x32_bf16 v[90:93], v[46:49], v[222:225], v[90:93]
	v_mfma_f32_16x16x32_bf16 v[94:97], v[134:137], v[218:221], v[94:97]
	v_mfma_f32_16x16x32_bf16 v[94:97], v[138:141], v[222:225], v[94:97]
	v_mfma_f32_16x16x32_bf16 v[98:101], v[42:45], v[226:229], v[98:101]
	v_mfma_f32_16x16x32_bf16 v[98:101], v[46:49], v[230:233], v[98:101]
	v_mfma_f32_16x16x32_bf16 v[102:105], v[134:137], v[226:229], v[102:105]
	v_mfma_f32_16x16x32_bf16 v[102:105], v[138:141], v[230:233], v[102:105]
	v_mfma_f32_16x16x32_bf16 v[106:109], v[142:145], v[196:199], v[106:109]
	v_mfma_f32_16x16x32_bf16 v[106:109], v[184:187], v[200:203], v[106:109]
	v_mfma_f32_16x16x32_bf16 v[110:113], v[188:191], v[196:199], v[110:113]
	v_mfma_f32_16x16x32_bf16 v[110:113], v[192:195], v[200:203], v[110:113]
	v_mfma_f32_16x16x32_bf16 v[114:117], v[142:145], v[204:207], v[114:117]
	v_mfma_f32_16x16x32_bf16 v[114:117], v[184:187], v[214:217], v[114:117]
	v_mfma_f32_16x16x32_bf16 v[50:53], v[188:191], v[204:207], v[50:53]
	v_mfma_f32_16x16x32_bf16 v[50:53], v[192:195], v[214:217], v[50:53]
	v_mfma_f32_16x16x32_bf16 v[54:57], v[142:145], v[218:221], v[54:57]
	v_mfma_f32_16x16x32_bf16 v[54:57], v[184:187], v[222:225], v[54:57]
	v_mfma_f32_16x16x32_bf16 v[58:61], v[188:191], v[218:221], v[58:61]
	v_mfma_f32_16x16x32_bf16 v[58:61], v[192:195], v[222:225], v[58:61]
	v_mfma_f32_16x16x32_bf16 v[62:65], v[142:145], v[226:229], v[62:65]
	v_mfma_f32_16x16x32_bf16 v[62:65], v[184:187], v[230:233], v[62:65]
	v_mfma_f32_16x16x32_bf16 v[66:69], v[188:191], v[226:229], v[66:69]
	v_mfma_f32_16x16x32_bf16 v[66:69], v[192:195], v[230:233], v[66:69]
	s_barrier
	s_mov_b64 s[26:27], 0x180
	s_mov_b32 m0, s88
	v_lshl_add_u64 v[208:209], v[2:3], 0, s[26:27]
	s_add_u32 s20, s46, 0x18180
	ds_read_b128 v[196:199], v178 offset:49152
	ds_read_b128 v[200:203], v178 offset:50176
	ds_read_b128 v[204:207], v178 offset:51200
	ds_read_b128 v[214:217], v178 offset:52224
	ds_read_b128 v[218:221], v178 offset:53248
	ds_read_b128 v[222:225], v178 offset:54272
	ds_read_b128 v[226:229], v178 offset:55296
	ds_read_b128 v[230:233], v178 offset:56320
	global_load_lds_dwordx4 v[208:209], off
	v_lshl_add_u64 v[208:209], v[4:5], 0, s[26:27]
	s_mov_b32 m0, s89
	s_addc_u32 s21, s47, 0
	global_load_lds_dwordx4 v[208:209], off
	v_lshl_add_u64 v[208:209], s[20:21], 0, v[166:167]
	s_mov_b32 m0, s28
	s_nop 0
	global_load_lds_dwordx4 v[208:209], off
	v_lshl_add_u64 v[208:209], s[20:21], 0, v[162:163]
	s_mov_b32 m0, s29
	s_nop 0
	global_load_lds_dwordx4 v[208:209], off
	v_lshl_add_u64 v[208:209], v[6:7], 0, s[26:27]
	s_mov_b32 m0, s90
	s_nop 0
	global_load_lds_dwordx4 v[208:209], off
	v_lshl_add_u64 v[208:209], v[8:9], 0, s[26:27]
	s_mov_b32 m0, s91
	s_nop 0
	global_load_lds_dwordx4 v[208:209], off
	s_waitcnt vmcnt(8)
	s_waitcnt lgkmcnt(0)
	s_barrier
; #define PG8_STAGE(bufoff, gbase, voff) do { _Pragma("unroll") for (int _i = 0; _i < 2; ++_i) \
;         __builtin_amdgcn_global_load_lds((const unsigned*)((const char*)(gbase) + (voff)[_i]), (PG8_LAS unsigned*)(lds + (bufoff) + ldsw + _i * 8192), 16, 0, 0); } while (0)
; #define PG8_LDA(dst, b, h) do { _Pragma("unroll") for (int m = 0; m < 4; ++m) _Pragma("unroll") for (int k = 0; k < 2; ++k) dst[m][k] = *(const PG8_LAS bf16x8*)(lds + PG8_SA(b, h) + aoff + m * 2048 + k * 1024); } while (0)
; #define PG8_LDB(dst, b, h) do { _Pragma("unroll") for (int n = 0; n < 2; ++n) _Pragma("unroll") for (int k = 0; k < 2; ++k) dst[n][k] = *(const PG8_LAS bf16x8*)(lds + PG8_SB(b, h) + boff + n * 2048 + k * 1024); } while (0)
; #define PG8_MMA(ai, bj, At, Bt) do { __builtin_amdgcn_s_setprio(1); _Pragma("unroll") for (int m = 0; m < 4; ++m) _Pragma("unroll") for (int n = 0; n < 2; ++n) _Pragma("unroll") for (int k = 0; k < 2; ++k) \
;         acc[ai][bj][m][n] = __builtin_amdgcn_mfma_f32_16x16x32_bf16(Bt[n][k], At[m][k], acc[ai][bj][m][n], 0, 0, 0); __builtin_amdgcn_s_setprio(0); } while (0)
; #define PG8_BAR __builtin_amdgcn_s_barrier()
; template <class Epi, class Sched, bool ALIGN_EPI = false, bool SP2 = false>
; __device__ __forceinline__ void gemm_phase(PG8_LAS unsigned char* lds, const Gemm g, const Sched& S, const Epi& E, const int tid) {
;     ...
;             PG8_LDB(B0, 0, 0); PG8_LDB(B1, 0, 1); PG8_SCHED; PG8_LDA(At, 0, 0); PG8_STAGE(PG8_SA(1, 1), a1 + hstep, voffA);
;             PG8_WAIT_V(8); PG8_WAIT_L(0); PG8_BAR; PG8_MMA(0, 0, At, B0); PG8_MMA(0, 1, At, B1); PG8_BAR; PG8_SCHED;
;             PG8_LDA(At, 0, 1); PG8_STAGE(PG8_SB(0, 0), b2, voffB); PG8_STAGE(PG8_SB(0, 1), b2 + hstep, voffB); PG8_STAGE(PG8_SA(0, 0), a2, voffA);
;             PG8_WAIT_V(8); PG8_WAIT_L(0); PG8_BAR; PG8_MMA(1, 0, At, B0); PG8_MMA(1, 1, At, B1); PG8_BAR; PG8_SCHED;
;             PG8_LDB(B0, 1, 0); PG8_LDB(B1, 1, 1); PG8_SCHED; PG8_LDA(At, 1, 0); PG8_STAGE(PG8_SA(0, 1), a2 + hstep, voffA);
;             PG8_WAIT_V(8); PG8_WAIT_L(0); PG8_BAR; PG8_MMA(0, 0, At, B0); PG8_MMA(0, 1, At, B1); PG8_BAR; PG8_SCHED;
;             PG8_LDA(At, 1, 1); PG8_STAGE(PG8_SB(1, 0), b3, voffB); PG8_STAGE(PG8_SB(1, 1), b3 + hstep, voffB); PG8_STAGE(PG8_SA(1, 0), a3, voffA);
;             PG8_WAIT_V(8); PG8_WAIT_L(0); PG8_BAR; PG8_MMA(1, 0, At, B0); PG8_MMA(1, 1, At, B1); PG8_BAR; PG8_SCHED;
	v_mfma_f32_16x16x32_bf16 v[146:149], v[42:45], v[196:199], v[146:149]
	v_mfma_f32_16x16x32_bf16 v[154:157], v[42:45], v[204:207], v[154:157]
	v_mfma_f32_16x16x32_bf16 v[170:173], v[42:45], v[218:221], v[170:173]
	v_mfma_f32_16x16x32_bf16 v[42:45], v[42:45], v[226:229], v[180:183]
	v_mfma_f32_16x16x32_bf16 v[26:29], v[134:137], v[226:229], v[26:29]
	v_mfma_f32_16x16x32_bf16 v[150:153], v[134:137], v[196:199], v[150:153]
	v_mfma_f32_16x16x32_bf16 v[158:161], v[134:137], v[204:207], v[158:161]
	v_mfma_f32_16x16x32_bf16 v[174:177], v[134:137], v[218:221], v[174:177]
	v_mfma_f32_16x16x32_bf16 v[42:45], v[46:49], v[230:233], v[42:45]
	v_mfma_f32_16x16x32_bf16 v[26:29], v[138:141], v[230:233], v[26:29]
	v_mfma_f32_16x16x32_bf16 v[146:149], v[46:49], v[200:203], v[146:149]
	v_mfma_f32_16x16x32_bf16 v[150:153], v[138:141], v[200:203], v[150:153]
	v_mfma_f32_16x16x32_bf16 v[154:157], v[46:49], v[214:217], v[154:157]
	v_mfma_f32_16x16x32_bf16 v[158:161], v[138:141], v[214:217], v[158:161]
	v_mfma_f32_16x16x32_bf16 v[170:173], v[46:49], v[222:225], v[170:173]
	v_mfma_f32_16x16x32_bf16 v[174:177], v[138:141], v[222:225], v[174:177]
	v_mfma_f32_16x16x32_bf16 v[30:33], v[142:145], v[196:199], v[30:33]
	v_mfma_f32_16x16x32_bf16 v[46:49], v[188:191], v[196:199], v[70:73]
	v_mfma_f32_16x16x32_bf16 v[70:73], v[142:145], v[204:207], v[118:121]
	v_mfma_f32_16x16x32_bf16 v[118:121], v[188:191], v[204:207], v[122:125]
	v_mfma_f32_16x16x32_bf16 v[122:125], v[142:145], v[218:221], v[126:129]
	v_mfma_f32_16x16x32_bf16 v[126:129], v[188:191], v[218:221], v[130:133]
	v_mfma_f32_16x16x32_bf16 v[34:37], v[142:145], v[226:229], v[34:37]
	v_mfma_f32_16x16x32_bf16 v[38:41], v[188:191], v[226:229], v[38:41]
	v_mfma_f32_16x16x32_bf16 v[30:33], v[184:187], v[200:203], v[30:33]
	v_mfma_f32_16x16x32_bf16 v[46:49], v[192:195], v[200:203], v[46:49]
	v_mfma_f32_16x16x32_bf16 v[70:73], v[184:187], v[214:217], v[70:73]
	v_mfma_f32_16x16x32_bf16 v[118:121], v[192:195], v[214:217], v[118:121]
	v_mfma_f32_16x16x32_bf16 v[122:125], v[184:187], v[222:225], v[122:125]
	v_mfma_f32_16x16x32_bf16 v[126:129], v[192:195], v[222:225], v[126:129]
	v_mfma_f32_16x16x32_bf16 v[34:37], v[184:187], v[230:233], v[34:37]
	v_mfma_f32_16x16x32_bf16 v[38:41], v[192:195], v[230:233], v[38:41]
	s_barrier
	ds_read_b128 v[130:133], v0
	ds_read_b128 v[134:137], v10
	ds_read_b128 v[138:141], v11
	ds_read_b128 v[142:145], v12
	ds_read_b128 v[180:183], v13
	ds_read_b128 v[184:187], v14
	ds_read_b128 v[188:191], v15
	ds_read_b128 v[192:195], v16
	s_add_u32 s20, s30, 0x18180
	s_addc_u32 s21, s31, 0
	s_mov_b32 m0, s5
	v_lshl_add_u64 v[208:209], s[20:21], 0, v[168:169]
	ds_read_b128 v[196:199], v178
	ds_read_b128 v[200:203], v178 offset:1024
	ds_read_b128 v[204:207], v178 offset:2048
	ds_read_b128 v[214:217], v178 offset:3072
	ds_read_b128 v[218:221], v178 offset:4096
	ds_read_b128 v[222:225], v178 offset:5120
	ds_read_b128 v[226:229], v178 offset:6144
	ds_read_b128 v[230:233], v178 offset:7168
	global_load_lds_dwordx4 v[208:209], off
	v_lshl_add_u64 v[208:209], s[20:21], 0, v[164:165]
	s_mov_b32 m0, s4
	s_nop 0
	global_load_lds_dwordx4 v[208:209], off
	s_waitcnt vmcnt(8)
	s_waitcnt lgkmcnt(0)
	s_barrier
	v_mfma_f32_16x16x32_bf16 v[74:77], v[130:133], v[196:199], v[74:77]
	v_mfma_f32_16x16x32_bf16 v[74:77], v[134:137], v[200:203], v[74:77]
	v_mfma_f32_16x16x32_bf16 v[78:81], v[138:141], v[196:199], v[78:81]
	v_mfma_f32_16x16x32_bf16 v[78:81], v[142:145], v[200:203], v[78:81]
	v_mfma_f32_16x16x32_bf16 v[82:85], v[130:133], v[204:207], v[82:85]
	v_mfma_f32_16x16x32_bf16 v[82:85], v[134:137], v[214:217], v[82:85]
	v_mfma_f32_16x16x32_bf16 v[86:89], v[138:141], v[204:207], v[86:89]
	v_mfma_f32_16x16x32_bf16 v[86:89], v[142:145], v[214:217], v[86:89]
	v_mfma_f32_16x16x32_bf16 v[90:93], v[130:133], v[218:221], v[90:93]
	v_mfma_f32_16x16x32_bf16 v[90:93], v[134:137], v[222:225], v[90:93]
	v_mfma_f32_16x16x32_bf16 v[94:97], v[138:141], v[218:221], v[94:97]
	v_mfma_f32_16x16x32_bf16 v[94:97], v[142:145], v[222:225], v[94:97]
	v_mfma_f32_16x16x32_bf16 v[98:101], v[130:133], v[226:229], v[98:101]
	v_mfma_f32_16x16x32_bf16 v[98:101], v[134:137], v[230:233], v[98:101]
	v_mfma_f32_16x16x32_bf16 v[102:105], v[138:141], v[226:229], v[102:105]
	v_mfma_f32_16x16x32_bf16 v[102:105], v[142:145], v[230:233], v[102:105]
	v_mfma_f32_16x16x32_bf16 v[106:109], v[180:183], v[196:199], v[106:109]
	v_mfma_f32_16x16x32_bf16 v[106:109], v[184:187], v[200:203], v[106:109]
	v_mfma_f32_16x16x32_bf16 v[110:113], v[188:191], v[196:199], v[110:113]
	v_mfma_f32_16x16x32_bf16 v[110:113], v[192:195], v[200:203], v[110:113]
	v_mfma_f32_16x16x32_bf16 v[114:117], v[180:183], v[204:207], v[114:117]
	v_mfma_f32_16x16x32_bf16 v[114:117], v[184:187], v[214:217], v[114:117]
	v_mfma_f32_16x16x32_bf16 v[50:53], v[188:191], v[204:207], v[50:53]
	v_mfma_f32_16x16x32_bf16 v[50:53], v[192:195], v[214:217], v[50:53]
	v_mfma_f32_16x16x32_bf16 v[54:57], v[180:183], v[218:221], v[54:57]
	v_mfma_f32_16x16x32_bf16 v[54:57], v[184:187], v[222:225], v[54:57]
	v_mfma_f32_16x16x32_bf16 v[58:61], v[188:191], v[218:221], v[58:61]
	v_mfma_f32_16x16x32_bf16 v[58:61], v[192:195], v[222:225], v[58:61]
	v_mfma_f32_16x16x32_bf16 v[62:65], v[180:183], v[226:229], v[62:65]
	v_mfma_f32_16x16x32_bf16 v[62:65], v[184:187], v[230:233], v[62:65]
	v_mfma_f32_16x16x32_bf16 v[66:69], v[188:191], v[226:229], v[66:69]
	v_mfma_f32_16x16x32_bf16 v[66:69], v[192:195], v[230:233], v[66:69]
	s_barrier
; #define PG8_STAGE(bufoff, gbase, voff) do { _Pragma("unroll") for (int _i = 0; _i < 2; ++_i) \
;         __builtin_amdgcn_global_load_lds((const unsigned*)((const char*)(gbase) + (voff)[_i]), (PG8_LAS unsigned*)(lds + (bufoff) + ldsw + _i * 8192), 16, 0, 0); } while (0)
; #define PG8_LDA(dst, b, h) do { _Pragma("unroll") for (int m = 0; m < 4; ++m) _Pragma("unroll") for (int k = 0; k < 2; ++k) dst[m][k] = *(const PG8_LAS bf16x8*)(lds + PG8_SA(b, h) + aoff + m * 2048 + k * 1024); } while (0)
; #define PG8_LDB(dst, b, h) do { _Pragma("unroll") for (int n = 0; n < 2; ++n) _Pragma("unroll") for (int k = 0; k < 2; ++k) dst[n][k] = *(const PG8_LAS bf16x8*)(lds + PG8_SB(b, h) + boff + n * 2048 + k * 1024); } while (0)
; #define PG8_MMA(ai, bj, At, Bt) do { __builtin_amdgcn_s_setprio(1); _Pragma("unroll") for (int m = 0; m < 4; ++m) _Pragma("unroll") for (int n = 0; n < 2; ++n) _Pragma("unroll") for (int k = 0; k < 2; ++k) \
;         acc[ai][bj][m][n] = __builtin_amdgcn_mfma_f32_16x16x32_bf16(Bt[n][k], At[m][k], acc[ai][bj][m][n], 0, 0, 0); __builtin_amdgcn_s_setprio(0); } while (0)
; #define PG8_WAIT_V(n) asm volatile("s_waitcnt vmcnt(" #n ")" ::: "memory")
; #define PG8_WAIT_L(n) asm volatile("s_waitcnt lgkmcnt(" #n ")" ::: "memory")
; #define PG8_BAR __builtin_amdgcn_s_barrier()
; #define PG8_SCHED __builtin_amdgcn_sched_barrier(0)
; template <class Epi, class Sched, bool ALIGN_EPI = false, bool SP2 = false>
; __device__ __forceinline__ void gemm_phase(PG8_LAS unsigned char* lds, const Gemm g, const Sched& S, const Epi& E, const int tid) {
;     ...
;             PG8_LDA(At, 0, 1); PG8_STAGE(PG8_SB(0, 0), b2, voffB); PG8_STAGE(PG8_SB(0, 1), b2 + hstep, voffB); PG8_STAGE(PG8_SA(0, 0), a2, voffA);
;             PG8_WAIT_V(8); PG8_WAIT_L(0); PG8_BAR; PG8_MMA(1, 0, At, B0); PG8_MMA(1, 1, At, B1); PG8_BAR; PG8_SCHED;
;             PG8_LDB(B0, 1, 0); PG8_LDB(B1, 1, 1); PG8_SCHED; PG8_LDA(At, 1, 0); PG8_STAGE(PG8_SA(0, 1), a2 + hstep, voffA);
;             PG8_WAIT_V(8); PG8_WAIT_L(0); PG8_BAR; PG8_MMA(0, 0, At, B0); PG8_MMA(0, 1, At, B1); PG8_BAR; PG8_SCHED;
	s_mov_b64 s[26:27], 0x200
	s_mov_b32 m0, s8
	v_lshl_add_u64 v[208:209], v[2:3], 0, s[26:27]
	s_add_u32 s20, s46, 0x18200
	ds_read_b128 v[196:199], v178 offset:16384
	ds_read_b128 v[200:203], v178 offset:17408
	ds_read_b128 v[204:207], v178 offset:18432
	ds_read_b128 v[214:217], v178 offset:19456
	ds_read_b128 v[218:221], v178 offset:20480
	ds_read_b128 v[222:225], v178 offset:21504
	ds_read_b128 v[226:229], v178 offset:22528
	ds_read_b128 v[230:233], v178 offset:23552
	global_load_lds_dwordx4 v[208:209], off
	v_lshl_add_u64 v[208:209], v[4:5], 0, s[26:27]
	s_mov_b32 m0, s9
	s_addc_u32 s21, s47, 0
	global_load_lds_dwordx4 v[208:209], off
	v_lshl_add_u64 v[208:209], s[20:21], 0, v[166:167]
	s_mov_b32 m0, s14
	s_nop 0
	global_load_lds_dwordx4 v[208:209], off
	v_lshl_add_u64 v[208:209], s[20:21], 0, v[162:163]
	s_mov_b32 m0, s34
	s_nop 0
	global_load_lds_dwordx4 v[208:209], off
	v_lshl_add_u64 v[208:209], v[6:7], 0, s[26:27]
	s_mov_b32 m0, s1
	s_nop 0
	global_load_lds_dwordx4 v[208:209], off
	v_lshl_add_u64 v[208:209], v[8:9], 0, s[26:27]
	s_mov_b32 m0, s35
	s_nop 0
	global_load_lds_dwordx4 v[208:209], off
	s_waitcnt vmcnt(8)
	s_waitcnt lgkmcnt(0)
	s_barrier
	v_mfma_f32_16x16x32_bf16 v[42:45], v[130:133], v[226:229], v[42:45]
	v_mfma_f32_16x16x32_bf16 v[42:45], v[134:137], v[230:233], v[42:45]
	v_mfma_f32_16x16x32_bf16 v[26:29], v[138:141], v[226:229], v[26:29]
	v_mfma_f32_16x16x32_bf16 v[26:29], v[142:145], v[230:233], v[26:29]
	v_mfma_f32_16x16x32_bf16 v[146:149], v[130:133], v[196:199], v[146:149]
	v_mfma_f32_16x16x32_bf16 v[146:149], v[134:137], v[200:203], v[146:149]
	v_mfma_f32_16x16x32_bf16 v[150:153], v[138:141], v[196:199], v[150:153]
	v_mfma_f32_16x16x32_bf16 v[150:153], v[142:145], v[200:203], v[150:153]
	v_mfma_f32_16x16x32_bf16 v[154:157], v[130:133], v[204:207], v[154:157]
	v_mfma_f32_16x16x32_bf16 v[154:157], v[134:137], v[214:217], v[154:157]
	v_mfma_f32_16x16x32_bf16 v[158:161], v[138:141], v[204:207], v[158:161]
	v_mfma_f32_16x16x32_bf16 v[158:161], v[142:145], v[214:217], v[158:161]
	v_mfma_f32_16x16x32_bf16 v[170:173], v[130:133], v[218:221], v[170:173]
	v_mfma_f32_16x16x32_bf16 v[170:173], v[134:137], v[222:225], v[170:173]
	v_mfma_f32_16x16x32_bf16 v[174:177], v[138:141], v[218:221], v[174:177]
	v_mfma_f32_16x16x32_bf16 v[174:177], v[142:145], v[222:225], v[174:177]
	v_mfma_f32_16x16x32_bf16 v[30:33], v[180:183], v[196:199], v[30:33]
	v_mfma_f32_16x16x32_bf16 v[30:33], v[184:187], v[200:203], v[30:33]
	v_mfma_f32_16x16x32_bf16 v[46:49], v[188:191], v[196:199], v[46:49]
	v_mfma_f32_16x16x32_bf16 v[46:49], v[192:195], v[200:203], v[46:49]
	v_mfma_f32_16x16x32_bf16 v[70:73], v[180:183], v[204:207], v[70:73]
	v_mfma_f32_16x16x32_bf16 v[70:73], v[184:187], v[214:217], v[70:73]
	v_mfma_f32_16x16x32_bf16 v[118:121], v[188:191], v[204:207], v[118:121]
	v_mfma_f32_16x16x32_bf16 v[118:121], v[192:195], v[214:217], v[118:121]
	v_mfma_f32_16x16x32_bf16 v[122:125], v[180:183], v[218:221], v[122:125]
	v_mfma_f32_16x16x32_bf16 v[122:125], v[184:187], v[222:225], v[122:125]
	v_mfma_f32_16x16x32_bf16 v[126:129], v[188:191], v[218:221], v[126:129]
	v_mfma_f32_16x16x32_bf16 v[126:129], v[192:195], v[222:225], v[126:129]
	v_mfma_f32_16x16x32_bf16 v[34:37], v[180:183], v[226:229], v[34:37]
	v_mfma_f32_16x16x32_bf16 v[34:37], v[184:187], v[230:233], v[34:37]
	v_mfma_f32_16x16x32_bf16 v[38:41], v[188:191], v[226:229], v[38:41]
	v_mfma_f32_16x16x32_bf16 v[38:41], v[192:195], v[230:233], v[38:41]
	s_barrier
	ds_read_b128 v[130:133], v17
	ds_read_b128 v[134:137], v18
	ds_read_b128 v[138:141], v19
	ds_read_b128 v[142:145], v20
	ds_read_b128 v[180:183], v21
	ds_read_b128 v[184:187], v22
	ds_read_b128 v[188:191], v23
	ds_read_b128 v[192:195], v24
	s_add_u32 s20, s30, 0x18200
	s_addc_u32 s21, s31, 0
	s_mov_b32 m0, s84
	v_lshl_add_u64 v[208:209], s[20:21], 0, v[168:169]
	ds_read_b128 v[196:199], v178 offset:32768
	ds_read_b128 v[200:203], v178 offset:33792
	ds_read_b128 v[204:207], v178 offset:34816
	ds_read_b128 v[214:217], v178 offset:35840
	ds_read_b128 v[218:221], v178 offset:36864
	ds_read_b128 v[222:225], v178 offset:37888
	ds_read_b128 v[226:229], v178 offset:38912
	ds_read_b128 v[230:233], v178 offset:39936
	global_load_lds_dwordx4 v[208:209], off
	v_lshl_add_u64 v[208:209], s[20:21], 0, v[164:165]
	s_mov_b32 m0, s85
	s_nop 0
	global_load_lds_dwordx4 v[208:209], off
	s_waitcnt vmcnt(8)
	s_waitcnt lgkmcnt(0)
	s_barrier
	v_mfma_f32_16x16x32_bf16 v[74:77], v[130:133], v[196:199], v[74:77]
	v_mfma_f32_16x16x32_bf16 v[74:77], v[134:137], v[200:203], v[74:77]
	v_mfma_f32_16x16x32_bf16 v[78:81], v[138:141], v[196:199], v[78:81]
	v_mfma_f32_16x16x32_bf16 v[78:81], v[142:145], v[200:203], v[78:81]
	v_mfma_f32_16x16x32_bf16 v[82:85], v[130:133], v[204:207], v[82:85]
	v_mfma_f32_16x16x32_bf16 v[82:85], v[134:137], v[214:217], v[82:85]
	v_mfma_f32_16x16x32_bf16 v[86:89], v[138:141], v[204:207], v[86:89]
	v_mfma_f32_16x16x32_bf16 v[86:89], v[142:145], v[214:217], v[86:89]
	v_mfma_f32_16x16x32_bf16 v[90:93], v[130:133], v[218:221], v[90:93]
	v_mfma_f32_16x16x32_bf16 v[90:93], v[134:137], v[222:225], v[90:93]
	v_mfma_f32_16x16x32_bf16 v[94:97], v[138:141], v[218:221], v[94:97]
	v_mfma_f32_16x16x32_bf16 v[94:97], v[142:145], v[222:225], v[94:97]
	v_mfma_f32_16x16x32_bf16 v[98:101], v[130:133], v[226:229], v[98:101]
	v_mfma_f32_16x16x32_bf16 v[98:101], v[134:137], v[230:233], v[98:101]
	v_mfma_f32_16x16x32_bf16 v[102:105], v[138:141], v[226:229], v[102:105]
	v_mfma_f32_16x16x32_bf16 v[102:105], v[142:145], v[230:233], v[102:105]
	v_mfma_f32_16x16x32_bf16 v[106:109], v[180:183], v[196:199], v[106:109]
	v_mfma_f32_16x16x32_bf16 v[106:109], v[184:187], v[200:203], v[106:109]
	v_mfma_f32_16x16x32_bf16 v[110:113], v[188:191], v[196:199], v[110:113]
	v_mfma_f32_16x16x32_bf16 v[110:113], v[192:195], v[200:203], v[110:113]
	v_mfma_f32_16x16x32_bf16 v[114:117], v[180:183], v[204:207], v[114:117]
	v_mfma_f32_16x16x32_bf16 v[114:117], v[184:187], v[214:217], v[114:117]
	v_mfma_f32_16x16x32_bf16 v[50:53], v[188:191], v[204:207], v[50:53]
	v_mfma_f32_16x16x32_bf16 v[50:53], v[192:195], v[214:217], v[50:53]
	v_mfma_f32_16x16x32_bf16 v[54:57], v[180:183], v[218:221], v[54:57]
	v_mfma_f32_16x16x32_bf16 v[54:57], v[184:187], v[222:225], v[54:57]
	v_mfma_f32_16x16x32_bf16 v[58:61], v[188:191], v[218:221], v[58:61]
	v_mfma_f32_16x16x32_bf16 v[58:61], v[192:195], v[222:225], v[58:61]
	v_mfma_f32_16x16x32_bf16 v[62:65], v[180:183], v[226:229], v[62:65]
	v_mfma_f32_16x16x32_bf16 v[62:65], v[184:187], v[230:233], v[62:65]
	v_mfma_f32_16x16x32_bf16 v[66:69], v[188:191], v[226:229], v[66:69]
	v_mfma_f32_16x16x32_bf16 v[66:69], v[192:195], v[230:233], v[66:69]
	s_barrier
; #define PG8_STAGE(bufoff, gbase, voff) do { _Pragma("unroll") for (int _i = 0; _i < 2; ++_i) \
;         __builtin_amdgcn_global_load_lds((const unsigned*)((const char*)(gbase) + (voff)[_i]), (PG8_LAS unsigned*)(lds + (bufoff) + ldsw + _i * 8192), 16, 0, 0); } while (0)
; #define PG8_LDA(dst, b, h) do { _Pragma("unroll") for (int m = 0; m < 4; ++m) _Pragma("unroll") for (int k = 0; k < 2; ++k) dst[m][k] = *(const PG8_LAS bf16x8*)(lds + PG8_SA(b, h) + aoff + m * 2048 + k * 1024); } while (0)
; #define PG8_LDB(dst, b, h) do { _Pragma("unroll") for (int n = 0; n < 2; ++n) _Pragma("unroll") for (int k = 0; k < 2; ++k) dst[n][k] = *(const PG8_LAS bf16x8*)(lds + PG8_SB(b, h) + boff + n * 2048 + k * 1024); } while (0)
; #define PG8_MMA(ai, bj, At, Bt) do { __builtin_amdgcn_s_setprio(1); _Pragma("unroll") for (int m = 0; m < 4; ++m) _Pragma("unroll") for (int n = 0; n < 2; ++n) _Pragma("unroll") for (int k = 0; k < 2; ++k) \
;         acc[ai][bj][m][n] = __builtin_amdgcn_mfma_f32_16x16x32_bf16(Bt[n][k], At[m][k], acc[ai][bj][m][n], 0, 0, 0); __builtin_amdgcn_s_setprio(0); } while (0)
; #define PG8_BAR __builtin_amdgcn_s_barrier()
; template <class Epi, class Sched, bool ALIGN_EPI = false, bool SP2 = false>
; __device__ __forceinline__ void gemm_phase(PG8_LAS unsigned char* lds, const Gemm g, const Sched& S, const Epi& E, const int tid) {
;     ...
;             PG8_LDB(B0, 0, 0); PG8_LDB(B1, 0, 1); PG8_SCHED; PG8_LDA(At, 0, 0); PG8_STAGE(PG8_SA(1, 1), a1 + hstep, voffA);
;             PG8_WAIT_V(8); PG8_WAIT_L(0); PG8_BAR; PG8_MMA(0, 0, At, B0); PG8_MMA(0, 1, At, B1); PG8_BAR; PG8_SCHED;
;             PG8_LDA(At, 0, 1); PG8_STAGE(PG8_SB(0, 0), b2, voffB); PG8_STAGE(PG8_SB(0, 1), b2 + hstep, voffB); PG8_STAGE(PG8_SA(0, 0), a2, voffA);
;             PG8_WAIT_V(8); PG8_WAIT_L(0); PG8_BAR; PG8_MMA(1, 0, At, B0); PG8_MMA(1, 1, At, B1); PG8_BAR; PG8_SCHED;
;             PG8_LDB(B0, 1, 0); PG8_LDB(B1, 1, 1); PG8_SCHED; PG8_LDA(At, 1, 0); PG8_STAGE(PG8_SA(0, 1), a2 + hstep, voffA);
;             PG8_WAIT_V(8); PG8_WAIT_L(0); PG8_BAR; PG8_MMA(0, 0, At, B0); PG8_MMA(0, 1, At, B1); PG8_BAR; PG8_SCHED;
;             PG8_LDA(At, 1, 1); PG8_STAGE(PG8_SB(1, 0), b3, voffB); PG8_STAGE(PG8_SB(1, 1), b3 + hstep, voffB); PG8_STAGE(PG8_SA(1, 0), a3, voffA);
;             PG8_WAIT_V(8); PG8_WAIT_L(0); PG8_BAR; PG8_MMA(1, 0, At, B0); PG8_MMA(1, 1, At, B1); PG8_BAR; PG8_SCHED;
	s_mov_b64 s[26:27], 0x280
	s_mov_b32 m0, s88
	v_lshl_add_u64 v[2:3], v[2:3], 0, s[26:27]
	s_add_u32 s20, s46, 0x18280
	ds_read_b128 v[196:199], v178 offset:49152
	ds_read_b128 v[200:203], v178 offset:50176
	ds_read_b128 v[204:207], v178 offset:51200
	ds_read_b128 v[214:217], v178 offset:52224
	ds_read_b128 v[218:221], v178 offset:53248
	ds_read_b128 v[222:225], v178 offset:54272
	ds_read_b128 v[226:229], v178 offset:55296
	ds_read_b128 v[230:233], v178 offset:56320
	global_load_lds_dwordx4 v[2:3], off
	v_lshl_add_u64 v[2:3], v[4:5], 0, s[26:27]
	s_mov_b32 m0, s89
	s_addc_u32 s21, s47, 0
	global_load_lds_dwordx4 v[2:3], off
	v_lshl_add_u64 v[2:3], s[20:21], 0, v[166:167]
	s_mov_b32 m0, s28
	s_nop 0
	global_load_lds_dwordx4 v[2:3], off
	v_lshl_add_u64 v[2:3], s[20:21], 0, v[162:163]
	s_mov_b32 m0, s29
	s_nop 0
	global_load_lds_dwordx4 v[2:3], off
	v_lshl_add_u64 v[2:3], v[6:7], 0, s[26:27]
	s_mov_b32 m0, s90
	s_nop 0
	global_load_lds_dwordx4 v[2:3], off
	v_lshl_add_u64 v[2:3], v[8:9], 0, s[26:27]
	s_mov_b32 m0, s91
	s_nop 0
	global_load_lds_dwordx4 v[2:3], off
	s_waitcnt vmcnt(8)
	s_waitcnt lgkmcnt(0)
	s_barrier
	v_mfma_f32_16x16x32_bf16 v[2:5], v[130:133], v[196:199], v[146:149]
	v_mfma_f32_16x16x32_bf16 v[6:9], v[138:141], v[196:199], v[150:153]
	v_mfma_f32_16x16x32_bf16 v[42:45], v[130:133], v[226:229], v[42:45]
	v_mfma_f32_16x16x32_bf16 v[26:29], v[138:141], v[226:229], v[26:29]
	v_mfma_f32_16x16x32_bf16 v[2:5], v[134:137], v[200:203], v[2:5]
	v_mfma_f32_16x16x32_bf16 v[6:9], v[142:145], v[200:203], v[6:9]
	v_mfma_f32_16x16x32_bf16 v[146:149], v[130:133], v[204:207], v[154:157]
	v_mfma_f32_16x16x32_bf16 v[150:153], v[138:141], v[204:207], v[158:161]
	v_mfma_f32_16x16x32_bf16 v[154:157], v[130:133], v[218:221], v[170:173]
	v_mfma_f32_16x16x32_bf16 v[158:161], v[138:141], v[218:221], v[174:177]
	v_mfma_f32_16x16x32_bf16 v[42:45], v[134:137], v[230:233], v[42:45]
	v_mfma_f32_16x16x32_bf16 v[26:29], v[142:145], v[230:233], v[26:29]
	v_mfma_f32_16x16x32_bf16 v[146:149], v[134:137], v[214:217], v[146:149]
	v_mfma_f32_16x16x32_bf16 v[150:153], v[142:145], v[214:217], v[150:153]
	v_mfma_f32_16x16x32_bf16 v[154:157], v[134:137], v[222:225], v[154:157]
	v_mfma_f32_16x16x32_bf16 v[158:161], v[142:145], v[222:225], v[158:161]
	v_mfma_f32_16x16x32_bf16 v[30:33], v[180:183], v[196:199], v[30:33]
	v_mfma_f32_16x16x32_bf16 v[30:33], v[184:187], v[200:203], v[30:33]
	v_mfma_f32_16x16x32_bf16 v[46:49], v[188:191], v[196:199], v[46:49]
	v_mfma_f32_16x16x32_bf16 v[46:49], v[192:195], v[200:203], v[46:49]
	v_mfma_f32_16x16x32_bf16 v[70:73], v[180:183], v[204:207], v[70:73]
	v_mfma_f32_16x16x32_bf16 v[70:73], v[184:187], v[214:217], v[70:73]
	v_mfma_f32_16x16x32_bf16 v[118:121], v[188:191], v[204:207], v[118:121]
	v_mfma_f32_16x16x32_bf16 v[118:121], v[192:195], v[214:217], v[118:121]
	v_mfma_f32_16x16x32_bf16 v[122:125], v[180:183], v[218:221], v[122:125]
	v_mfma_f32_16x16x32_bf16 v[122:125], v[184:187], v[222:225], v[122:125]
	v_mfma_f32_16x16x32_bf16 v[126:129], v[188:191], v[218:221], v[126:129]
	v_mfma_f32_16x16x32_bf16 v[126:129], v[192:195], v[222:225], v[126:129]
	v_mfma_f32_16x16x32_bf16 v[34:37], v[180:183], v[226:229], v[34:37]
	v_mfma_f32_16x16x32_bf16 v[34:37], v[184:187], v[230:233], v[34:37]
	v_mfma_f32_16x16x32_bf16 v[38:41], v[188:191], v[226:229], v[38:41]
	v_mfma_f32_16x16x32_bf16 v[38:41], v[192:195], v[230:233], v[38:41]
	s_barrier
	ds_read_b128 v[130:133], v0
	ds_read_b128 v[134:137], v10
	ds_read_b128 v[138:141], v11
	ds_read_b128 v[142:145], v12
	ds_read_b128 v[10:13], v13
	ds_read_b128 v[170:173], v14
	ds_read_b128 v[174:177], v15
	ds_read_b128 v[180:183], v16
	s_add_u32 s20, s30, 0x18280
	s_addc_u32 s21, s31, 0
	s_mov_b32 m0, s5
	v_lshl_add_u64 v[14:15], s[20:21], 0, v[168:169]
	ds_read_b128 v[184:187], v178
	ds_read_b128 v[188:191], v178 offset:1024
	ds_read_b128 v[192:195], v178 offset:2048
	ds_read_b128 v[196:199], v178 offset:3072
	ds_read_b128 v[200:203], v178 offset:4096
	ds_read_b128 v[204:207], v178 offset:5120
	ds_read_b128 v[214:217], v178 offset:6144
	ds_read_b128 v[218:221], v178 offset:7168
	global_load_lds_dwordx4 v[14:15], off
	v_lshl_add_u64 v[14:15], s[20:21], 0, v[164:165]
	s_mov_b32 m0, s4
	s_nop 0
	global_load_lds_dwordx4 v[14:15], off
	s_waitcnt vmcnt(8)
	s_waitcnt lgkmcnt(0)
	s_barrier
	v_mfma_f32_16x16x32_bf16 v[94:97], v[138:141], v[200:203], v[94:97]
	v_mfma_f32_16x16x32_bf16 v[222:225], v[142:145], v[204:207], v[94:97]
	v_mfma_f32_16x16x32_bf16 v[94:97], v[130:133], v[214:217], v[98:101]
	v_mfma_f32_16x16x32_bf16 v[74:77], v[130:133], v[184:187], v[74:77]
	v_mfma_f32_16x16x32_bf16 v[78:81], v[138:141], v[184:187], v[78:81]
	v_mfma_f32_16x16x32_bf16 v[82:85], v[130:133], v[192:195], v[82:85]
	v_mfma_f32_16x16x32_bf16 v[86:89], v[138:141], v[192:195], v[86:89]
	v_mfma_f32_16x16x32_bf16 v[90:93], v[130:133], v[200:203], v[90:93]
	v_mfma_f32_16x16x32_bf16 v[98:101], v[134:137], v[218:221], v[94:97]
	v_mfma_f32_16x16x32_bf16 v[94:97], v[138:141], v[214:217], v[102:105]
	v_mfma_f32_16x16x32_bf16 v[74:77], v[134:137], v[188:191], v[74:77]
	v_mfma_f32_16x16x32_bf16 v[78:81], v[142:145], v[188:191], v[78:81]
	v_mfma_f32_16x16x32_bf16 v[82:85], v[134:137], v[196:199], v[82:85]
	v_mfma_f32_16x16x32_bf16 v[86:89], v[142:145], v[196:199], v[86:89]
	v_mfma_f32_16x16x32_bf16 v[90:93], v[134:137], v[204:207], v[90:93]
	v_mfma_f32_16x16x32_bf16 v[102:105], v[142:145], v[218:221], v[94:97]
	v_mfma_f32_16x16x32_bf16 v[94:97], v[10:13], v[184:187], v[106:109]
	v_mfma_f32_16x16x32_bf16 v[226:229], v[170:173], v[188:191], v[94:97]
	v_mfma_f32_16x16x32_bf16 v[94:97], v[174:177], v[184:187], v[110:113]
	v_mfma_f32_16x16x32_bf16 v[50:53], v[174:177], v[192:195], v[50:53]
	v_mfma_f32_16x16x32_bf16 v[54:57], v[10:13], v[200:203], v[54:57]
	v_mfma_f32_16x16x32_bf16 v[58:61], v[174:177], v[200:203], v[58:61]
	v_mfma_f32_16x16x32_bf16 v[62:65], v[10:13], v[214:217], v[62:65]
	v_mfma_f32_16x16x32_bf16 v[184:187], v[180:183], v[188:191], v[94:97]
	v_mfma_f32_16x16x32_bf16 v[94:97], v[10:13], v[192:195], v[114:117]
	v_mfma_f32_16x16x32_bf16 v[50:53], v[180:183], v[196:199], v[50:53]
	v_mfma_f32_16x16x32_bf16 v[54:57], v[170:173], v[204:207], v[54:57]
	v_mfma_f32_16x16x32_bf16 v[58:61], v[180:183], v[204:207], v[58:61]
	v_mfma_f32_16x16x32_bf16 v[62:65], v[170:173], v[218:221], v[62:65]
	v_mfma_f32_16x16x32_bf16 v[66:69], v[174:177], v[214:217], v[66:69]
	v_mfma_f32_16x16x32_bf16 v[188:191], v[170:173], v[196:199], v[94:97]
	v_mfma_f32_16x16x32_bf16 v[192:195], v[180:183], v[218:221], v[66:69]
	s_barrier
; #define PG8_STAGE(bufoff, gbase, voff) do { _Pragma("unroll") for (int _i = 0; _i < 2; ++_i) \
;         __builtin_amdgcn_global_load_lds((const unsigned*)((const char*)(gbase) + (voff)[_i]), (PG8_LAS unsigned*)(lds + (bufoff) + ldsw + _i * 8192), 16, 0, 0); } while (0)
; #define PG8_LDA(dst, b, h) do { _Pragma("unroll") for (int m = 0; m < 4; ++m) _Pragma("unroll") for (int k = 0; k < 2; ++k) dst[m][k] = *(const PG8_LAS bf16x8*)(lds + PG8_SA(b, h) + aoff + m * 2048 + k * 1024); } while (0)
; #define PG8_LDB(dst, b, h) do { _Pragma("unroll") for (int n = 0; n < 2; ++n) _Pragma("unroll") for (int k = 0; k < 2; ++k) dst[n][k] = *(const PG8_LAS bf16x8*)(lds + PG8_SB(b, h) + boff + n * 2048 + k * 1024); } while (0)
; #define PG8_MMA(ai, bj, At, Bt) do { __builtin_amdgcn_s_setprio(1); _Pragma("unroll") for (int m = 0; m < 4; ++m) _Pragma("unroll") for (int n = 0; n < 2; ++n) _Pragma("unroll") for (int k = 0; k < 2; ++k) \
;         acc[ai][bj][m][n] = __builtin_amdgcn_mfma_f32_16x16x32_bf16(Bt[n][k], At[m][k], acc[ai][bj][m][n], 0, 0, 0); __builtin_amdgcn_s_setprio(0); } while (0)
; #define PG8_WAIT_V(n) asm volatile("s_waitcnt vmcnt(" #n ")" ::: "memory")
; #define PG8_WAIT_L(n) asm volatile("s_waitcnt lgkmcnt(" #n ")" ::: "memory")
; #define PG8_BAR __builtin_amdgcn_s_barrier()
; #define PG8_SCHED __builtin_amdgcn_sched_barrier(0)
; template <class Epi, class Sched, bool ALIGN_EPI = false, bool SP2 = false>
; __device__ __forceinline__ void gemm_phase(PG8_LAS unsigned char* lds, const Gemm g, const Sched& S, const Epi& E, const int tid) {
;     ...
;             PG8_LDA(At, 0, 1); PG8_STAGE(PG8_SB(0, 0), b2, voffB); PG8_STAGE(PG8_SB(0, 1), b2 + hstep, voffB); PG8_STAGE(PG8_SA(0, 0), a2, voffA);
;             PG8_WAIT_V(8); PG8_WAIT_L(0); PG8_BAR; PG8_MMA(1, 0, At, B0); PG8_MMA(1, 1, At, B1); PG8_BAR; PG8_SCHED;
;             PG8_LDB(B0, 1, 0); PG8_LDB(B1, 1, 1); PG8_SCHED; PG8_LDA(At, 1, 0); PG8_STAGE(PG8_SA(0, 1), a2 + hstep, voffA);
;             PG8_WAIT_V(8); PG8_WAIT_L(0); PG8_BAR; PG8_MMA(0, 0, At, B0); PG8_MMA(0, 1, At, B1); PG8_BAR; PG8_SCHED;
	s_mov_b32 m0, s8
	v_lshl_add_u64 v[208:209], s[44:45], 0, v[166:167]
	s_add_u32 s4, s44, 0x18000
	s_nop 0
	ds_read_b128 v[66:69], v178 offset:16384
	ds_read_b128 v[94:97], v178 offset:17408
	ds_read_b128 v[106:109], v178 offset:18432
	ds_read_b128 v[110:113], v178 offset:19456
	ds_read_b128 v[114:117], v178 offset:20480
	ds_read_b128 v[196:199], v178 offset:21504
	ds_read_b128 v[200:203], v178 offset:22528
	ds_read_b128 v[204:207], v178 offset:23552
	global_load_lds_dwordx4 v[208:209], off
	v_lshl_add_u64 v[210:211], s[44:45], 0, v[162:163]
	s_mov_b32 m0, s9
	s_addc_u32 s5, s45, 0
	global_load_lds_dwordx4 v[210:211], off
	v_lshl_add_u64 v[14:15], s[4:5], 0, v[166:167]
	s_mov_b32 m0, s14
	v_lshl_add_u64 v[212:213], s[38:39], 0, v[168:169]
	global_load_lds_dwordx4 v[14:15], off
	v_lshl_add_u64 v[14:15], s[4:5], 0, v[162:163]
	s_mov_b32 m0, s34
	v_lshl_add_u64 v[246:247], s[38:39], 0, v[164:165]
	global_load_lds_dwordx4 v[14:15], off
	s_mov_b32 m0, s1
	s_nop 0
	global_load_lds_dwordx4 v[212:213], off
	s_mov_b32 m0, s35
	s_nop 0
	global_load_lds_dwordx4 v[246:247], off
	s_waitcnt vmcnt(8)
	s_waitcnt lgkmcnt(0)
	s_barrier
	v_mfma_f32_16x16x32_bf16 v[2:5], v[130:133], v[66:69], v[2:5]
	v_mfma_f32_16x16x32_bf16 v[6:9], v[138:141], v[66:69], v[6:9]
	v_mfma_f32_16x16x32_bf16 v[2:5], v[134:137], v[94:97], v[2:5]
	v_mfma_f32_16x16x32_bf16 v[6:9], v[142:145], v[94:97], v[6:9]
	v_mfma_f32_16x16x32_bf16 v[146:149], v[130:133], v[106:109], v[146:149]
	v_mfma_f32_16x16x32_bf16 v[150:153], v[138:141], v[106:109], v[150:153]
	v_mfma_f32_16x16x32_bf16 v[154:157], v[130:133], v[114:117], v[154:157]
	v_mfma_f32_16x16x32_bf16 v[158:161], v[138:141], v[114:117], v[158:161]
	v_mfma_f32_16x16x32_bf16 v[42:45], v[130:133], v[200:203], v[42:45]
	v_mfma_f32_16x16x32_bf16 v[26:29], v[138:141], v[200:203], v[26:29]
	v_mfma_f32_16x16x32_bf16 v[146:149], v[134:137], v[110:113], v[146:149]
	v_mfma_f32_16x16x32_bf16 v[150:153], v[142:145], v[110:113], v[150:153]
	v_mfma_f32_16x16x32_bf16 v[154:157], v[134:137], v[196:199], v[154:157]
	v_mfma_f32_16x16x32_bf16 v[158:161], v[142:145], v[196:199], v[158:161]
	v_mfma_f32_16x16x32_bf16 v[130:133], v[134:137], v[204:207], v[42:45]
	v_mfma_f32_16x16x32_bf16 v[134:137], v[142:145], v[204:207], v[26:29]
	v_mfma_f32_16x16x32_bf16 v[26:29], v[10:13], v[66:69], v[30:33]
	v_mfma_f32_16x16x32_bf16 v[138:141], v[170:173], v[94:97], v[26:29]
	v_mfma_f32_16x16x32_bf16 v[26:29], v[174:177], v[66:69], v[46:49]
	v_mfma_f32_16x16x32_bf16 v[142:145], v[180:183], v[94:97], v[26:29]
	v_mfma_f32_16x16x32_bf16 v[26:29], v[10:13], v[106:109], v[70:73]
	v_mfma_f32_16x16x32_bf16 v[214:217], v[170:173], v[110:113], v[26:29]
	v_mfma_f32_16x16x32_bf16 v[26:29], v[174:177], v[106:109], v[118:121]
	v_mfma_f32_16x16x32_bf16 v[218:221], v[180:183], v[110:113], v[26:29]
	v_mfma_f32_16x16x32_bf16 v[26:29], v[10:13], v[114:117], v[122:125]
	v_mfma_f32_16x16x32_bf16 v[10:13], v[10:13], v[200:203], v[34:37]
	v_mfma_f32_16x16x32_bf16 v[230:233], v[170:173], v[196:199], v[26:29]
	v_mfma_f32_16x16x32_bf16 v[26:29], v[174:177], v[114:117], v[126:129]
	v_mfma_f32_16x16x32_bf16 v[170:173], v[170:173], v[204:207], v[10:13]
	v_mfma_f32_16x16x32_bf16 v[10:13], v[174:177], v[200:203], v[38:41]
	v_mfma_f32_16x16x32_bf16 v[196:199], v[180:183], v[196:199], v[26:29]
	v_mfma_f32_16x16x32_bf16 v[174:177], v[180:183], v[204:207], v[10:13]
	s_barrier
	s_nop 3
	ds_read_b128 v[10:13], v17
	ds_read_b128 v[14:17], v18
	ds_read_b128 v[34:37], v19
	ds_read_b128 v[38:41], v20
	ds_read_b128 v[180:183], v21
	ds_read_b128 v[200:203], v22
	ds_read_b128 v[204:207], v23
	ds_read_b128 v[234:237], v24
	s_add_u32 s4, s38, 0x18000
	s_addc_u32 s5, s39, 0
	s_mov_b32 m0, s84
	v_lshl_add_u64 v[66:67], s[4:5], 0, v[168:169]
	ds_read_b128 v[18:21], v178 offset:32768
	ds_read_b128 v[22:25], v178 offset:33792
	ds_read_b128 v[26:29], v178 offset:34816
	ds_read_b128 v[30:33], v178 offset:35840
	ds_read_b128 v[42:45], v178 offset:36864
	ds_read_b128 v[46:49], v178 offset:37888
	ds_read_b128 v[238:241], v178 offset:38912
	ds_read_b128 v[242:245], v178 offset:39936
	global_load_lds_dwordx4 v[66:67], off
	v_lshl_add_u64 v[66:67], s[4:5], 0, v[164:165]
	s_mov_b32 m0, s85
	s_nop 0
	global_load_lds_dwordx4 v[66:67], off
	s_waitcnt vmcnt(8)
	s_waitcnt lgkmcnt(0)
	s_barrier
; #define PG8_STAGE(bufoff, gbase, voff) do { _Pragma("unroll") for (int _i = 0; _i < 2; ++_i) \
;         __builtin_amdgcn_global_load_lds((const unsigned*)((const char*)(gbase) + (voff)[_i]), (PG8_LAS unsigned*)(lds + (bufoff) + ldsw + _i * 8192), 16, 0, 0); } while (0)
; #define PG8_LDA(dst, b, h) do { _Pragma("unroll") for (int m = 0; m < 4; ++m) _Pragma("unroll") for (int k = 0; k < 2; ++k) dst[m][k] = *(const PG8_LAS bf16x8*)(lds + PG8_SA(b, h) + aoff + m * 2048 + k * 1024); } while (0)
; #define PG8_MMA(ai, bj, At, Bt) do { __builtin_amdgcn_s_setprio(1); _Pragma("unroll") for (int m = 0; m < 4; ++m) _Pragma("unroll") for (int n = 0; n < 2; ++n) _Pragma("unroll") for (int k = 0; k < 2; ++k) \
;         acc[ai][bj][m][n] = __builtin_amdgcn_mfma_f32_16x16x32_bf16(Bt[n][k], At[m][k], acc[ai][bj][m][n], 0, 0, 0); __builtin_amdgcn_s_setprio(0); } while (0)
; #define PG8_WAIT_V(n) asm volatile("s_waitcnt vmcnt(" #n ")" ::: "memory")
; #define PG8_WAIT_L(n) asm volatile("s_waitcnt lgkmcnt(" #n ")" ::: "memory")
; #define PG8_BAR __builtin_amdgcn_s_barrier()
; #define PG8_SCHED __builtin_amdgcn_sched_barrier(0)
; template <class Epi, class Sched, bool ALIGN_EPI = false, bool SP2 = false>
; __device__ __forceinline__ void gemm_phase(PG8_LAS unsigned char* lds, const Gemm g, const Sched& S, const Epi& E, const int tid) {
;     ...
;             PG8_WAIT_V(8); PG8_WAIT_L(0); PG8_BAR; PG8_MMA(0, 0, At, B0); PG8_MMA(0, 1, At, B1); PG8_BAR; PG8_SCHED;
;             PG8_LDA(At, 1, 1); PG8_STAGE(PG8_SB(1, 0), b3, voffB); PG8_STAGE(PG8_SB(1, 1), b3 + hstep, voffB); PG8_STAGE(PG8_SA(1, 0), a3, voffA);
;             PG8_WAIT_V(8); PG8_WAIT_L(0); PG8_BAR; PG8_MMA(1, 0, At, B0); PG8_MMA(1, 1, At, B1); PG8_BAR; PG8_SCHED;
;     ...
;         if constexpr (ALIGN_EPI) { if (wr == 0) PG8_BAR; }
	v_mfma_f32_16x16x32_bf16 v[66:69], v[10:13], v[18:21], v[74:77]
	v_mfma_f32_16x16x32_bf16 v[126:129], v[14:17], v[22:25], v[66:69]
	v_mfma_f32_16x16x32_bf16 v[66:69], v[34:37], v[18:21], v[78:81]
	v_mfma_f32_16x16x32_bf16 v[122:125], v[38:41], v[22:25], v[66:69]
	v_mfma_f32_16x16x32_bf16 v[66:69], v[10:13], v[26:29], v[82:85]
	v_mfma_f32_16x16x32_bf16 v[110:113], v[14:17], v[30:33], v[66:69]
	v_mfma_f32_16x16x32_bf16 v[66:69], v[34:37], v[26:29], v[86:89]
	v_mfma_f32_16x16x32_bf16 v[106:109], v[38:41], v[30:33], v[66:69]
	v_mfma_f32_16x16x32_bf16 v[66:69], v[10:13], v[42:45], v[90:93]
	v_mfma_f32_16x16x32_bf16 v[94:97], v[14:17], v[46:49], v[66:69]
	v_mfma_f32_16x16x32_bf16 v[66:69], v[34:37], v[42:45], v[222:225]
	v_mfma_f32_16x16x32_bf16 v[90:93], v[38:41], v[46:49], v[66:69]
	v_mfma_f32_16x16x32_bf16 v[66:69], v[10:13], v[238:241], v[98:101]
	v_mfma_f32_16x16x32_bf16 v[70:73], v[14:17], v[242:245], v[66:69]
	v_mfma_f32_16x16x32_bf16 v[66:69], v[34:37], v[238:241], v[102:105]
	v_mfma_f32_16x16x32_bf16 v[66:69], v[38:41], v[242:245], v[66:69]
	v_mfma_f32_16x16x32_bf16 v[74:77], v[180:183], v[18:21], v[226:229]
	v_mfma_f32_16x16x32_bf16 v[18:21], v[204:207], v[18:21], v[184:187]
	v_mfma_f32_16x16x32_bf16 v[114:117], v[234:237], v[22:25], v[18:21]
	v_mfma_f32_16x16x32_bf16 v[18:21], v[180:183], v[26:29], v[188:191]
	v_mfma_f32_16x16x32_bf16 v[102:105], v[200:203], v[30:33], v[18:21]
	v_mfma_f32_16x16x32_bf16 v[18:21], v[204:207], v[26:29], v[50:53]
	v_mfma_f32_16x16x32_bf16 v[98:101], v[234:237], v[30:33], v[18:21]
	v_mfma_f32_16x16x32_bf16 v[18:21], v[180:183], v[42:45], v[54:57]
	v_mfma_f32_16x16x32_bf16 v[86:89], v[200:203], v[46:49], v[18:21]
	v_mfma_f32_16x16x32_bf16 v[18:21], v[204:207], v[42:45], v[58:61]
	v_mfma_f32_16x16x32_bf16 v[82:85], v[234:237], v[46:49], v[18:21]
	v_mfma_f32_16x16x32_bf16 v[18:21], v[180:183], v[238:241], v[62:65]
	v_mfma_f32_16x16x32_bf16 v[54:57], v[200:203], v[242:245], v[18:21]
	v_mfma_f32_16x16x32_bf16 v[18:21], v[204:207], v[238:241], v[192:195]
	v_mfma_f32_16x16x32_bf16 v[118:121], v[200:203], v[22:25], v[74:77]
	v_mfma_f32_16x16x32_bf16 v[50:53], v[234:237], v[242:245], v[18:21]
	s_barrier
	s_mov_b32 m0, s88
	v_lshl_add_u64 v[26:27], v[208:209], 0, s[12:13]
	s_add_u32 s4, s44, 0x18080
	s_nop 0
	ds_read_b128 v[18:21], v178 offset:49152
	ds_read_b128 v[22:25], v178 offset:50176
	ds_read_b128 v[184:187], v178 offset:51200
	ds_read_b128 v[188:191], v178 offset:52224
	ds_read_b128 v[192:195], v178 offset:53248
	ds_read_b128 v[222:225], v178 offset:54272
	ds_read_b128 v[226:229], v178 offset:55296
	ds_read_b128 v[238:241], v178 offset:56320
	global_load_lds_dwordx4 v[26:27], off
	v_lshl_add_u64 v[26:27], v[210:211], 0, s[12:13]
	s_mov_b32 m0, s89
	s_addc_u32 s5, s45, 0
	global_load_lds_dwordx4 v[26:27], off
	v_lshl_add_u64 v[26:27], s[4:5], 0, v[166:167]
	s_mov_b32 m0, s28
	s_nop 0
	global_load_lds_dwordx4 v[26:27], off
	v_lshl_add_u64 v[26:27], s[4:5], 0, v[162:163]
	s_mov_b32 m0, s29
	s_nop 0
	global_load_lds_dwordx4 v[26:27], off
	v_lshl_add_u64 v[26:27], v[212:213], 0, s[12:13]
	s_mov_b32 m0, s90
	s_nop 0
	global_load_lds_dwordx4 v[26:27], off
	v_lshl_add_u64 v[26:27], v[246:247], 0, s[12:13]
	s_mov_b32 m0, s91
	s_nop 0
	global_load_lds_dwordx4 v[26:27], off
	s_waitcnt vmcnt(8)
	s_waitcnt lgkmcnt(0)
	s_barrier
	v_mfma_f32_16x16x32_bf16 v[2:5], v[10:13], v[18:21], v[2:5]
	v_mfma_f32_16x16x32_bf16 v[78:81], v[14:17], v[22:25], v[2:5]
	v_mfma_f32_16x16x32_bf16 v[2:5], v[34:37], v[18:21], v[6:9]
	v_mfma_f32_16x16x32_bf16 v[74:77], v[38:41], v[22:25], v[2:5]
	v_mfma_f32_16x16x32_bf16 v[2:5], v[10:13], v[184:187], v[146:149]
	v_mfma_f32_16x16x32_bf16 v[46:49], v[14:17], v[188:191], v[2:5]
	v_mfma_f32_16x16x32_bf16 v[2:5], v[34:37], v[184:187], v[150:153]
	v_mfma_f32_16x16x32_bf16 v[42:45], v[38:41], v[188:191], v[2:5]
	v_mfma_f32_16x16x32_bf16 v[2:5], v[10:13], v[192:195], v[154:157]
	v_mfma_f32_16x16x32_bf16 v[30:33], v[14:17], v[222:225], v[2:5]
	v_mfma_f32_16x16x32_bf16 v[2:5], v[34:37], v[192:195], v[158:161]
	v_mfma_f32_16x16x32_bf16 v[26:29], v[38:41], v[222:225], v[2:5]
	v_mfma_f32_16x16x32_bf16 v[2:5], v[10:13], v[226:229], v[130:133]
	v_mfma_f32_16x16x32_bf16 v[14:17], v[14:17], v[238:241], v[2:5]
	v_mfma_f32_16x16x32_bf16 v[2:5], v[34:37], v[226:229], v[134:137]
	v_mfma_f32_16x16x32_bf16 v[10:13], v[38:41], v[238:241], v[2:5]
	v_mfma_f32_16x16x32_bf16 v[2:5], v[180:183], v[18:21], v[138:141]
	v_mfma_f32_16x16x32_bf16 v[62:65], v[200:203], v[22:25], v[2:5]
	v_mfma_f32_16x16x32_bf16 v[2:5], v[204:207], v[18:21], v[142:145]
	v_mfma_f32_16x16x32_bf16 v[58:61], v[234:237], v[22:25], v[2:5]
	v_mfma_f32_16x16x32_bf16 v[2:5], v[180:183], v[184:187], v[214:217]
	v_mfma_f32_16x16x32_bf16 v[38:41], v[200:203], v[188:191], v[2:5]
	v_mfma_f32_16x16x32_bf16 v[2:5], v[204:207], v[184:187], v[218:221]
	v_mfma_f32_16x16x32_bf16 v[34:37], v[234:237], v[188:191], v[2:5]
	v_mfma_f32_16x16x32_bf16 v[2:5], v[180:183], v[192:195], v[230:233]
	v_mfma_f32_16x16x32_bf16 v[22:25], v[200:203], v[222:225], v[2:5]
	v_mfma_f32_16x16x32_bf16 v[2:5], v[204:207], v[192:195], v[196:199]
	v_mfma_f32_16x16x32_bf16 v[18:21], v[234:237], v[222:225], v[2:5]
	v_mfma_f32_16x16x32_bf16 v[2:5], v[180:183], v[226:229], v[170:173]
	v_mfma_f32_16x16x32_bf16 v[6:9], v[200:203], v[238:241], v[2:5]
	v_mfma_f32_16x16x32_bf16 v[2:5], v[204:207], v[226:229], v[174:177]
	v_mfma_f32_16x16x32_bf16 v[2:5], v[234:237], v[238:241], v[2:5]
	s_barrier
	s_andn2_b64 vcc, exec, s[40:41]
	s_cbranch_vccnz .LBB0_390
	s_barrier

; #define PG8_STAGE(bufoff, gbase, voff) do { _Pragma("unroll") for (int _i = 0; _i < 2; ++_i) \
;         __builtin_amdgcn_global_load_lds((const unsigned*)((const char*)(gbase) + (voff)[_i]), (PG8_LAS unsigned*)(lds + (bufoff) + ldsw + _i * 8192), 16, 0, 0); } while (0)
; #define PG8_LDA(dst, b, h) do { _Pragma("unroll") for (int m = 0; m < 4; ++m) _Pragma("unroll") for (int k = 0; k < 2; ++k) dst[m][k] = *(const PG8_LAS bf16x8*)(lds + PG8_SA(b, h) + aoff + m * 2048 + k * 1024); } while (0)
; #define PG8_LDB(dst, b, h) do { _Pragma("unroll") for (int n = 0; n < 2; ++n) _Pragma("unroll") for (int k = 0; k < 2; ++k) dst[n][k] = *(const PG8_LAS bf16x8*)(lds + PG8_SB(b, h) + boff + n * 2048 + k * 1024); } while (0)
; #define PG8_MMA(ai, bj, At, Bt) do { __builtin_amdgcn_s_setprio(1); _Pragma("unroll") for (int m = 0; m < 4; ++m) _Pragma("unroll") for (int n = 0; n < 2; ++n) _Pragma("unroll") for (int k = 0; k < 2; ++k) \
;         acc[ai][bj][m][n] = __builtin_amdgcn_mfma_f32_16x16x32_bf16(Bt[n][k], At[m][k], acc[ai][bj][m][n], 0, 0, 0); __builtin_amdgcn_s_setprio(0); } while (0)
; #define PG8_WAIT_V(n) asm volatile("s_waitcnt vmcnt(" #n ")" ::: "memory")
; #define PG8_WAIT_L(n) asm volatile("s_waitcnt lgkmcnt(" #n ")" ::: "memory")
; template <class Epi, class Sched, bool ALIGN_EPI = false, bool SP2 = false>
; __device__ __forceinline__ void gemm_phase(PG8_LAS unsigned char* lds, const Gemm g, const Sched& S, const Epi& E, const int tid) {
;     ...
;             const bool last = (t == nt - 2);
;             const char* a1 = cA + (size_t)(t + 1) * kstep;
;             const char* a2 = last ? nA : cA + (size_t)(t + 2) * kstep; const char* b2 = last ? nB : cB + (size_t)(t + 2) * kstep;
;             const char* a3 = a2 + kstep; const char* b3 = b2 + kstep;
;             if (last && has_next) S.a_ready(nxt);
;             if constexpr (SP2) {
;             PG8_LDB(B0, 0, 0); PG8_LDB(B1, 0, 1); PG8_SCHED; PG8_LDA(At, 0, 0); PG8_STAGE(PG8_SA(1, 1), a1 + hstep, voffA);
;             PG8_WAIT_V(8); PG8_WAIT_L(0); PG8_BAR; PG8_MMA(0, 0, At, B0); PG8_MMA(0, 1, At, B1); PG8_BAR; PG8_SCHED;
;             PG8_LDA(At, 0, 1); PG8_STAGE(PG8_SB(0, 0), b2, voffB); PG8_STAGE(PG8_SB(0, 1), b2 + hstep, voffB); PG8_STAGE(PG8_SA(0, 0), a2, voffA);
;             PG8_WAIT_V(8); PG8_WAIT_L(0); PG8_BAR; PG8_MMA(1, 0, At, B0); PG8_MMA(1, 1, At, B1); PG8_BAR; PG8_SCHED;
.LBB0_499:
	v_or_b32_e32 v140, 0x10000, v145
	v_add_u32_e32 v146, 0x10400, v145
	v_add_u32_e32 v150, 0x10800, v145
	v_add_u32_e32 v154, 0x10c00, v145
	v_or_b32_e32 v158, 0x14000, v145
	v_add_u32_e32 v162, 0x14400, v145
	v_add_u32_e32 v166, 0x14800, v145
	v_add_u32_e32 v170, 0x14c00, v145
	ds_read_b128 v[140:143], v140
	ds_read_b128 v[146:149], v146
	ds_read_b128 v[150:153], v150
	ds_read_b128 v[154:157], v154
	ds_read_b128 v[158:161], v158
	ds_read_b128 v[162:165], v162
	ds_read_b128 v[166:169], v166
	ds_read_b128 v[170:173], v170
	s_add_u32 s88, s86, 0xfffc0080
	s_addc_u32 s89, s87, -1
	s_cmp_eq_u32 s96, 12
	s_cselect_b32 s91, s39, s89
	s_cselect_b32 s90, s43, s88
	s_cselect_b32 s89, s41, s85
	s_cselect_b32 s88, s50, s51
	v_lshl_add_u64 v[178:179], s[86:87], 0, v[136:137]
	s_add_i32 m0, s0, 0xc000
	ds_read_b128 v[174:177], v144
	ds_read_b128 v[184:187], v144 offset:1024
	ds_read_b128 v[188:191], v144 offset:2048
	ds_read_b128 v[192:195], v144 offset:3072
	ds_read_b128 v[196:199], v144 offset:4096
	ds_read_b128 v[200:203], v144 offset:5120
	ds_read_b128 v[204:207], v144 offset:6144
	ds_read_b128 v[214:217], v144 offset:7168
	global_load_lds_dwordx4 v[178:179], off
	v_lshl_add_u64 v[178:179], s[86:87], 0, v[138:139]
	s_add_i32 m0, s0, 0xe000
	s_nop 0
	global_load_lds_dwordx4 v[178:179], off
	s_waitcnt vmcnt(8)
	s_waitcnt lgkmcnt(0)
	s_barrier
	v_mfma_f32_16x16x32_bf16 v[126:129], v[140:143], v[174:177], v[126:129]
	v_mfma_f32_16x16x32_bf16 v[126:129], v[146:149], v[184:187], v[126:129]
	v_mfma_f32_16x16x32_bf16 v[122:125], v[150:153], v[174:177], v[122:125]
	v_mfma_f32_16x16x32_bf16 v[122:125], v[154:157], v[184:187], v[122:125]
	v_mfma_f32_16x16x32_bf16 v[114:117], v[140:143], v[188:191], v[114:117]
	v_mfma_f32_16x16x32_bf16 v[114:117], v[146:149], v[192:195], v[114:117]
	v_mfma_f32_16x16x32_bf16 v[106:109], v[150:153], v[188:191], v[106:109]
	v_mfma_f32_16x16x32_bf16 v[106:109], v[154:157], v[192:195], v[106:109]
	v_mfma_f32_16x16x32_bf16 v[98:101], v[140:143], v[196:199], v[98:101]
	v_mfma_f32_16x16x32_bf16 v[98:101], v[146:149], v[200:203], v[98:101]
	v_mfma_f32_16x16x32_bf16 v[90:93], v[150:153], v[196:199], v[90:93]
	v_mfma_f32_16x16x32_bf16 v[90:93], v[154:157], v[200:203], v[90:93]
	v_mfma_f32_16x16x32_bf16 v[82:85], v[140:143], v[204:207], v[82:85]
	v_mfma_f32_16x16x32_bf16 v[82:85], v[146:149], v[214:217], v[82:85]
	v_mfma_f32_16x16x32_bf16 v[74:77], v[150:153], v[204:207], v[74:77]
	v_mfma_f32_16x16x32_bf16 v[74:77], v[154:157], v[214:217], v[74:77]
	v_mfma_f32_16x16x32_bf16 v[118:121], v[158:161], v[174:177], v[118:121]
	v_mfma_f32_16x16x32_bf16 v[118:121], v[162:165], v[184:187], v[118:121]
	v_mfma_f32_16x16x32_bf16 v[110:113], v[166:169], v[174:177], v[110:113]
	v_mfma_f32_16x16x32_bf16 v[110:113], v[170:173], v[184:187], v[110:113]
	v_mfma_f32_16x16x32_bf16 v[102:105], v[158:161], v[188:191], v[102:105]
	v_mfma_f32_16x16x32_bf16 v[102:105], v[162:165], v[192:195], v[102:105]
	v_mfma_f32_16x16x32_bf16 v[94:97], v[166:169], v[188:191], v[94:97]
	v_mfma_f32_16x16x32_bf16 v[94:97], v[170:173], v[192:195], v[94:97]
	v_mfma_f32_16x16x32_bf16 v[86:89], v[158:161], v[196:199], v[86:89]
	v_mfma_f32_16x16x32_bf16 v[86:89], v[162:165], v[200:203], v[86:89]
	v_mfma_f32_16x16x32_bf16 v[78:81], v[166:169], v[196:199], v[78:81]
	v_mfma_f32_16x16x32_bf16 v[78:81], v[170:173], v[200:203], v[78:81]
	v_mfma_f32_16x16x32_bf16 v[70:73], v[158:161], v[204:207], v[70:73]
	v_mfma_f32_16x16x32_bf16 v[70:73], v[162:165], v[214:217], v[70:73]
	v_mfma_f32_16x16x32_bf16 v[66:69], v[166:169], v[204:207], v[66:69]
	v_mfma_f32_16x16x32_bf16 v[66:69], v[170:173], v[214:217], v[66:69]
	s_barrier
	s_mov_b32 m0, s1
	v_lshl_add_u64 v[178:179], s[88:89], 0, v[0:1]
	s_add_u32 s92, s88, 0x40000
	ds_read_b128 v[174:177], v144 offset:16384
	ds_read_b128 v[184:187], v144 offset:17408
	ds_read_b128 v[188:191], v144 offset:18432
	ds_read_b128 v[192:195], v144 offset:19456
	ds_read_b128 v[196:199], v144 offset:20480
	ds_read_b128 v[200:203], v144 offset:21504
	ds_read_b128 v[204:207], v144 offset:22528
	ds_read_b128 v[214:217], v144 offset:23552
	global_load_lds_dwordx4 v[178:179], off
	v_lshl_add_u64 v[180:181], s[88:89], 0, v[134:135]
	s_mov_b32 m0, s2
	s_addc_u32 s93, s89, 0
	global_load_lds_dwordx4 v[180:181], off
	v_lshl_add_u64 v[182:183], s[92:93], 0, v[0:1]
	s_mov_b32 m0, s4
	v_lshl_add_u64 v[218:219], s[90:91], 0, v[132:133]
	global_load_lds_dwordx4 v[182:183], off
	v_lshl_add_u64 v[182:183], s[92:93], 0, v[134:135]
	s_mov_b32 m0, s5
	s_nop 0
	global_load_lds_dwordx4 v[182:183], off
	v_lshl_add_u64 v[182:183], s[90:91], 0, v[130:131]
	s_mov_b32 m0, s0
	s_nop 0
	global_load_lds_dwordx4 v[182:183], off
	s_mov_b32 m0, s6
	s_nop 0
	global_load_lds_dwordx4 v[218:219], off
	s_waitcnt vmcnt(8)
	s_waitcnt lgkmcnt(0)
	s_barrier
; #define PG8_STAGE(bufoff, gbase, voff) do { _Pragma("unroll") for (int _i = 0; _i < 2; ++_i) \
;         __builtin_amdgcn_global_load_lds((const unsigned*)((const char*)(gbase) + (voff)[_i]), (PG8_LAS unsigned*)(lds + (bufoff) + ldsw + _i * 8192), 16, 0, 0); } while (0)
; #define PG8_LDA(dst, b, h) do { _Pragma("unroll") for (int m = 0; m < 4; ++m) _Pragma("unroll") for (int k = 0; k < 2; ++k) dst[m][k] = *(const PG8_LAS bf16x8*)(lds + PG8_SA(b, h) + aoff + m * 2048 + k * 1024); } while (0)
; #define PG8_LDB(dst, b, h) do { _Pragma("unroll") for (int n = 0; n < 2; ++n) _Pragma("unroll") for (int k = 0; k < 2; ++k) dst[n][k] = *(const PG8_LAS bf16x8*)(lds + PG8_SB(b, h) + boff + n * 2048 + k * 1024); } while (0)
; #define PG8_MMA(ai, bj, At, Bt) do { __builtin_amdgcn_s_setprio(1); _Pragma("unroll") for (int m = 0; m < 4; ++m) _Pragma("unroll") for (int n = 0; n < 2; ++n) _Pragma("unroll") for (int k = 0; k < 2; ++k) \
;         acc[ai][bj][m][n] = __builtin_amdgcn_mfma_f32_16x16x32_bf16(Bt[n][k], At[m][k], acc[ai][bj][m][n], 0, 0, 0); __builtin_amdgcn_s_setprio(0); } while (0)
; #define PG8_WAIT_V(n) asm volatile("s_waitcnt vmcnt(" #n ")" ::: "memory")
; #define PG8_WAIT_L(n) asm volatile("s_waitcnt lgkmcnt(" #n ")" ::: "memory")
; #define PG8_BAR __builtin_amdgcn_s_barrier()
; #define PG8_SCHED __builtin_amdgcn_sched_barrier(0)
; template <class Epi, class Sched, bool ALIGN_EPI = false, bool SP2 = false>
; __device__ __forceinline__ void gemm_phase(PG8_LAS unsigned char* lds, const Gemm g, const Sched& S, const Epi& E, const int tid) {
;     ...
;             PG8_WAIT_V(8); PG8_WAIT_L(0); PG8_BAR; PG8_MMA(1, 0, At, B0); PG8_MMA(1, 1, At, B1); PG8_BAR; PG8_SCHED;
;             PG8_LDB(B0, 1, 0); PG8_LDB(B1, 1, 1); PG8_SCHED; PG8_LDA(At, 1, 0); PG8_STAGE(PG8_SA(0, 1), a2 + hstep, voffA);
;             PG8_WAIT_V(8); PG8_WAIT_L(0); PG8_BAR; PG8_MMA(0, 0, At, B0); PG8_MMA(0, 1, At, B1); PG8_BAR; PG8_SCHED;
	v_mfma_f32_16x16x32_bf16 v[62:65], v[140:143], v[174:177], v[62:65]
	v_mfma_f32_16x16x32_bf16 v[62:65], v[146:149], v[184:187], v[62:65]
	v_mfma_f32_16x16x32_bf16 v[58:61], v[150:153], v[174:177], v[58:61]
	v_mfma_f32_16x16x32_bf16 v[58:61], v[154:157], v[184:187], v[58:61]
	v_mfma_f32_16x16x32_bf16 v[50:53], v[140:143], v[188:191], v[50:53]
	v_mfma_f32_16x16x32_bf16 v[50:53], v[146:149], v[192:195], v[50:53]
	v_mfma_f32_16x16x32_bf16 v[42:45], v[150:153], v[188:191], v[42:45]
	v_mfma_f32_16x16x32_bf16 v[42:45], v[154:157], v[192:195], v[42:45]
	v_mfma_f32_16x16x32_bf16 v[34:37], v[140:143], v[196:199], v[34:37]
	v_mfma_f32_16x16x32_bf16 v[34:37], v[146:149], v[200:203], v[34:37]
	v_mfma_f32_16x16x32_bf16 v[26:29], v[150:153], v[196:199], v[26:29]
	v_mfma_f32_16x16x32_bf16 v[26:29], v[154:157], v[200:203], v[26:29]
	v_mfma_f32_16x16x32_bf16 v[18:21], v[140:143], v[204:207], v[18:21]
	v_mfma_f32_16x16x32_bf16 v[18:21], v[146:149], v[214:217], v[18:21]
	v_mfma_f32_16x16x32_bf16 v[10:13], v[150:153], v[204:207], v[10:13]
	v_mfma_f32_16x16x32_bf16 v[10:13], v[154:157], v[214:217], v[10:13]
	v_mfma_f32_16x16x32_bf16 v[54:57], v[158:161], v[174:177], v[54:57]
	v_mfma_f32_16x16x32_bf16 v[54:57], v[162:165], v[184:187], v[54:57]
	v_mfma_f32_16x16x32_bf16 v[46:49], v[166:169], v[174:177], v[46:49]
	v_mfma_f32_16x16x32_bf16 v[46:49], v[170:173], v[184:187], v[46:49]
	v_mfma_f32_16x16x32_bf16 v[38:41], v[158:161], v[188:191], v[38:41]
	v_mfma_f32_16x16x32_bf16 v[38:41], v[162:165], v[192:195], v[38:41]
	v_mfma_f32_16x16x32_bf16 v[30:33], v[166:169], v[188:191], v[30:33]
	v_mfma_f32_16x16x32_bf16 v[30:33], v[170:173], v[192:195], v[30:33]
	v_mfma_f32_16x16x32_bf16 v[22:25], v[158:161], v[196:199], v[22:25]
	v_mfma_f32_16x16x32_bf16 v[22:25], v[162:165], v[200:203], v[22:25]
	v_mfma_f32_16x16x32_bf16 v[14:17], v[166:169], v[196:199], v[14:17]
	v_mfma_f32_16x16x32_bf16 v[14:17], v[170:173], v[200:203], v[14:17]
	v_mfma_f32_16x16x32_bf16 v[6:9], v[158:161], v[204:207], v[6:9]
	v_mfma_f32_16x16x32_bf16 v[6:9], v[162:165], v[214:217], v[6:9]
	v_mfma_f32_16x16x32_bf16 v[2:5], v[166:169], v[204:207], v[2:5]
	v_mfma_f32_16x16x32_bf16 v[2:5], v[170:173], v[214:217], v[2:5]
	s_barrier
	v_or_b32_e32 v140, 0x18000, v145
	v_add_u32_e32 v146, 0x18400, v145
	v_add_u32_e32 v150, 0x18800, v145
	v_add_u32_e32 v154, 0x18c00, v145
	v_or_b32_e32 v158, 0x1c000, v145
	v_add_u32_e32 v162, 0x1c400, v145
	v_add_u32_e32 v166, 0x1c800, v145
	v_add_u32_e32 v170, 0x1cc00, v145
	ds_read_b128 v[140:143], v140
	ds_read_b128 v[146:149], v146
	ds_read_b128 v[150:153], v150
	ds_read_b128 v[154:157], v154
	ds_read_b128 v[158:161], v158
	ds_read_b128 v[162:165], v162
	ds_read_b128 v[166:169], v166
	ds_read_b128 v[170:173], v170
	s_add_u32 s90, s90, 0x40000
	s_addc_u32 s91, s91, 0
	s_mov_b32 m0, s8
	v_lshl_add_u64 v[220:221], s[90:91], 0, v[130:131]
	ds_read_b128 v[174:177], v144 offset:32768
	ds_read_b128 v[184:187], v144 offset:33792
	ds_read_b128 v[188:191], v144 offset:34816
	ds_read_b128 v[192:195], v144 offset:35840
	ds_read_b128 v[196:199], v144 offset:36864
	ds_read_b128 v[200:203], v144 offset:37888
	ds_read_b128 v[204:207], v144 offset:38912
	ds_read_b128 v[214:217], v144 offset:39936
	global_load_lds_dwordx4 v[220:221], off
	v_lshl_add_u64 v[220:221], s[90:91], 0, v[132:133]
	s_mov_b32 m0, s9
	s_nop 0
	global_load_lds_dwordx4 v[220:221], off
	s_waitcnt vmcnt(8)
	s_waitcnt lgkmcnt(0)
	s_barrier
	v_mfma_f32_16x16x32_bf16 v[126:129], v[140:143], v[174:177], v[126:129]
	v_mfma_f32_16x16x32_bf16 v[126:129], v[146:149], v[184:187], v[126:129]
	v_mfma_f32_16x16x32_bf16 v[122:125], v[150:153], v[174:177], v[122:125]
	v_mfma_f32_16x16x32_bf16 v[122:125], v[154:157], v[184:187], v[122:125]
	v_mfma_f32_16x16x32_bf16 v[114:117], v[140:143], v[188:191], v[114:117]
	v_mfma_f32_16x16x32_bf16 v[114:117], v[146:149], v[192:195], v[114:117]
	v_mfma_f32_16x16x32_bf16 v[106:109], v[150:153], v[188:191], v[106:109]
	v_mfma_f32_16x16x32_bf16 v[106:109], v[154:157], v[192:195], v[106:109]
	v_mfma_f32_16x16x32_bf16 v[98:101], v[140:143], v[196:199], v[98:101]
	v_mfma_f32_16x16x32_bf16 v[98:101], v[146:149], v[200:203], v[98:101]
	v_mfma_f32_16x16x32_bf16 v[90:93], v[150:153], v[196:199], v[90:93]
	v_mfma_f32_16x16x32_bf16 v[90:93], v[154:157], v[200:203], v[90:93]
	v_mfma_f32_16x16x32_bf16 v[82:85], v[140:143], v[204:207], v[82:85]
	v_mfma_f32_16x16x32_bf16 v[82:85], v[146:149], v[214:217], v[82:85]
	v_mfma_f32_16x16x32_bf16 v[74:77], v[150:153], v[204:207], v[74:77]
	v_mfma_f32_16x16x32_bf16 v[74:77], v[154:157], v[214:217], v[74:77]
	v_mfma_f32_16x16x32_bf16 v[118:121], v[158:161], v[174:177], v[118:121]
	v_mfma_f32_16x16x32_bf16 v[118:121], v[162:165], v[184:187], v[118:121]
	v_mfma_f32_16x16x32_bf16 v[110:113], v[166:169], v[174:177], v[110:113]
	v_mfma_f32_16x16x32_bf16 v[110:113], v[170:173], v[184:187], v[110:113]
	v_mfma_f32_16x16x32_bf16 v[102:105], v[158:161], v[188:191], v[102:105]
	v_mfma_f32_16x16x32_bf16 v[102:105], v[162:165], v[192:195], v[102:105]
	v_mfma_f32_16x16x32_bf16 v[94:97], v[166:169], v[188:191], v[94:97]
	v_mfma_f32_16x16x32_bf16 v[94:97], v[170:173], v[192:195], v[94:97]
	v_mfma_f32_16x16x32_bf16 v[86:89], v[158:161], v[196:199], v[86:89]
	v_mfma_f32_16x16x32_bf16 v[86:89], v[162:165], v[200:203], v[86:89]
	v_mfma_f32_16x16x32_bf16 v[78:81], v[166:169], v[196:199], v[78:81]
	v_mfma_f32_16x16x32_bf16 v[78:81], v[170:173], v[200:203], v[78:81]
	v_mfma_f32_16x16x32_bf16 v[70:73], v[158:161], v[204:207], v[70:73]
	v_mfma_f32_16x16x32_bf16 v[70:73], v[162:165], v[214:217], v[70:73]
	v_mfma_f32_16x16x32_bf16 v[66:69], v[166:169], v[204:207], v[66:69]
	v_mfma_f32_16x16x32_bf16 v[66:69], v[170:173], v[214:217], v[66:69]
	s_barrier
; #define PG8_STAGE(bufoff, gbase, voff) do { _Pragma("unroll") for (int _i = 0; _i < 2; ++_i) \
;         __builtin_amdgcn_global_load_lds((const unsigned*)((const char*)(gbase) + (voff)[_i]), (PG8_LAS unsigned*)(lds + (bufoff) + ldsw + _i * 8192), 16, 0, 0); } while (0)
; #define PG8_LDA(dst, b, h) do { _Pragma("unroll") for (int m = 0; m < 4; ++m) _Pragma("unroll") for (int k = 0; k < 2; ++k) dst[m][k] = *(const PG8_LAS bf16x8*)(lds + PG8_SA(b, h) + aoff + m * 2048 + k * 1024); } while (0)
; #define PG8_MMA(ai, bj, At, Bt) do { __builtin_amdgcn_s_setprio(1); _Pragma("unroll") for (int m = 0; m < 4; ++m) _Pragma("unroll") for (int n = 0; n < 2; ++n) _Pragma("unroll") for (int k = 0; k < 2; ++k) \
;         acc[ai][bj][m][n] = __builtin_amdgcn_mfma_f32_16x16x32_bf16(Bt[n][k], At[m][k], acc[ai][bj][m][n], 0, 0, 0); __builtin_amdgcn_s_setprio(0); } while (0)
; #define PG8_WAIT_V(n) asm volatile("s_waitcnt vmcnt(" #n ")" ::: "memory")
; #define PG8_WAIT_L(n) asm volatile("s_waitcnt lgkmcnt(" #n ")" ::: "memory")
; #define PG8_BAR __builtin_amdgcn_s_barrier()
; #define PG8_SCHED __builtin_amdgcn_sched_barrier(0)
; template <class Epi, class Sched, bool ALIGN_EPI = false, bool SP2 = false>
; __device__ __forceinline__ void gemm_phase(PG8_LAS unsigned char* lds, const Gemm g, const Sched& S, const Epi& E, const int tid) {
;     ...
;         for (int t = 0; t < nt; t += 2) {
;     ...
;             PG8_LDA(At, 1, 1); PG8_STAGE(PG8_SB(1, 0), b3, voffB); PG8_STAGE(PG8_SB(1, 1), b3 + hstep, voffB); PG8_STAGE(PG8_SA(1, 0), a3, voffA);
;             PG8_WAIT_V(8); PG8_WAIT_L(0); PG8_BAR; PG8_MMA(1, 0, At, B0); PG8_MMA(1, 1, At, B1); PG8_BAR; PG8_SCHED;
	s_mov_b32 m0, s17
	v_lshl_add_u64 v[178:179], v[178:179], 0, s[12:13]
	s_add_u32 s88, s88, 0x40080
	ds_read_b128 v[174:177], v144 offset:49152
	ds_read_b128 v[184:187], v144 offset:50176
	ds_read_b128 v[188:191], v144 offset:51200
	ds_read_b128 v[192:195], v144 offset:52224
	ds_read_b128 v[196:199], v144 offset:53248
	ds_read_b128 v[200:203], v144 offset:54272
	ds_read_b128 v[204:207], v144 offset:55296
	ds_read_b128 v[214:217], v144 offset:56320
	global_load_lds_dwordx4 v[178:179], off
	v_lshl_add_u64 v[178:179], v[180:181], 0, s[12:13]
	s_mov_b32 m0, s20
	s_addc_u32 s89, s89, 0
	global_load_lds_dwordx4 v[178:179], off
	v_lshl_add_u64 v[178:179], s[88:89], 0, v[0:1]
	s_mov_b32 m0, s26
	s_nop 0
	global_load_lds_dwordx4 v[178:179], off
	v_lshl_add_u64 v[178:179], s[88:89], 0, v[134:135]
	s_mov_b32 m0, s27
	s_nop 0
	global_load_lds_dwordx4 v[178:179], off
	v_lshl_add_u64 v[178:179], v[182:183], 0, s[12:13]
	s_mov_b32 m0, s21
	s_nop 0
	global_load_lds_dwordx4 v[178:179], off
	v_lshl_add_u64 v[178:179], v[218:219], 0, s[12:13]
	s_mov_b32 m0, s24
	s_nop 0
	global_load_lds_dwordx4 v[178:179], off
	s_waitcnt vmcnt(8)
	s_waitcnt lgkmcnt(0)
	s_barrier
	v_mfma_f32_16x16x32_bf16 v[62:65], v[140:143], v[174:177], v[62:65]
	v_mfma_f32_16x16x32_bf16 v[62:65], v[146:149], v[184:187], v[62:65]
	v_mfma_f32_16x16x32_bf16 v[58:61], v[150:153], v[174:177], v[58:61]
	v_mfma_f32_16x16x32_bf16 v[58:61], v[154:157], v[184:187], v[58:61]
	v_mfma_f32_16x16x32_bf16 v[50:53], v[140:143], v[188:191], v[50:53]
	v_mfma_f32_16x16x32_bf16 v[50:53], v[146:149], v[192:195], v[50:53]
	v_mfma_f32_16x16x32_bf16 v[42:45], v[150:153], v[188:191], v[42:45]
	v_mfma_f32_16x16x32_bf16 v[42:45], v[154:157], v[192:195], v[42:45]
	v_mfma_f32_16x16x32_bf16 v[34:37], v[140:143], v[196:199], v[34:37]
	v_mfma_f32_16x16x32_bf16 v[34:37], v[146:149], v[200:203], v[34:37]
	v_mfma_f32_16x16x32_bf16 v[26:29], v[150:153], v[196:199], v[26:29]
	v_mfma_f32_16x16x32_bf16 v[26:29], v[154:157], v[200:203], v[26:29]
	v_mfma_f32_16x16x32_bf16 v[18:21], v[140:143], v[204:207], v[18:21]
	v_mfma_f32_16x16x32_bf16 v[18:21], v[146:149], v[214:217], v[18:21]
	v_mfma_f32_16x16x32_bf16 v[10:13], v[150:153], v[204:207], v[10:13]
	v_mfma_f32_16x16x32_bf16 v[10:13], v[154:157], v[214:217], v[10:13]
	v_mfma_f32_16x16x32_bf16 v[54:57], v[158:161], v[174:177], v[54:57]
	v_mfma_f32_16x16x32_bf16 v[54:57], v[162:165], v[184:187], v[54:57]
	v_mfma_f32_16x16x32_bf16 v[46:49], v[166:169], v[174:177], v[46:49]
	v_mfma_f32_16x16x32_bf16 v[46:49], v[170:173], v[184:187], v[46:49]
	v_mfma_f32_16x16x32_bf16 v[38:41], v[158:161], v[188:191], v[38:41]
	v_mfma_f32_16x16x32_bf16 v[38:41], v[162:165], v[192:195], v[38:41]
	v_mfma_f32_16x16x32_bf16 v[30:33], v[166:169], v[188:191], v[30:33]
	v_mfma_f32_16x16x32_bf16 v[30:33], v[170:173], v[192:195], v[30:33]
	v_mfma_f32_16x16x32_bf16 v[22:25], v[158:161], v[196:199], v[22:25]
	v_mfma_f32_16x16x32_bf16 v[22:25], v[162:165], v[200:203], v[22:25]
	v_mfma_f32_16x16x32_bf16 v[14:17], v[166:169], v[196:199], v[14:17]
	v_mfma_f32_16x16x32_bf16 v[14:17], v[170:173], v[200:203], v[14:17]
	v_mfma_f32_16x16x32_bf16 v[6:9], v[158:161], v[204:207], v[6:9]
	v_mfma_f32_16x16x32_bf16 v[6:9], v[162:165], v[214:217], v[6:9]
	v_mfma_f32_16x16x32_bf16 v[2:5], v[166:169], v[204:207], v[2:5]
	v_mfma_f32_16x16x32_bf16 v[2:5], v[170:173], v[214:217], v[2:5]
	s_barrier
	s_add_i32 s96, s96, 2
	s_add_u32 s86, s86, 0x100
	s_addc_u32 s87, s87, 0
	s_add_u32 s51, s51, 0x100
	s_addc_u32 s85, s85, 0
	s_cmp_gt_u32 s96, 13
	s_cbranch_scc0 .LBB0_499
	s_and_b64 vcc, exec, s[14:15]
	s_cbranch_vccz .LBB0_502
	s_barrier

; #define PG8_STAGE(bufoff, gbase, voff) do { _Pragma("unroll") for (int _i = 0; _i < 2; ++_i) \
;         __builtin_amdgcn_global_load_lds((const unsigned*)((const char*)(gbase) + (voff)[_i]), (PG8_LAS unsigned*)(lds + (bufoff) + ldsw + _i * 8192), 16, 0, 0); } while (0)
; #define PG8_LDA(dst, b, h) do { _Pragma("unroll") for (int m = 0; m < 4; ++m) _Pragma("unroll") for (int k = 0; k < 2; ++k) dst[m][k] = *(const PG8_LAS bf16x8*)(lds + PG8_SA(b, h) + aoff + m * 2048 + k * 1024); } while (0)
; #define PG8_LDB(dst, b, h) do { _Pragma("unroll") for (int n = 0; n < 2; ++n) _Pragma("unroll") for (int k = 0; k < 2; ++k) dst[n][k] = *(const PG8_LAS bf16x8*)(lds + PG8_SB(b, h) + boff + n * 2048 + k * 1024); } while (0)
; #define PG8_MMA(ai, bj, At, Bt) do { __builtin_amdgcn_s_setprio(1); _Pragma("unroll") for (int m = 0; m < 4; ++m) _Pragma("unroll") for (int n = 0; n < 2; ++n) _Pragma("unroll") for (int k = 0; k < 2; ++k) \
;         acc[ai][bj][m][n] = __builtin_amdgcn_mfma_f32_16x16x32_bf16(Bt[n][k], At[m][k], acc[ai][bj][m][n], 0, 0, 0); __builtin_amdgcn_s_setprio(0); } while (0)
; #define PG8_WAIT_V(n) asm volatile("s_waitcnt vmcnt(" #n ")" ::: "memory")
; #define PG8_WAIT_L(n) asm volatile("s_waitcnt lgkmcnt(" #n ")" ::: "memory")
; template <class Epi, class Sched, bool ALIGN_EPI = false, bool SP2 = false>
; __device__ __forceinline__ void gemm_phase(PG8_LAS unsigned char* lds, const Gemm g, const Sched& S, const Epi& E, const int tid) {
;     ...
;             const bool last = (t == nt - 2);
;             const char* a1 = cA + (size_t)(t + 1) * kstep;
;             const char* a2 = last ? nA : cA + (size_t)(t + 2) * kstep; const char* b2 = last ? nB : cB + (size_t)(t + 2) * kstep;
;             const char* a3 = a2 + kstep; const char* b3 = b2 + kstep;
;             if (last && has_next) S.a_ready(nxt);
;             if constexpr (SP2) {
;             PG8_LDB(B0, 0, 0); PG8_LDB(B1, 0, 1); PG8_SCHED; PG8_LDA(At, 0, 0); PG8_STAGE(PG8_SA(1, 1), a1 + hstep, voffA);
;             PG8_WAIT_V(8); PG8_WAIT_L(0); PG8_BAR; PG8_MMA(0, 0, At, B0); PG8_MMA(0, 1, At, B1); PG8_BAR; PG8_SCHED;
;             PG8_LDA(At, 0, 1); PG8_STAGE(PG8_SB(0, 0), b2, voffB); PG8_STAGE(PG8_SB(0, 1), b2 + hstep, voffB); PG8_STAGE(PG8_SA(0, 0), a2, voffA);
;             PG8_WAIT_V(8); PG8_WAIT_L(0); PG8_BAR; PG8_MMA(1, 0, At, B0); PG8_MMA(1, 1, At, B1); PG8_BAR; PG8_SCHED;
.LBB0_684:
	v_or_b32_e32 v130, 0x10000, v177
	v_add_u32_e32 v134, 0x10400, v177
	v_add_u32_e32 v138, 0x10800, v177
	v_add_u32_e32 v142, 0x10c00, v177
	v_or_b32_e32 v146, 0x14000, v177
	v_add_u32_e32 v157, 0x14400, v177
	ds_read_b128 v[130:133], v130
	ds_read_b128 v[134:137], v134
	ds_read_b128 v[138:141], v138
	ds_read_b128 v[142:145], v142
	ds_read_b128 v[146:149], v146
	ds_read_b128 v[164:167], v157
	v_add_u32_e32 v157, 0x14800, v177
	v_add_u32_e32 v172, 0x14c00, v177
	s_add_i32 s92, s88, 2
	ds_read_b128 v[168:171], v157
	ds_read_b128 v[172:175], v172
	s_add_u32 s93, s86, 0x80
	s_addc_u32 s89, s87, 0
	s_cmp_eq_u32 s20, s88
	s_cselect_b32 s88, s38, s93
	s_cselect_b32 s89, s39, s89
	s_cselect_b32 s95, s85, vcc_hi
	s_cselect_b32 s94, s84, vcc_lo
	v_lshl_add_u64 v[178:179], s[86:87], 0, v[160:161]
	s_add_i32 m0, s17, 0xc000
	ds_read_b128 v[184:187], v176
	ds_read_b128 v[188:191], v176 offset:1024
	ds_read_b128 v[192:195], v176 offset:2048
	ds_read_b128 v[196:199], v176 offset:3072
	ds_read_b128 v[200:203], v176 offset:4096
	ds_read_b128 v[204:207], v176 offset:5120
	ds_read_b128 v[214:217], v176 offset:6144
	ds_read_b128 v[218:221], v176 offset:7168
	global_load_lds_dwordx4 v[178:179], off
	v_lshl_add_u64 v[178:179], s[86:87], 0, v[162:163]
	s_add_i32 m0, s17, 0xe000
	s_nop 0
	global_load_lds_dwordx4 v[178:179], off
	s_waitcnt vmcnt(8)
	s_waitcnt lgkmcnt(0)
	s_barrier
	v_mfma_f32_16x16x32_bf16 v[126:129], v[130:133], v[184:187], v[126:129]
	v_mfma_f32_16x16x32_bf16 v[126:129], v[134:137], v[188:191], v[126:129]
	v_mfma_f32_16x16x32_bf16 v[122:125], v[138:141], v[184:187], v[122:125]
	v_mfma_f32_16x16x32_bf16 v[122:125], v[142:145], v[188:191], v[122:125]
	v_mfma_f32_16x16x32_bf16 v[110:113], v[130:133], v[192:195], v[110:113]
	v_mfma_f32_16x16x32_bf16 v[110:113], v[134:137], v[196:199], v[110:113]
	v_mfma_f32_16x16x32_bf16 v[106:109], v[138:141], v[192:195], v[106:109]
	v_mfma_f32_16x16x32_bf16 v[106:109], v[142:145], v[196:199], v[106:109]
	v_mfma_f32_16x16x32_bf16 v[94:97], v[130:133], v[200:203], v[94:97]
	v_mfma_f32_16x16x32_bf16 v[94:97], v[134:137], v[204:207], v[94:97]
	v_mfma_f32_16x16x32_bf16 v[90:93], v[138:141], v[200:203], v[90:93]
	v_mfma_f32_16x16x32_bf16 v[90:93], v[142:145], v[204:207], v[90:93]
	v_mfma_f32_16x16x32_bf16 v[78:81], v[130:133], v[214:217], v[78:81]
	v_mfma_f32_16x16x32_bf16 v[78:81], v[134:137], v[218:221], v[78:81]
	v_mfma_f32_16x16x32_bf16 v[74:77], v[138:141], v[214:217], v[74:77]
	v_mfma_f32_16x16x32_bf16 v[74:77], v[142:145], v[218:221], v[74:77]
	v_mfma_f32_16x16x32_bf16 v[118:121], v[146:149], v[184:187], v[118:121]
	v_mfma_f32_16x16x32_bf16 v[118:121], v[164:167], v[188:191], v[118:121]
	v_mfma_f32_16x16x32_bf16 v[114:117], v[168:171], v[184:187], v[114:117]
	v_mfma_f32_16x16x32_bf16 v[114:117], v[172:175], v[188:191], v[114:117]
	v_mfma_f32_16x16x32_bf16 v[102:105], v[146:149], v[192:195], v[102:105]
	v_mfma_f32_16x16x32_bf16 v[102:105], v[164:167], v[196:199], v[102:105]
	v_mfma_f32_16x16x32_bf16 v[98:101], v[168:171], v[192:195], v[98:101]
	v_mfma_f32_16x16x32_bf16 v[98:101], v[172:175], v[196:199], v[98:101]
	v_mfma_f32_16x16x32_bf16 v[86:89], v[146:149], v[200:203], v[86:89]
	v_mfma_f32_16x16x32_bf16 v[86:89], v[164:167], v[204:207], v[86:89]
	v_mfma_f32_16x16x32_bf16 v[82:85], v[168:171], v[200:203], v[82:85]
	v_mfma_f32_16x16x32_bf16 v[82:85], v[172:175], v[204:207], v[82:85]
	v_mfma_f32_16x16x32_bf16 v[70:73], v[146:149], v[214:217], v[70:73]
	v_mfma_f32_16x16x32_bf16 v[70:73], v[164:167], v[218:221], v[70:73]
	v_mfma_f32_16x16x32_bf16 v[66:69], v[168:171], v[214:217], v[66:69]
	v_mfma_f32_16x16x32_bf16 v[66:69], v[172:175], v[218:221], v[66:69]
	s_barrier
	s_mov_b32 m0, s26
	v_lshl_add_u64 v[178:179], s[94:95], 0, v[0:1]
	v_lshl_add_u64 v[180:181], s[94:95], 0, v[150:151]
	s_add_u32 s94, s94, s40
	ds_read_b128 v[184:187], v176 offset:16384
	ds_read_b128 v[188:191], v176 offset:17408
	ds_read_b128 v[192:195], v176 offset:18432
	ds_read_b128 v[196:199], v176 offset:19456
	ds_read_b128 v[200:203], v176 offset:20480
	ds_read_b128 v[204:207], v176 offset:21504
	ds_read_b128 v[214:217], v176 offset:22528
	ds_read_b128 v[218:221], v176 offset:23552
	global_load_lds_dwordx4 v[178:179], off
	s_mov_b32 m0, s27
	s_addc_u32 s95, s95, 0
	global_load_lds_dwordx4 v[180:181], off
	v_lshl_add_u64 v[182:183], s[94:95], 0, v[0:1]
	s_mov_b32 m0, s34
	v_lshl_add_u64 v[222:223], s[94:95], 0, v[150:151]
	global_load_lds_dwordx4 v[182:183], off
	s_mov_b32 m0, s35
	v_lshl_add_u64 v[224:225], s[88:89], 0, v[154:155]
	global_load_lds_dwordx4 v[222:223], off
	s_mov_b32 m0, s17
	v_lshl_add_u64 v[226:227], s[88:89], 0, v[152:153]
	global_load_lds_dwordx4 v[224:225], off
	s_mov_b32 m0, s50
	s_nop 0
	global_load_lds_dwordx4 v[226:227], off
	s_waitcnt vmcnt(8)
	s_waitcnt lgkmcnt(0)
	s_barrier
; #define PG8_STAGE(bufoff, gbase, voff) do { _Pragma("unroll") for (int _i = 0; _i < 2; ++_i) \
;         __builtin_amdgcn_global_load_lds((const unsigned*)((const char*)(gbase) + (voff)[_i]), (PG8_LAS unsigned*)(lds + (bufoff) + ldsw + _i * 8192), 16, 0, 0); } while (0)
; #define PG8_LDA(dst, b, h) do { _Pragma("unroll") for (int m = 0; m < 4; ++m) _Pragma("unroll") for (int k = 0; k < 2; ++k) dst[m][k] = *(const PG8_LAS bf16x8*)(lds + PG8_SA(b, h) + aoff + m * 2048 + k * 1024); } while (0)
; #define PG8_LDB(dst, b, h) do { _Pragma("unroll") for (int n = 0; n < 2; ++n) _Pragma("unroll") for (int k = 0; k < 2; ++k) dst[n][k] = *(const PG8_LAS bf16x8*)(lds + PG8_SB(b, h) + boff + n * 2048 + k * 1024); } while (0)
; #define PG8_MMA(ai, bj, At, Bt) do { __builtin_amdgcn_s_setprio(1); _Pragma("unroll") for (int m = 0; m < 4; ++m) _Pragma("unroll") for (int n = 0; n < 2; ++n) _Pragma("unroll") for (int k = 0; k < 2; ++k) \
;         acc[ai][bj][m][n] = __builtin_amdgcn_mfma_f32_16x16x32_bf16(Bt[n][k], At[m][k], acc[ai][bj][m][n], 0, 0, 0); __builtin_amdgcn_s_setprio(0); } while (0)
; #define PG8_WAIT_V(n) asm volatile("s_waitcnt vmcnt(" #n ")" ::: "memory")
; #define PG8_WAIT_L(n) asm volatile("s_waitcnt lgkmcnt(" #n ")" ::: "memory")
; #define PG8_BAR __builtin_amdgcn_s_barrier()
; #define PG8_SCHED __builtin_amdgcn_sched_barrier(0)
; template <class Epi, class Sched, bool ALIGN_EPI = false, bool SP2 = false>
; __device__ __forceinline__ void gemm_phase(PG8_LAS unsigned char* lds, const Gemm g, const Sched& S, const Epi& E, const int tid) {
;     ...
;             PG8_WAIT_V(8); PG8_WAIT_L(0); PG8_BAR; PG8_MMA(1, 0, At, B0); PG8_MMA(1, 1, At, B1); PG8_BAR; PG8_SCHED;
;             PG8_LDB(B0, 1, 0); PG8_LDB(B1, 1, 1); PG8_SCHED; PG8_LDA(At, 1, 0); PG8_STAGE(PG8_SA(0, 1), a2 + hstep, voffA);
;             PG8_WAIT_V(8); PG8_WAIT_L(0); PG8_BAR; PG8_MMA(0, 0, At, B0); PG8_MMA(0, 1, At, B1); PG8_BAR; PG8_SCHED;
	v_mfma_f32_16x16x32_bf16 v[62:65], v[130:133], v[184:187], v[62:65]
	v_mfma_f32_16x16x32_bf16 v[62:65], v[134:137], v[188:191], v[62:65]
	v_mfma_f32_16x16x32_bf16 v[58:61], v[138:141], v[184:187], v[58:61]
	v_mfma_f32_16x16x32_bf16 v[58:61], v[142:145], v[188:191], v[58:61]
	v_mfma_f32_16x16x32_bf16 v[46:49], v[130:133], v[192:195], v[46:49]
	v_mfma_f32_16x16x32_bf16 v[46:49], v[134:137], v[196:199], v[46:49]
	v_mfma_f32_16x16x32_bf16 v[42:45], v[138:141], v[192:195], v[42:45]
	v_mfma_f32_16x16x32_bf16 v[42:45], v[142:145], v[196:199], v[42:45]
	v_mfma_f32_16x16x32_bf16 v[30:33], v[130:133], v[200:203], v[30:33]
	v_mfma_f32_16x16x32_bf16 v[30:33], v[134:137], v[204:207], v[30:33]
	v_mfma_f32_16x16x32_bf16 v[26:29], v[138:141], v[200:203], v[26:29]
	v_mfma_f32_16x16x32_bf16 v[26:29], v[142:145], v[204:207], v[26:29]
	v_mfma_f32_16x16x32_bf16 v[14:17], v[130:133], v[214:217], v[14:17]
	v_mfma_f32_16x16x32_bf16 v[14:17], v[134:137], v[218:221], v[14:17]
	v_mfma_f32_16x16x32_bf16 v[10:13], v[138:141], v[214:217], v[10:13]
	v_mfma_f32_16x16x32_bf16 v[10:13], v[142:145], v[218:221], v[10:13]
	v_mfma_f32_16x16x32_bf16 v[54:57], v[146:149], v[184:187], v[54:57]
	v_mfma_f32_16x16x32_bf16 v[54:57], v[164:167], v[188:191], v[54:57]
	v_mfma_f32_16x16x32_bf16 v[50:53], v[168:171], v[184:187], v[50:53]
	v_mfma_f32_16x16x32_bf16 v[50:53], v[172:175], v[188:191], v[50:53]
	v_mfma_f32_16x16x32_bf16 v[38:41], v[146:149], v[192:195], v[38:41]
	v_mfma_f32_16x16x32_bf16 v[38:41], v[164:167], v[196:199], v[38:41]
	v_mfma_f32_16x16x32_bf16 v[34:37], v[168:171], v[192:195], v[34:37]
	v_mfma_f32_16x16x32_bf16 v[34:37], v[172:175], v[196:199], v[34:37]
	v_mfma_f32_16x16x32_bf16 v[22:25], v[146:149], v[200:203], v[22:25]
	v_mfma_f32_16x16x32_bf16 v[22:25], v[164:167], v[204:207], v[22:25]
	v_mfma_f32_16x16x32_bf16 v[18:21], v[168:171], v[200:203], v[18:21]
	v_mfma_f32_16x16x32_bf16 v[18:21], v[172:175], v[204:207], v[18:21]
	v_mfma_f32_16x16x32_bf16 v[6:9], v[146:149], v[214:217], v[6:9]
	v_mfma_f32_16x16x32_bf16 v[6:9], v[164:167], v[218:221], v[6:9]
	v_mfma_f32_16x16x32_bf16 v[2:5], v[168:171], v[214:217], v[2:5]
	v_mfma_f32_16x16x32_bf16 v[2:5], v[172:175], v[218:221], v[2:5]
	s_barrier
	v_or_b32_e32 v130, 0x18000, v177
	v_add_u32_e32 v134, 0x18400, v177
	v_add_u32_e32 v138, 0x18800, v177
	v_add_u32_e32 v142, 0x18c00, v177
	v_or_b32_e32 v146, 0x1c000, v177
	v_add_u32_e32 v157, 0x1c400, v177
	ds_read_b128 v[130:133], v130
	ds_read_b128 v[134:137], v134
	ds_read_b128 v[138:141], v138
	ds_read_b128 v[142:145], v142
	ds_read_b128 v[146:149], v146
	ds_read_b128 v[164:167], v157
	v_add_u32_e32 v157, 0x1c800, v177
	v_add_u32_e32 v172, 0x1cc00, v177
	ds_read_b128 v[168:171], v157
	ds_read_b128 v[172:175], v172
	s_add_u32 s88, s88, s40
	s_addc_u32 s89, s89, 0
	s_mov_b32 m0, s51
	v_lshl_add_u64 v[228:229], s[88:89], 0, v[154:155]
	ds_read_b128 v[184:187], v176 offset:32768
	ds_read_b128 v[188:191], v176 offset:33792
	ds_read_b128 v[192:195], v176 offset:34816
	ds_read_b128 v[196:199], v176 offset:35840
	ds_read_b128 v[200:203], v176 offset:36864
	ds_read_b128 v[204:207], v176 offset:37888
	ds_read_b128 v[214:217], v176 offset:38912
	ds_read_b128 v[218:221], v176 offset:39936
	global_load_lds_dwordx4 v[228:229], off
	v_lshl_add_u64 v[228:229], s[88:89], 0, v[152:153]
	s_mov_b32 m0, s90
	s_nop 0
	global_load_lds_dwordx4 v[228:229], off
	s_waitcnt vmcnt(8)
	s_waitcnt lgkmcnt(0)
	s_barrier
	v_mfma_f32_16x16x32_bf16 v[126:129], v[130:133], v[184:187], v[126:129]
	v_mfma_f32_16x16x32_bf16 v[126:129], v[134:137], v[188:191], v[126:129]
	v_mfma_f32_16x16x32_bf16 v[122:125], v[138:141], v[184:187], v[122:125]
	v_mfma_f32_16x16x32_bf16 v[122:125], v[142:145], v[188:191], v[122:125]
	v_mfma_f32_16x16x32_bf16 v[110:113], v[130:133], v[192:195], v[110:113]
	v_mfma_f32_16x16x32_bf16 v[110:113], v[134:137], v[196:199], v[110:113]
	v_mfma_f32_16x16x32_bf16 v[106:109], v[138:141], v[192:195], v[106:109]
	v_mfma_f32_16x16x32_bf16 v[106:109], v[142:145], v[196:199], v[106:109]
	v_mfma_f32_16x16x32_bf16 v[94:97], v[130:133], v[200:203], v[94:97]
	v_mfma_f32_16x16x32_bf16 v[94:97], v[134:137], v[204:207], v[94:97]
	v_mfma_f32_16x16x32_bf16 v[90:93], v[138:141], v[200:203], v[90:93]
	v_mfma_f32_16x16x32_bf16 v[90:93], v[142:145], v[204:207], v[90:93]
	v_mfma_f32_16x16x32_bf16 v[78:81], v[130:133], v[214:217], v[78:81]
	v_mfma_f32_16x16x32_bf16 v[78:81], v[134:137], v[218:221], v[78:81]
	v_mfma_f32_16x16x32_bf16 v[74:77], v[138:141], v[214:217], v[74:77]
	v_mfma_f32_16x16x32_bf16 v[74:77], v[142:145], v[218:221], v[74:77]
	v_mfma_f32_16x16x32_bf16 v[118:121], v[146:149], v[184:187], v[118:121]
	v_mfma_f32_16x16x32_bf16 v[118:121], v[164:167], v[188:191], v[118:121]
	v_mfma_f32_16x16x32_bf16 v[114:117], v[168:171], v[184:187], v[114:117]
	v_mfma_f32_16x16x32_bf16 v[114:117], v[172:175], v[188:191], v[114:117]
	v_mfma_f32_16x16x32_bf16 v[102:105], v[146:149], v[192:195], v[102:105]
	v_mfma_f32_16x16x32_bf16 v[102:105], v[164:167], v[196:199], v[102:105]
	v_mfma_f32_16x16x32_bf16 v[98:101], v[168:171], v[192:195], v[98:101]
	v_mfma_f32_16x16x32_bf16 v[98:101], v[172:175], v[196:199], v[98:101]
	v_mfma_f32_16x16x32_bf16 v[86:89], v[146:149], v[200:203], v[86:89]
	v_mfma_f32_16x16x32_bf16 v[86:89], v[164:167], v[204:207], v[86:89]
	v_mfma_f32_16x16x32_bf16 v[82:85], v[168:171], v[200:203], v[82:85]
	v_mfma_f32_16x16x32_bf16 v[82:85], v[172:175], v[204:207], v[82:85]
	v_mfma_f32_16x16x32_bf16 v[70:73], v[146:149], v[214:217], v[70:73]
	v_mfma_f32_16x16x32_bf16 v[70:73], v[164:167], v[218:221], v[70:73]
	v_mfma_f32_16x16x32_bf16 v[66:69], v[168:171], v[214:217], v[66:69]
	v_mfma_f32_16x16x32_bf16 v[66:69], v[172:175], v[218:221], v[66:69]
	s_barrier
; #define PG8_STAGE(bufoff, gbase, voff) do { _Pragma("unroll") for (int _i = 0; _i < 2; ++_i) \
;         __builtin_amdgcn_global_load_lds((const unsigned*)((const char*)(gbase) + (voff)[_i]), (PG8_LAS unsigned*)(lds + (bufoff) + ldsw + _i * 8192), 16, 0, 0); } while (0)
; #define PG8_LDA(dst, b, h) do { _Pragma("unroll") for (int m = 0; m < 4; ++m) _Pragma("unroll") for (int k = 0; k < 2; ++k) dst[m][k] = *(const PG8_LAS bf16x8*)(lds + PG8_SA(b, h) + aoff + m * 2048 + k * 1024); } while (0)
; #define PG8_MMA(ai, bj, At, Bt) do { __builtin_amdgcn_s_setprio(1); _Pragma("unroll") for (int m = 0; m < 4; ++m) _Pragma("unroll") for (int n = 0; n < 2; ++n) _Pragma("unroll") for (int k = 0; k < 2; ++k) \
;         acc[ai][bj][m][n] = __builtin_amdgcn_mfma_f32_16x16x32_bf16(Bt[n][k], At[m][k], acc[ai][bj][m][n], 0, 0, 0); __builtin_amdgcn_s_setprio(0); } while (0)
; #define PG8_WAIT_V(n) asm volatile("s_waitcnt vmcnt(" #n ")" ::: "memory")
; #define PG8_WAIT_L(n) asm volatile("s_waitcnt lgkmcnt(" #n ")" ::: "memory")
; #define PG8_BAR __builtin_amdgcn_s_barrier()
; #define PG8_SCHED __builtin_amdgcn_sched_barrier(0)
; template <class Epi, class Sched, bool ALIGN_EPI = false, bool SP2 = false>
; __device__ __forceinline__ void gemm_phase(PG8_LAS unsigned char* lds, const Gemm g, const Sched& S, const Epi& E, const int tid) {
;     ...
;         for (int t = 0; t < nt; t += 2) {
;     ...
;             PG8_LDA(At, 1, 1); PG8_STAGE(PG8_SB(1, 0), b3, voffB); PG8_STAGE(PG8_SB(1, 1), b3 + hstep, voffB); PG8_STAGE(PG8_SA(1, 0), a3, voffA);
;             PG8_WAIT_V(8); PG8_WAIT_L(0); PG8_BAR; PG8_MMA(1, 0, At, B0); PG8_MMA(1, 1, At, B1); PG8_BAR; PG8_SCHED;
	s_mov_b32 m0, s91
	v_lshl_add_u64 v[178:179], v[178:179], 0, s[12:13]
	ds_read_b128 v[184:187], v176 offset:49152
	ds_read_b128 v[188:191], v176 offset:50176
	ds_read_b128 v[192:195], v176 offset:51200
	ds_read_b128 v[196:199], v176 offset:52224
	ds_read_b128 v[200:203], v176 offset:53248
	ds_read_b128 v[204:207], v176 offset:54272
	ds_read_b128 v[214:217], v176 offset:55296
	ds_read_b128 v[218:221], v176 offset:56320
	global_load_lds_dwordx4 v[178:179], off
	v_lshl_add_u64 v[178:179], v[180:181], 0, s[12:13]
	s_mov_b32 m0, s28
	s_nop 0
	global_load_lds_dwordx4 v[178:179], off
	v_lshl_add_u64 v[178:179], v[182:183], 0, s[12:13]
	s_mov_b32 m0, s97
	s_nop 0
	global_load_lds_dwordx4 v[178:179], off
	v_lshl_add_u64 v[178:179], v[222:223], 0, s[12:13]
	s_mov_b32 m0, s15
	s_nop 0
	global_load_lds_dwordx4 v[178:179], off
	v_lshl_add_u64 v[178:179], v[224:225], 0, s[12:13]
	s_mov_b32 m0, s29
	s_nop 0
	global_load_lds_dwordx4 v[178:179], off
	v_lshl_add_u64 v[178:179], v[226:227], 0, s[12:13]
	s_mov_b32 m0, s96
	s_nop 0
	global_load_lds_dwordx4 v[178:179], off
	s_waitcnt vmcnt(8)
	s_waitcnt lgkmcnt(0)
	s_barrier
	v_mfma_f32_16x16x32_bf16 v[62:65], v[130:133], v[184:187], v[62:65]
	v_mfma_f32_16x16x32_bf16 v[62:65], v[134:137], v[188:191], v[62:65]
	v_mfma_f32_16x16x32_bf16 v[58:61], v[138:141], v[184:187], v[58:61]
	v_mfma_f32_16x16x32_bf16 v[58:61], v[142:145], v[188:191], v[58:61]
	v_mfma_f32_16x16x32_bf16 v[46:49], v[130:133], v[192:195], v[46:49]
	v_mfma_f32_16x16x32_bf16 v[46:49], v[134:137], v[196:199], v[46:49]
	v_mfma_f32_16x16x32_bf16 v[42:45], v[138:141], v[192:195], v[42:45]
	v_mfma_f32_16x16x32_bf16 v[42:45], v[142:145], v[196:199], v[42:45]
	v_mfma_f32_16x16x32_bf16 v[30:33], v[130:133], v[200:203], v[30:33]
	v_mfma_f32_16x16x32_bf16 v[30:33], v[134:137], v[204:207], v[30:33]
	v_mfma_f32_16x16x32_bf16 v[26:29], v[138:141], v[200:203], v[26:29]
	v_mfma_f32_16x16x32_bf16 v[26:29], v[142:145], v[204:207], v[26:29]
	v_mfma_f32_16x16x32_bf16 v[14:17], v[130:133], v[214:217], v[14:17]
	v_mfma_f32_16x16x32_bf16 v[14:17], v[134:137], v[218:221], v[14:17]
	v_mfma_f32_16x16x32_bf16 v[10:13], v[138:141], v[214:217], v[10:13]
	v_mfma_f32_16x16x32_bf16 v[10:13], v[142:145], v[218:221], v[10:13]
	v_mfma_f32_16x16x32_bf16 v[54:57], v[146:149], v[184:187], v[54:57]
	v_mfma_f32_16x16x32_bf16 v[54:57], v[164:167], v[188:191], v[54:57]
	v_mfma_f32_16x16x32_bf16 v[50:53], v[168:171], v[184:187], v[50:53]
	v_mfma_f32_16x16x32_bf16 v[50:53], v[172:175], v[188:191], v[50:53]
	v_mfma_f32_16x16x32_bf16 v[38:41], v[146:149], v[192:195], v[38:41]
	v_mfma_f32_16x16x32_bf16 v[38:41], v[164:167], v[196:199], v[38:41]
	v_mfma_f32_16x16x32_bf16 v[34:37], v[168:171], v[192:195], v[34:37]
	v_mfma_f32_16x16x32_bf16 v[34:37], v[172:175], v[196:199], v[34:37]
	v_mfma_f32_16x16x32_bf16 v[22:25], v[146:149], v[200:203], v[22:25]
	v_mfma_f32_16x16x32_bf16 v[22:25], v[164:167], v[204:207], v[22:25]
	v_mfma_f32_16x16x32_bf16 v[18:21], v[168:171], v[200:203], v[18:21]
	v_mfma_f32_16x16x32_bf16 v[18:21], v[172:175], v[204:207], v[18:21]
	v_mfma_f32_16x16x32_bf16 v[6:9], v[146:149], v[214:217], v[6:9]
	v_mfma_f32_16x16x32_bf16 v[6:9], v[164:167], v[218:221], v[6:9]
	v_mfma_f32_16x16x32_bf16 v[2:5], v[168:171], v[214:217], v[2:5]
	v_mfma_f32_16x16x32_bf16 v[2:5], v[172:175], v[218:221], v[2:5]
	s_barrier
	s_add_u32 s86, s86, 0x100
	s_addc_u32 s87, s87, 0
	s_add_u32 vcc_lo, vcc_lo, 0x100
	s_addc_u32 vcc_hi, vcc_hi, 0
	s_cmp_ge_u32 s92, s2
	s_mov_b32 s88, s92
	s_cbranch_scc0 .LBB0_684
	s_and_b64 vcc, exec, s[30:31]
	s_cbranch_vccz .LBB0_687
	s_barrier

; #define PG8_STAGE(bufoff, gbase, voff) do { _Pragma("unroll") for (int _i = 0; _i < 2; ++_i) \
;         __builtin_amdgcn_global_load_lds((const unsigned*)((const char*)(gbase) + (voff)[_i]), (PG8_LAS unsigned*)(lds + (bufoff) + ldsw + _i * 8192), 16, 0, 0); } while (0)
; #define PG8_LDA(dst, b, h) do { _Pragma("unroll") for (int m = 0; m < 4; ++m) _Pragma("unroll") for (int k = 0; k < 2; ++k) dst[m][k] = *(const PG8_LAS bf16x8*)(lds + PG8_SA(b, h) + aoff + m * 2048 + k * 1024); } while (0)
; #define PG8_LDB(dst, b, h) do { _Pragma("unroll") for (int n = 0; n < 2; ++n) _Pragma("unroll") for (int k = 0; k < 2; ++k) dst[n][k] = *(const PG8_LAS bf16x8*)(lds + PG8_SB(b, h) + boff + n * 2048 + k * 1024); } while (0)
; #define PG8_MMA(ai, bj, At, Bt) do { __builtin_amdgcn_s_setprio(1); _Pragma("unroll") for (int m = 0; m < 4; ++m) _Pragma("unroll") for (int n = 0; n < 2; ++n) _Pragma("unroll") for (int k = 0; k < 2; ++k) \
;         acc[ai][bj][m][n] = __builtin_amdgcn_mfma_f32_16x16x32_bf16(Bt[n][k], At[m][k], acc[ai][bj][m][n], 0, 0, 0); __builtin_amdgcn_s_setprio(0); } while (0)
; #define PG8_WAIT_V(n) asm volatile("s_waitcnt vmcnt(" #n ")" ::: "memory")
; #define PG8_WAIT_L(n) asm volatile("s_waitcnt lgkmcnt(" #n ")" ::: "memory")
; template <class Epi, class Sched, bool ALIGN_EPI = false, bool SP2 = false>
; __device__ __forceinline__ void gemm_phase(PG8_LAS unsigned char* lds, const Gemm g, const Sched& S, const Epi& E, const int tid) {
;     ...
;             const bool last = (t == nt - 2);
;             const char* a1 = cA + (size_t)(t + 1) * kstep;
;             const char* a2 = last ? nA : cA + (size_t)(t + 2) * kstep; const char* b2 = last ? nB : cB + (size_t)(t + 2) * kstep;
;             const char* a3 = a2 + kstep; const char* b3 = b2 + kstep;
;             if (last && has_next) S.a_ready(nxt);
;             if constexpr (SP2) {
;             PG8_LDB(B0, 0, 0); PG8_LDB(B1, 0, 1); PG8_SCHED; PG8_LDA(At, 0, 0); PG8_STAGE(PG8_SA(1, 1), a1 + hstep, voffA);
;             PG8_WAIT_V(8); PG8_WAIT_L(0); PG8_BAR; PG8_MMA(0, 0, At, B0); PG8_MMA(0, 1, At, B1); PG8_BAR; PG8_SCHED;
;             PG8_LDA(At, 0, 1); PG8_STAGE(PG8_SB(0, 0), b2, voffB); PG8_STAGE(PG8_SB(0, 1), b2 + hstep, voffB); PG8_STAGE(PG8_SA(0, 0), a2, voffA);
;             PG8_WAIT_V(8); PG8_WAIT_L(0); PG8_BAR; PG8_MMA(1, 0, At, B0); PG8_MMA(1, 1, At, B1); PG8_BAR; PG8_SCHED;
.LBB0_695:
	s_add_i32 s42, s41, 2
	s_mov_b32 s43, s7
	s_or_b32 s6, s41, 1
	s_lshl_b64 s[44:45], s[42:43], 7
	v_or_b32_e32 v138, 0x10000, v137
	v_add_u32_e32 v142, 0x10400, v137
	v_add_u32_e32 v146, 0x10800, v137
	v_add_u32_e32 v150, 0x10c00, v137
	v_or_b32_e32 v154, 0x14000, v137
	v_add_u32_e32 v158, 0x14400, v137
	v_add_u32_e32 v162, 0x14800, v137
	v_add_u32_e32 v166, 0x14c00, v137
	s_cmp_lg_u32 s41, s35
	ds_read_b128 v[138:141], v138
	ds_read_b128 v[142:145], v142
	ds_read_b128 v[146:149], v146
	ds_read_b128 v[150:153], v150
	ds_read_b128 v[154:157], v154
	ds_read_b128 v[158:161], v158
	ds_read_b128 v[162:165], v162
	ds_read_b128 v[166:169], v166
	s_cselect_b32 s43, s44, 0
	s_cselect_b32 s41, s45, 0
	s_add_u32 s44, s36, s43
	s_addc_u32 s45, s37, s41
	s_add_u32 s46, s30, s43
	s_addc_u32 s47, s31, s41
	s_lshl_b64 s[50:51], s[6:7], 7
	s_add_u32 s50, s38, s50
	s_addc_u32 s51, s39, s51
	v_lshl_add_u64 v[178:179], s[50:51], 0, v[134:135]
	s_add_i32 m0, s4, 0xc000
	ds_read_b128 v[170:173], v136
	ds_read_b128 v[174:177], v136 offset:1024
	ds_read_b128 v[184:187], v136 offset:2048
	ds_read_b128 v[188:191], v136 offset:3072
	ds_read_b128 v[192:195], v136 offset:4096
	ds_read_b128 v[196:199], v136 offset:5120
	ds_read_b128 v[200:203], v136 offset:6144
	ds_read_b128 v[204:207], v136 offset:7168
	global_load_lds_dwordx4 v[178:179], off
	v_lshl_add_u64 v[178:179], s[50:51], 0, v[132:133]
	s_add_i32 m0, s4, 0xe000
	s_nop 0
	global_load_lds_dwordx4 v[178:179], off
	s_waitcnt vmcnt(8)
	s_waitcnt lgkmcnt(0)
	s_barrier
	v_mfma_f32_16x16x32_bf16 v[126:129], v[138:141], v[170:173], v[126:129]
	v_mfma_f32_16x16x32_bf16 v[126:129], v[142:145], v[174:177], v[126:129]
	v_mfma_f32_16x16x32_bf16 v[122:125], v[146:149], v[170:173], v[122:125]
	v_mfma_f32_16x16x32_bf16 v[122:125], v[150:153], v[174:177], v[122:125]
	v_mfma_f32_16x16x32_bf16 v[118:121], v[138:141], v[184:187], v[118:121]
	v_mfma_f32_16x16x32_bf16 v[118:121], v[142:145], v[188:191], v[118:121]
	v_mfma_f32_16x16x32_bf16 v[114:117], v[146:149], v[184:187], v[114:117]
	v_mfma_f32_16x16x32_bf16 v[114:117], v[150:153], v[188:191], v[114:117]
	v_mfma_f32_16x16x32_bf16 v[106:109], v[138:141], v[192:195], v[106:109]
	v_mfma_f32_16x16x32_bf16 v[106:109], v[142:145], v[196:199], v[106:109]
	v_mfma_f32_16x16x32_bf16 v[98:101], v[146:149], v[192:195], v[98:101]
	v_mfma_f32_16x16x32_bf16 v[98:101], v[150:153], v[196:199], v[98:101]
	v_mfma_f32_16x16x32_bf16 v[90:93], v[138:141], v[200:203], v[90:93]
	v_mfma_f32_16x16x32_bf16 v[90:93], v[142:145], v[204:207], v[90:93]
	v_mfma_f32_16x16x32_bf16 v[82:85], v[146:149], v[200:203], v[82:85]
	v_mfma_f32_16x16x32_bf16 v[82:85], v[150:153], v[204:207], v[82:85]
	v_mfma_f32_16x16x32_bf16 v[110:113], v[154:157], v[170:173], v[110:113]
	v_mfma_f32_16x16x32_bf16 v[110:113], v[158:161], v[174:177], v[110:113]
	v_mfma_f32_16x16x32_bf16 v[102:105], v[162:165], v[170:173], v[102:105]
	v_mfma_f32_16x16x32_bf16 v[102:105], v[166:169], v[174:177], v[102:105]
	v_mfma_f32_16x16x32_bf16 v[94:97], v[154:157], v[184:187], v[94:97]
	v_mfma_f32_16x16x32_bf16 v[94:97], v[158:161], v[188:191], v[94:97]
	v_mfma_f32_16x16x32_bf16 v[86:89], v[162:165], v[184:187], v[86:89]
	v_mfma_f32_16x16x32_bf16 v[86:89], v[166:169], v[188:191], v[86:89]
	v_mfma_f32_16x16x32_bf16 v[78:81], v[154:157], v[192:195], v[78:81]
	v_mfma_f32_16x16x32_bf16 v[78:81], v[158:161], v[196:199], v[78:81]
	v_mfma_f32_16x16x32_bf16 v[74:77], v[162:165], v[192:195], v[74:77]
	v_mfma_f32_16x16x32_bf16 v[74:77], v[166:169], v[196:199], v[74:77]
	v_mfma_f32_16x16x32_bf16 v[70:73], v[154:157], v[200:203], v[70:73]
	v_mfma_f32_16x16x32_bf16 v[70:73], v[158:161], v[204:207], v[70:73]
	v_mfma_f32_16x16x32_bf16 v[66:69], v[162:165], v[200:203], v[66:69]
	v_mfma_f32_16x16x32_bf16 v[66:69], v[166:169], v[204:207], v[66:69]
	s_barrier
	s_mov_b32 m0, s0
	v_lshl_add_u64 v[178:179], s[46:47], 0, v[0:1]
	v_lshl_add_u64 v[180:181], s[46:47], 0, v[130:131]
	s_add_u32 s46, s46, s40
	ds_read_b128 v[170:173], v136 offset:16384
	ds_read_b128 v[174:177], v136 offset:17408
	ds_read_b128 v[184:187], v136 offset:18432
	ds_read_b128 v[188:191], v136 offset:19456
	ds_read_b128 v[192:195], v136 offset:20480
	ds_read_b128 v[196:199], v136 offset:21504
	ds_read_b128 v[200:203], v136 offset:22528
	ds_read_b128 v[204:207], v136 offset:23552
	global_load_lds_dwordx4 v[178:179], off
	s_mov_b32 m0, s1
	s_addc_u32 s47, s47, 0
	global_load_lds_dwordx4 v[180:181], off
	v_lshl_add_u64 v[182:183], s[46:47], 0, v[0:1]
	s_mov_b32 m0, s5
	v_lshl_add_u64 v[214:215], s[46:47], 0, v[130:131]
	global_load_lds_dwordx4 v[182:183], off
	s_mov_b32 m0, s8
	v_lshl_add_u64 v[216:217], s[44:45], 0, v[134:135]
	global_load_lds_dwordx4 v[214:215], off
	s_mov_b32 m0, s4
	v_lshl_add_u64 v[218:219], s[44:45], 0, v[132:133]
	global_load_lds_dwordx4 v[216:217], off
	s_mov_b32 m0, s9
	s_nop 0
	global_load_lds_dwordx4 v[218:219], off
	s_waitcnt vmcnt(8)
	s_waitcnt lgkmcnt(0)
	s_barrier
; #define PG8_STAGE(bufoff, gbase, voff) do { _Pragma("unroll") for (int _i = 0; _i < 2; ++_i) \
;         __builtin_amdgcn_global_load_lds((const unsigned*)((const char*)(gbase) + (voff)[_i]), (PG8_LAS unsigned*)(lds + (bufoff) + ldsw + _i * 8192), 16, 0, 0); } while (0)
; #define PG8_LDA(dst, b, h) do { _Pragma("unroll") for (int m = 0; m < 4; ++m) _Pragma("unroll") for (int k = 0; k < 2; ++k) dst[m][k] = *(const PG8_LAS bf16x8*)(lds + PG8_SA(b, h) + aoff + m * 2048 + k * 1024); } while (0)
; #define PG8_LDB(dst, b, h) do { _Pragma("unroll") for (int n = 0; n < 2; ++n) _Pragma("unroll") for (int k = 0; k < 2; ++k) dst[n][k] = *(const PG8_LAS bf16x8*)(lds + PG8_SB(b, h) + boff + n * 2048 + k * 1024); } while (0)
; #define PG8_MMA(ai, bj, At, Bt) do { __builtin_amdgcn_s_setprio(1); _Pragma("unroll") for (int m = 0; m < 4; ++m) _Pragma("unroll") for (int n = 0; n < 2; ++n) _Pragma("unroll") for (int k = 0; k < 2; ++k) \
;         acc[ai][bj][m][n] = __builtin_amdgcn_mfma_f32_16x16x32_bf16(Bt[n][k], At[m][k], acc[ai][bj][m][n], 0, 0, 0); __builtin_amdgcn_s_setprio(0); } while (0)
; #define PG8_WAIT_V(n) asm volatile("s_waitcnt vmcnt(" #n ")" ::: "memory")
; #define PG8_WAIT_L(n) asm volatile("s_waitcnt lgkmcnt(" #n ")" ::: "memory")
; #define PG8_BAR __builtin_amdgcn_s_barrier()
; #define PG8_SCHED __builtin_amdgcn_sched_barrier(0)
; template <class Epi, class Sched, bool ALIGN_EPI = false, bool SP2 = false>
; __device__ __forceinline__ void gemm_phase(PG8_LAS unsigned char* lds, const Gemm g, const Sched& S, const Epi& E, const int tid) {
;     ...
;             PG8_WAIT_V(8); PG8_WAIT_L(0); PG8_BAR; PG8_MMA(1, 0, At, B0); PG8_MMA(1, 1, At, B1); PG8_BAR; PG8_SCHED;
;             PG8_LDB(B0, 1, 0); PG8_LDB(B1, 1, 1); PG8_SCHED; PG8_LDA(At, 1, 0); PG8_STAGE(PG8_SA(0, 1), a2 + hstep, voffA);
;             PG8_WAIT_V(8); PG8_WAIT_L(0); PG8_BAR; PG8_MMA(0, 0, At, B0); PG8_MMA(0, 1, At, B1); PG8_BAR; PG8_SCHED;
	v_mfma_f32_16x16x32_bf16 v[62:65], v[138:141], v[170:173], v[62:65]
	v_mfma_f32_16x16x32_bf16 v[62:65], v[142:145], v[174:177], v[62:65]
	v_mfma_f32_16x16x32_bf16 v[58:61], v[146:149], v[170:173], v[58:61]
	v_mfma_f32_16x16x32_bf16 v[58:61], v[150:153], v[174:177], v[58:61]
	v_mfma_f32_16x16x32_bf16 v[54:57], v[138:141], v[184:187], v[54:57]
	v_mfma_f32_16x16x32_bf16 v[54:57], v[142:145], v[188:191], v[54:57]
	v_mfma_f32_16x16x32_bf16 v[50:53], v[146:149], v[184:187], v[50:53]
	v_mfma_f32_16x16x32_bf16 v[50:53], v[150:153], v[188:191], v[50:53]
	v_mfma_f32_16x16x32_bf16 v[38:41], v[138:141], v[192:195], v[38:41]
	v_mfma_f32_16x16x32_bf16 v[38:41], v[142:145], v[196:199], v[38:41]
	v_mfma_f32_16x16x32_bf16 v[34:37], v[146:149], v[192:195], v[34:37]
	v_mfma_f32_16x16x32_bf16 v[34:37], v[150:153], v[196:199], v[34:37]
	v_mfma_f32_16x16x32_bf16 v[22:25], v[138:141], v[200:203], v[22:25]
	v_mfma_f32_16x16x32_bf16 v[22:25], v[142:145], v[204:207], v[22:25]
	v_mfma_f32_16x16x32_bf16 v[18:21], v[146:149], v[200:203], v[18:21]
	v_mfma_f32_16x16x32_bf16 v[18:21], v[150:153], v[204:207], v[18:21]
	v_mfma_f32_16x16x32_bf16 v[46:49], v[154:157], v[170:173], v[46:49]
	v_mfma_f32_16x16x32_bf16 v[46:49], v[158:161], v[174:177], v[46:49]
	v_mfma_f32_16x16x32_bf16 v[42:45], v[162:165], v[170:173], v[42:45]
	v_mfma_f32_16x16x32_bf16 v[42:45], v[166:169], v[174:177], v[42:45]
	v_mfma_f32_16x16x32_bf16 v[30:33], v[154:157], v[184:187], v[30:33]
	v_mfma_f32_16x16x32_bf16 v[30:33], v[158:161], v[188:191], v[30:33]
	v_mfma_f32_16x16x32_bf16 v[26:29], v[162:165], v[184:187], v[26:29]
	v_mfma_f32_16x16x32_bf16 v[26:29], v[166:169], v[188:191], v[26:29]
	v_mfma_f32_16x16x32_bf16 v[14:17], v[154:157], v[192:195], v[14:17]
	v_mfma_f32_16x16x32_bf16 v[14:17], v[158:161], v[196:199], v[14:17]
	v_mfma_f32_16x16x32_bf16 v[10:13], v[162:165], v[192:195], v[10:13]
	v_mfma_f32_16x16x32_bf16 v[10:13], v[166:169], v[196:199], v[10:13]
	v_mfma_f32_16x16x32_bf16 v[6:9], v[154:157], v[200:203], v[6:9]
	v_mfma_f32_16x16x32_bf16 v[6:9], v[158:161], v[204:207], v[6:9]
	v_mfma_f32_16x16x32_bf16 v[2:5], v[162:165], v[200:203], v[2:5]
	v_mfma_f32_16x16x32_bf16 v[2:5], v[166:169], v[204:207], v[2:5]
	s_barrier
	v_or_b32_e32 v138, 0x18000, v137
	v_add_u32_e32 v142, 0x18400, v137
	v_add_u32_e32 v146, 0x18800, v137
	v_add_u32_e32 v150, 0x18c00, v137
	v_or_b32_e32 v154, 0x1c000, v137
	v_add_u32_e32 v158, 0x1c400, v137
	v_add_u32_e32 v162, 0x1c800, v137
	v_add_u32_e32 v166, 0x1cc00, v137
	ds_read_b128 v[138:141], v138
	ds_read_b128 v[142:145], v142
	ds_read_b128 v[146:149], v146
	ds_read_b128 v[150:153], v150
	ds_read_b128 v[154:157], v154
	ds_read_b128 v[158:161], v158
	ds_read_b128 v[162:165], v162
	ds_read_b128 v[166:169], v166
	s_add_u32 s44, s44, s40
	s_addc_u32 s45, s45, 0
	s_mov_b32 m0, s14
	v_lshl_add_u64 v[220:221], s[44:45], 0, v[134:135]
	ds_read_b128 v[170:173], v136 offset:32768
	ds_read_b128 v[174:177], v136 offset:33792
	ds_read_b128 v[184:187], v136 offset:34816
	ds_read_b128 v[188:191], v136 offset:35840
	ds_read_b128 v[192:195], v136 offset:36864
	ds_read_b128 v[196:199], v136 offset:37888
	ds_read_b128 v[200:203], v136 offset:38912
	ds_read_b128 v[204:207], v136 offset:39936
	global_load_lds_dwordx4 v[220:221], off
	v_lshl_add_u64 v[220:221], s[44:45], 0, v[132:133]
	s_mov_b32 m0, s15
	s_nop 0
	global_load_lds_dwordx4 v[220:221], off
	s_waitcnt vmcnt(8)
	s_waitcnt lgkmcnt(0)
	s_barrier
	v_mfma_f32_16x16x32_bf16 v[126:129], v[138:141], v[170:173], v[126:129]
	v_mfma_f32_16x16x32_bf16 v[126:129], v[142:145], v[174:177], v[126:129]
	v_mfma_f32_16x16x32_bf16 v[122:125], v[146:149], v[170:173], v[122:125]
	v_mfma_f32_16x16x32_bf16 v[122:125], v[150:153], v[174:177], v[122:125]
	v_mfma_f32_16x16x32_bf16 v[118:121], v[138:141], v[184:187], v[118:121]
	v_mfma_f32_16x16x32_bf16 v[118:121], v[142:145], v[188:191], v[118:121]
	v_mfma_f32_16x16x32_bf16 v[114:117], v[146:149], v[184:187], v[114:117]
	v_mfma_f32_16x16x32_bf16 v[114:117], v[150:153], v[188:191], v[114:117]
	v_mfma_f32_16x16x32_bf16 v[106:109], v[138:141], v[192:195], v[106:109]
	v_mfma_f32_16x16x32_bf16 v[106:109], v[142:145], v[196:199], v[106:109]
	v_mfma_f32_16x16x32_bf16 v[98:101], v[146:149], v[192:195], v[98:101]
	v_mfma_f32_16x16x32_bf16 v[98:101], v[150:153], v[196:199], v[98:101]
	v_mfma_f32_16x16x32_bf16 v[90:93], v[138:141], v[200:203], v[90:93]
	v_mfma_f32_16x16x32_bf16 v[90:93], v[142:145], v[204:207], v[90:93]
	v_mfma_f32_16x16x32_bf16 v[82:85], v[146:149], v[200:203], v[82:85]
	v_mfma_f32_16x16x32_bf16 v[82:85], v[150:153], v[204:207], v[82:85]
	v_mfma_f32_16x16x32_bf16 v[110:113], v[154:157], v[170:173], v[110:113]
	v_mfma_f32_16x16x32_bf16 v[110:113], v[158:161], v[174:177], v[110:113]
	v_mfma_f32_16x16x32_bf16 v[102:105], v[162:165], v[170:173], v[102:105]
	v_mfma_f32_16x16x32_bf16 v[102:105], v[166:169], v[174:177], v[102:105]
	v_mfma_f32_16x16x32_bf16 v[94:97], v[154:157], v[184:187], v[94:97]
	v_mfma_f32_16x16x32_bf16 v[94:97], v[158:161], v[188:191], v[94:97]
	v_mfma_f32_16x16x32_bf16 v[86:89], v[162:165], v[184:187], v[86:89]
	v_mfma_f32_16x16x32_bf16 v[86:89], v[166:169], v[188:191], v[86:89]
	v_mfma_f32_16x16x32_bf16 v[78:81], v[154:157], v[192:195], v[78:81]
	v_mfma_f32_16x16x32_bf16 v[78:81], v[158:161], v[196:199], v[78:81]
	v_mfma_f32_16x16x32_bf16 v[74:77], v[162:165], v[192:195], v[74:77]
	v_mfma_f32_16x16x32_bf16 v[74:77], v[166:169], v[196:199], v[74:77]
	v_mfma_f32_16x16x32_bf16 v[70:73], v[154:157], v[200:203], v[70:73]
	v_mfma_f32_16x16x32_bf16 v[70:73], v[158:161], v[204:207], v[70:73]
	v_mfma_f32_16x16x32_bf16 v[66:69], v[162:165], v[200:203], v[66:69]
	v_mfma_f32_16x16x32_bf16 v[66:69], v[166:169], v[204:207], v[66:69]
	s_barrier
; #define PG8_STAGE(bufoff, gbase, voff) do { _Pragma("unroll") for (int _i = 0; _i < 2; ++_i) \
;         __builtin_amdgcn_global_load_lds((const unsigned*)((const char*)(gbase) + (voff)[_i]), (PG8_LAS unsigned*)(lds + (bufoff) + ldsw + _i * 8192), 16, 0, 0); } while (0)
; #define PG8_LDA(dst, b, h) do { _Pragma("unroll") for (int m = 0; m < 4; ++m) _Pragma("unroll") for (int k = 0; k < 2; ++k) dst[m][k] = *(const PG8_LAS bf16x8*)(lds + PG8_SA(b, h) + aoff + m * 2048 + k * 1024); } while (0)
; #define PG8_MMA(ai, bj, At, Bt) do { __builtin_amdgcn_s_setprio(1); _Pragma("unroll") for (int m = 0; m < 4; ++m) _Pragma("unroll") for (int n = 0; n < 2; ++n) _Pragma("unroll") for (int k = 0; k < 2; ++k) \
;         acc[ai][bj][m][n] = __builtin_amdgcn_mfma_f32_16x16x32_bf16(Bt[n][k], At[m][k], acc[ai][bj][m][n], 0, 0, 0); __builtin_amdgcn_s_setprio(0); } while (0)
; #define PG8_WAIT_V(n) asm volatile("s_waitcnt vmcnt(" #n ")" ::: "memory")
; #define PG8_WAIT_L(n) asm volatile("s_waitcnt lgkmcnt(" #n ")" ::: "memory")
; #define PG8_BAR __builtin_amdgcn_s_barrier()
; #define PG8_SCHED __builtin_amdgcn_sched_barrier(0)
; template <class Epi, class Sched, bool ALIGN_EPI = false, bool SP2 = false>
; __device__ __forceinline__ void gemm_phase(PG8_LAS unsigned char* lds, const Gemm g, const Sched& S, const Epi& E, const int tid) {
;     ...
;         for (int t = 0; t < nt; t += 2) {
;     ...
;             PG8_LDA(At, 1, 1); PG8_STAGE(PG8_SB(1, 0), b3, voffB); PG8_STAGE(PG8_SB(1, 1), b3 + hstep, voffB); PG8_STAGE(PG8_SA(1, 0), a3, voffA);
;             PG8_WAIT_V(8); PG8_WAIT_L(0); PG8_BAR; PG8_MMA(1, 0, At, B0); PG8_MMA(1, 1, At, B1); PG8_BAR; PG8_SCHED;
	s_mov_b32 m0, s24
	v_lshl_add_u64 v[178:179], v[178:179], 0, s[12:13]
	ds_read_b128 v[170:173], v136 offset:49152
	ds_read_b128 v[174:177], v136 offset:50176
	ds_read_b128 v[184:187], v136 offset:51200
	ds_read_b128 v[188:191], v136 offset:52224
	ds_read_b128 v[192:195], v136 offset:53248
	ds_read_b128 v[196:199], v136 offset:54272
	ds_read_b128 v[200:203], v136 offset:55296
	ds_read_b128 v[204:207], v136 offset:56320
	global_load_lds_dwordx4 v[178:179], off
	v_lshl_add_u64 v[178:179], v[180:181], 0, s[12:13]
	s_mov_b32 m0, s26
	s_nop 0
	global_load_lds_dwordx4 v[178:179], off
	v_lshl_add_u64 v[178:179], v[182:183], 0, s[12:13]
	s_mov_b32 m0, s29
	s_nop 0
	global_load_lds_dwordx4 v[178:179], off
	v_lshl_add_u64 v[178:179], v[214:215], 0, s[12:13]
	s_mov_b32 m0, s34
	s_nop 0
	global_load_lds_dwordx4 v[178:179], off
	v_lshl_add_u64 v[178:179], v[216:217], 0, s[12:13]
	s_mov_b32 m0, s27
	s_nop 0
	global_load_lds_dwordx4 v[178:179], off
	v_lshl_add_u64 v[178:179], v[218:219], 0, s[12:13]
	s_mov_b32 m0, s28
	s_nop 0
	global_load_lds_dwordx4 v[178:179], off
	s_waitcnt vmcnt(8)
	s_waitcnt lgkmcnt(0)
	s_barrier
	v_mfma_f32_16x16x32_bf16 v[62:65], v[138:141], v[170:173], v[62:65]
	v_mfma_f32_16x16x32_bf16 v[62:65], v[142:145], v[174:177], v[62:65]
	v_mfma_f32_16x16x32_bf16 v[58:61], v[146:149], v[170:173], v[58:61]
	v_mfma_f32_16x16x32_bf16 v[58:61], v[150:153], v[174:177], v[58:61]
	v_mfma_f32_16x16x32_bf16 v[54:57], v[138:141], v[184:187], v[54:57]
	v_mfma_f32_16x16x32_bf16 v[54:57], v[142:145], v[188:191], v[54:57]
	v_mfma_f32_16x16x32_bf16 v[50:53], v[146:149], v[184:187], v[50:53]
	v_mfma_f32_16x16x32_bf16 v[50:53], v[150:153], v[188:191], v[50:53]
	v_mfma_f32_16x16x32_bf16 v[38:41], v[138:141], v[192:195], v[38:41]
	v_mfma_f32_16x16x32_bf16 v[38:41], v[142:145], v[196:199], v[38:41]
	v_mfma_f32_16x16x32_bf16 v[34:37], v[146:149], v[192:195], v[34:37]
	v_mfma_f32_16x16x32_bf16 v[34:37], v[150:153], v[196:199], v[34:37]
	v_mfma_f32_16x16x32_bf16 v[22:25], v[138:141], v[200:203], v[22:25]
	v_mfma_f32_16x16x32_bf16 v[22:25], v[142:145], v[204:207], v[22:25]
	v_mfma_f32_16x16x32_bf16 v[18:21], v[146:149], v[200:203], v[18:21]
	v_mfma_f32_16x16x32_bf16 v[18:21], v[150:153], v[204:207], v[18:21]
	v_mfma_f32_16x16x32_bf16 v[46:49], v[154:157], v[170:173], v[46:49]
	v_mfma_f32_16x16x32_bf16 v[46:49], v[158:161], v[174:177], v[46:49]
	v_mfma_f32_16x16x32_bf16 v[42:45], v[162:165], v[170:173], v[42:45]
	v_mfma_f32_16x16x32_bf16 v[42:45], v[166:169], v[174:177], v[42:45]
	v_mfma_f32_16x16x32_bf16 v[30:33], v[154:157], v[184:187], v[30:33]
	v_mfma_f32_16x16x32_bf16 v[30:33], v[158:161], v[188:191], v[30:33]
	v_mfma_f32_16x16x32_bf16 v[26:29], v[162:165], v[184:187], v[26:29]
	v_mfma_f32_16x16x32_bf16 v[26:29], v[166:169], v[188:191], v[26:29]
	v_mfma_f32_16x16x32_bf16 v[14:17], v[154:157], v[192:195], v[14:17]
	v_mfma_f32_16x16x32_bf16 v[14:17], v[158:161], v[196:199], v[14:17]
	v_mfma_f32_16x16x32_bf16 v[10:13], v[162:165], v[192:195], v[10:13]
	v_mfma_f32_16x16x32_bf16 v[10:13], v[166:169], v[196:199], v[10:13]
	v_mfma_f32_16x16x32_bf16 v[6:9], v[154:157], v[200:203], v[6:9]
	v_mfma_f32_16x16x32_bf16 v[6:9], v[158:161], v[204:207], v[6:9]
	v_mfma_f32_16x16x32_bf16 v[2:5], v[162:165], v[200:203], v[2:5]
	v_mfma_f32_16x16x32_bf16 v[2:5], v[166:169], v[204:207], v[2:5]
	s_barrier
	s_cmp_ge_u32 s42, s21
	s_mov_b32 s41, s42
	s_cbranch_scc0 .LBB0_695
	v_readlane_b32 s26, v254, 47
	v_readlane_b32 s28, v254, 49
	s_cmpk_lt_u32 s2, 0x100
	v_readlane_b32 s27, v254, 48
	v_readlane_b32 s29, v254, 50
	s_cbranch_scc0 .LBB0_698
	s_barrier

; #define PG8_STAGE(bufoff, gbase, voff) do { _Pragma("unroll") for (int _i = 0; _i < 2; ++_i) \
;         __builtin_amdgcn_global_load_lds((const unsigned*)((const char*)(gbase) + (voff)[_i]), (PG8_LAS unsigned*)(lds + (bufoff) + ldsw + _i * 8192), 16, 0, 0); } while (0)
; #define PG8_WAIT_V(n) asm volatile("s_waitcnt vmcnt(" #n ")" ::: "memory")
; #define PG8_BAR __builtin_amdgcn_s_barrier()
; template <class Epi, class Sched, bool ALIGN_EPI = false, bool SP2 = false>
; __device__ __forceinline__ void gemm_phase(PG8_LAS unsigned char* lds, const Gemm g, const Sched& S, const Epi& E, const int tid) {
;     ...
; #pragma unroll
;     for (int a = 0; a < 2; ++a)
; #pragma unroll
;         for (int b = 0; b < 2; ++b)
; #pragma unroll
;             for (int m = 0; m < 4; ++m)
; #pragma unroll
;                 for (int n = 0; n < 2; ++n) acc[a][b][m][n] = (f32x4){0.f, 0.f, 0.f, 0.f};
;     ...
;         PG8_WAIT_V(2); PG8_BAR;
;         PG8_STAGE(PG8_SB(1, 0), cB + kstep, voffB); PG8_STAGE(PG8_SA(1, 0), cA + kstep, voffA); PG8_STAGE(PG8_SB(1, 1), cB + hstep + kstep, voffB);
;         PG8_WAIT_V(6); PG8_BAR;
.LBB0_707:
	s_lshl_b32 s0, s0, 5
	v_readlane_b32 s84, v253, 21
	v_and_b32_e32 v9, 48, v8
	v_lshlrev_b32_e32 v18, 6, v8
	s_movk_i32 s5, 0x3c0
	v_lshlrev_b32_e32 v8, 2, v8
	s_and_b32 s90, s0, 0x60
	v_readlane_b32 s85, v253, 22
	v_and_or_b32 v9, v18, s5, v9
	v_and_b32_e32 v8, 32, v8
	s_lshl_b32 s0, s90, 7
	v_lshl_add_u64 v[10:11], s[84:85], 0, v[0:1]
	v_mov_b32_e32 v131, v1
	v_readlane_b32 s30, v253, 17
	s_lshl_b32 s89, s4, 6
	s_lshl_b32 s4, s4, 13
	v_bitop3_b32 v141, s0, v9, v8 bitop3:0xf6
	v_add_u32_e32 v222, 0x10000, v141
	s_add_i32 s0, s1, 0x18000
	v_lshl_add_u64 v[12:13], s[84:85], 0, v[130:131]
	v_mov_b32_e32 v135, v1
	v_readlane_b32 s31, v253, 18
	v_bitop3_b32 v140, v9, s4, v8 bitop3:0xde
	v_lshl_add_u64 v[8:9], v[10:11], 0, s[12:13]
	s_mov_b32 m0, s0
	s_add_i32 s17, s1, 0x1a000
	v_lshl_add_u64 v[14:15], s[30:31], 0, v[134:135]
	v_mov_b32_e32 v133, v1
	s_waitcnt vmcnt(2)
	s_barrier
	global_load_lds_dwordx4 v[8:9], off
	v_lshl_add_u64 v[8:9], v[12:13], 0, s[12:13]
	s_mov_b32 m0, s17
	s_add_i32 s91, s1, 0x8000
	v_lshl_add_u64 v[16:17], s[30:31], 0, v[132:133]
	global_load_lds_dwordx4 v[8:9], off
	v_lshl_add_u64 v[8:9], v[14:15], 0, s[12:13]
	s_mov_b32 m0, s91
	s_add_i32 s50, s1, 0xa000
	v_readlane_b32 s4, v253, 23
	global_load_lds_dwordx4 v[8:9], off
	v_lshl_add_u64 v[8:9], v[16:17], 0, s[12:13]
	s_mov_b32 m0, s50
	s_add_i32 s51, s1, 0x1c000
	v_readlane_b32 s5, v253, 24
	global_load_lds_dwordx4 v[8:9], off
	s_nop 0
	v_lshl_add_u64 v[8:9], s[4:5], 0, v[0:1]
	s_mov_b32 m0, s51
	s_add_i32 s26, s1, 0x1e000
	global_load_lds_dwordx4 v[8:9], off
	v_lshl_add_u64 v[8:9], s[4:5], 0, v[130:131]
	s_mov_b32 m0, s26
	s_cmpk_lt_u32 s2, 0x100
	global_load_lds_dwordx4 v[8:9], off
	v_lshlrev_b32_e32 v8, 14, v6
	v_and_b32_e32 v8, 0xffff8000, v8
	v_lshl_add_u32 v5, v5, 11, v8
	v_and_b32_e32 v6, 1, v6
	v_lshl_or_b32 v5, v6, 6, v5
	v_lshl_add_u32 v136, v7, 1, v5
	v_lshlrev_b32_e32 v5, 14, v2
	v_and_b32_e32 v5, 0xffff8000, v5
	s_waitcnt vmcnt(6)
	v_lshl_add_u32 v3, v3, 11, v5
	v_and_b32_e32 v2, 1, v2
	v_lshl_or_b32 v2, v2, 6, v3
	s_cselect_b64 s[38:39], -1, 0
	v_mov_b32_e32 v137, v1
	v_lshl_add_u32 v138, v4, 1, v2
	v_mov_b32_e32 v139, v1
	s_mov_b32 s27, 0
	v_readlane_b32 s2, v253, 10
	v_readlane_b32 s4, v253, 11
	s_barrier
	v_readlane_b32 s5, v253, 12
	v_mov_b64_e32 v[2:3], 0
	v_mov_b64_e32 v[4:5], 0
	v_mov_b64_e32 v[6:7], 0
	v_mov_b64_e32 v[8:9], 0
	v_mov_b64_e32 v[10:11], 0
	v_mov_b64_e32 v[12:13], 0
	v_mov_b64_e32 v[14:15], 0
	v_mov_b64_e32 v[16:17], 0
	v_mov_b64_e32 v[18:19], 0
	v_mov_b64_e32 v[20:21], 0
	v_mov_b64_e32 v[22:23], 0
	v_mov_b64_e32 v[24:25], 0
	v_mov_b64_e32 v[26:27], 0
	v_mov_b64_e32 v[28:29], 0
	v_mov_b64_e32 v[30:31], 0
	v_mov_b64_e32 v[32:33], 0
	v_mov_b64_e32 v[34:35], 0
	v_mov_b64_e32 v[36:37], 0
	v_mov_b64_e32 v[38:39], 0
	v_mov_b64_e32 v[40:41], 0
	v_mov_b64_e32 v[42:43], 0
	v_mov_b64_e32 v[44:45], 0
	v_mov_b64_e32 v[46:47], 0
	v_mov_b64_e32 v[48:49], 0
	v_mov_b64_e32 v[50:51], 0
	v_mov_b64_e32 v[52:53], 0
	v_mov_b64_e32 v[54:55], 0
	v_mov_b64_e32 v[56:57], 0
	v_mov_b64_e32 v[58:59], 0
	v_mov_b64_e32 v[60:61], 0
	v_mov_b64_e32 v[62:63], 0
	v_mov_b64_e32 v[64:65], 0
	v_mov_b64_e32 v[66:67], 0
	v_mov_b64_e32 v[68:69], 0
	v_mov_b64_e32 v[70:71], 0
	v_mov_b64_e32 v[72:73], 0
	v_mov_b64_e32 v[74:75], 0
	v_mov_b64_e32 v[76:77], 0
	v_mov_b64_e32 v[78:79], 0
	v_mov_b64_e32 v[80:81], 0
	v_mov_b64_e32 v[82:83], 0
	v_mov_b64_e32 v[84:85], 0
	v_mov_b64_e32 v[86:87], 0
	v_mov_b64_e32 v[88:89], 0
	v_mov_b64_e32 v[90:91], 0
	v_mov_b64_e32 v[92:93], 0
	v_mov_b64_e32 v[94:95], 0
	v_mov_b64_e32 v[96:97], 0
	v_mov_b64_e32 v[98:99], 0
	v_mov_b64_e32 v[100:101], 0
	v_mov_b64_e32 v[102:103], 0
	v_mov_b64_e32 v[104:105], 0
	v_mov_b64_e32 v[106:107], 0
	v_mov_b64_e32 v[108:109], 0
	v_mov_b64_e32 v[110:111], 0
	v_mov_b64_e32 v[112:113], 0
	v_mov_b64_e32 v[114:115], 0
	v_mov_b64_e32 v[116:117], 0
	v_mov_b64_e32 v[118:119], 0
	v_mov_b64_e32 v[120:121], 0
	v_mov_b64_e32 v[122:123], 0
	v_mov_b64_e32 v[124:125], 0
	v_mov_b64_e32 v[126:127], 0
	v_mov_b64_e32 v[128:129], 0
	s_branch .LBB0_710

; #define PG8_STAGE(bufoff, gbase, voff) do { _Pragma("unroll") for (int _i = 0; _i < 2; ++_i) \
;         __builtin_amdgcn_global_load_lds((const unsigned*)((const char*)(gbase) + (voff)[_i]), (PG8_LAS unsigned*)(lds + (bufoff) + ldsw + _i * 8192), 16, 0, 0); } while (0)
; #define PG8_LDA(dst, b, h) do { _Pragma("unroll") for (int m = 0; m < 4; ++m) _Pragma("unroll") for (int k = 0; k < 2; ++k) dst[m][k] = *(const PG8_LAS bf16x8*)(lds + PG8_SA(b, h) + aoff + m * 2048 + k * 1024); } while (0)
; #define PG8_LDB(dst, b, h) do { _Pragma("unroll") for (int n = 0; n < 2; ++n) _Pragma("unroll") for (int k = 0; k < 2; ++k) dst[n][k] = *(const PG8_LAS bf16x8*)(lds + PG8_SB(b, h) + boff + n * 2048 + k * 1024); } while (0)
; #define PG8_MMA(ai, bj, At, Bt) do { __builtin_amdgcn_s_setprio(1); _Pragma("unroll") for (int m = 0; m < 4; ++m) _Pragma("unroll") for (int n = 0; n < 2; ++n) _Pragma("unroll") for (int k = 0; k < 2; ++k) \
;         acc[ai][bj][m][n] = __builtin_amdgcn_mfma_f32_16x16x32_bf16(Bt[n][k], At[m][k], acc[ai][bj][m][n], 0, 0, 0); __builtin_amdgcn_s_setprio(0); } while (0)
; #define PG8_WAIT_V(n) asm volatile("s_waitcnt vmcnt(" #n ")" ::: "memory")
; #define PG8_WAIT_L(n) asm volatile("s_waitcnt lgkmcnt(" #n ")" ::: "memory")
; #define PG8_BAR __builtin_amdgcn_s_barrier()
; #define PG8_SCHED __builtin_amdgcn_sched_barrier(0)
; template <class Epi, class Sched, bool ALIGN_EPI = false, bool SP2 = false>
; __device__ __forceinline__ void gemm_phase(PG8_LAS unsigned char* lds, const Gemm g, const Sched& S, const Epi& E, const int tid) {
;     ...
;             PG8_LDB(B0, 0, 0); PG8_LDB(B1, 0, 1); PG8_SCHED; PG8_LDA(At, 0, 0); PG8_STAGE(PG8_SA(1, 1), a1 + hstep, voffA);
;             PG8_WAIT_V(8); PG8_WAIT_L(0); PG8_BAR; PG8_MMA(0, 0, At, B0); PG8_MMA(0, 1, At, B1); PG8_BAR; PG8_SCHED;
.LBB0_713:
	ds_read_b128 v[142:145], v222
	ds_read_b128 v[146:149], v222 offset:1024
	ds_read_b128 v[150:153], v222 offset:2048
	ds_read_b128 v[154:157], v222 offset:3072
	ds_read_b128 v[158:161], v222 offset:16384
	ds_read_b128 v[162:165], v222 offset:17408
	ds_read_b128 v[166:169], v222 offset:18432
	ds_read_b128 v[170:173], v222 offset:19456
	s_add_u32 s84, s30, 0xfffc0080
	s_addc_u32 s85, s31, -1
	s_cmp_eq_u32 s43, 12
	s_cselect_b32 s87, s5, s85
	s_cselect_b32 s86, s15, s84
	s_cselect_b32 s85, s20, s41
	s_cselect_b32 s84, s21, s24
	v_lshl_add_u64 v[178:179], s[30:31], 0, v[136:137]
	s_add_i32 m0, s1, 0xc000
	ds_read_b128 v[174:177], v140
	ds_read_b128 v[184:187], v140 offset:1024
	ds_read_b128 v[188:191], v140 offset:2048
	ds_read_b128 v[192:195], v140 offset:3072
	ds_read_b128 v[196:199], v140 offset:4096
	ds_read_b128 v[200:203], v140 offset:5120
	ds_read_b128 v[204:207], v140 offset:6144
	ds_read_b128 v[214:217], v140 offset:7168
	global_load_lds_dwordx4 v[178:179], off
	v_lshl_add_u64 v[178:179], s[30:31], 0, v[138:139]
	s_add_i32 m0, s1, 0xe000
	s_nop 0
	global_load_lds_dwordx4 v[178:179], off
	s_waitcnt vmcnt(8)
	s_waitcnt lgkmcnt(0)
	s_barrier
	v_mfma_f32_16x16x32_bf16 v[126:129], v[142:145], v[174:177], v[126:129]
	v_mfma_f32_16x16x32_bf16 v[126:129], v[146:149], v[184:187], v[126:129]
	v_mfma_f32_16x16x32_bf16 v[118:121], v[150:153], v[174:177], v[118:121]
	v_mfma_f32_16x16x32_bf16 v[118:121], v[154:157], v[184:187], v[118:121]
	v_mfma_f32_16x16x32_bf16 v[110:113], v[142:145], v[188:191], v[110:113]
	v_mfma_f32_16x16x32_bf16 v[110:113], v[146:149], v[192:195], v[110:113]
	v_mfma_f32_16x16x32_bf16 v[102:105], v[150:153], v[188:191], v[102:105]
	v_mfma_f32_16x16x32_bf16 v[102:105], v[154:157], v[192:195], v[102:105]
	v_mfma_f32_16x16x32_bf16 v[94:97], v[142:145], v[196:199], v[94:97]
	v_mfma_f32_16x16x32_bf16 v[94:97], v[146:149], v[200:203], v[94:97]
	v_mfma_f32_16x16x32_bf16 v[86:89], v[150:153], v[196:199], v[86:89]
	v_mfma_f32_16x16x32_bf16 v[86:89], v[154:157], v[200:203], v[86:89]
	v_mfma_f32_16x16x32_bf16 v[78:81], v[142:145], v[204:207], v[78:81]
	v_mfma_f32_16x16x32_bf16 v[78:81], v[146:149], v[214:217], v[78:81]
	v_mfma_f32_16x16x32_bf16 v[70:73], v[150:153], v[204:207], v[70:73]
	v_mfma_f32_16x16x32_bf16 v[70:73], v[154:157], v[214:217], v[70:73]
	v_mfma_f32_16x16x32_bf16 v[122:125], v[158:161], v[174:177], v[122:125]
	v_mfma_f32_16x16x32_bf16 v[122:125], v[162:165], v[184:187], v[122:125]
	v_mfma_f32_16x16x32_bf16 v[114:117], v[166:169], v[174:177], v[114:117]
	v_mfma_f32_16x16x32_bf16 v[114:117], v[170:173], v[184:187], v[114:117]
	v_mfma_f32_16x16x32_bf16 v[106:109], v[158:161], v[188:191], v[106:109]
	v_mfma_f32_16x16x32_bf16 v[106:109], v[162:165], v[192:195], v[106:109]
	v_mfma_f32_16x16x32_bf16 v[98:101], v[166:169], v[188:191], v[98:101]
	v_mfma_f32_16x16x32_bf16 v[98:101], v[170:173], v[192:195], v[98:101]
	v_mfma_f32_16x16x32_bf16 v[90:93], v[158:161], v[196:199], v[90:93]
	v_mfma_f32_16x16x32_bf16 v[90:93], v[162:165], v[200:203], v[90:93]
	v_mfma_f32_16x16x32_bf16 v[82:85], v[166:169], v[196:199], v[82:85]
	v_mfma_f32_16x16x32_bf16 v[82:85], v[170:173], v[200:203], v[82:85]
	v_mfma_f32_16x16x32_bf16 v[74:77], v[158:161], v[204:207], v[74:77]
	v_mfma_f32_16x16x32_bf16 v[74:77], v[162:165], v[214:217], v[74:77]
	v_mfma_f32_16x16x32_bf16 v[66:69], v[166:169], v[204:207], v[66:69]
	v_mfma_f32_16x16x32_bf16 v[66:69], v[170:173], v[214:217], v[66:69]
	s_barrier
	s_mov_b32 m0, s6
	v_lshl_add_u64 v[178:179], s[84:85], 0, v[0:1]
	s_add_u32 s92, s84, 0x40000
	ds_read_b128 v[174:177], v140 offset:16384
	ds_read_b128 v[184:187], v140 offset:17408
	ds_read_b128 v[188:191], v140 offset:18432
	ds_read_b128 v[192:195], v140 offset:19456
	ds_read_b128 v[196:199], v140 offset:20480
	ds_read_b128 v[200:203], v140 offset:21504
	ds_read_b128 v[204:207], v140 offset:22528
	ds_read_b128 v[214:217], v140 offset:23552
	global_load_lds_dwordx4 v[178:179], off
	v_lshl_add_u64 v[180:181], s[84:85], 0, v[130:131]
	s_mov_b32 m0, s8
	s_addc_u32 s93, s85, 0
	global_load_lds_dwordx4 v[180:181], off
	v_lshl_add_u64 v[182:183], s[92:93], 0, v[0:1]
	s_mov_b32 m0, s9
	v_lshl_add_u64 v[218:219], s[86:87], 0, v[132:133]
	global_load_lds_dwordx4 v[182:183], off
	v_lshl_add_u64 v[182:183], s[92:93], 0, v[130:131]
	s_mov_b32 m0, s14
	s_nop 0
	global_load_lds_dwordx4 v[182:183], off
	v_lshl_add_u64 v[182:183], s[86:87], 0, v[134:135]
	s_mov_b32 m0, s1
	s_nop 0
	global_load_lds_dwordx4 v[182:183], off
	s_mov_b32 m0, s34
	s_nop 0
	global_load_lds_dwordx4 v[218:219], off
	s_waitcnt vmcnt(8)
	s_waitcnt lgkmcnt(0)
	s_barrier
; #define PG8_STAGE(bufoff, gbase, voff) do { _Pragma("unroll") for (int _i = 0; _i < 2; ++_i) \
;         __builtin_amdgcn_global_load_lds((const unsigned*)((const char*)(gbase) + (voff)[_i]), (PG8_LAS unsigned*)(lds + (bufoff) + ldsw + _i * 8192), 16, 0, 0); } while (0)
; #define PG8_LDA(dst, b, h) do { _Pragma("unroll") for (int m = 0; m < 4; ++m) _Pragma("unroll") for (int k = 0; k < 2; ++k) dst[m][k] = *(const PG8_LAS bf16x8*)(lds + PG8_SA(b, h) + aoff + m * 2048 + k * 1024); } while (0)
; #define PG8_LDB(dst, b, h) do { _Pragma("unroll") for (int n = 0; n < 2; ++n) _Pragma("unroll") for (int k = 0; k < 2; ++k) dst[n][k] = *(const PG8_LAS bf16x8*)(lds + PG8_SB(b, h) + boff + n * 2048 + k * 1024); } while (0)
; #define PG8_MMA(ai, bj, At, Bt) do { __builtin_amdgcn_s_setprio(1); _Pragma("unroll") for (int m = 0; m < 4; ++m) _Pragma("unroll") for (int n = 0; n < 2; ++n) _Pragma("unroll") for (int k = 0; k < 2; ++k) \
;         acc[ai][bj][m][n] = __builtin_amdgcn_mfma_f32_16x16x32_bf16(Bt[n][k], At[m][k], acc[ai][bj][m][n], 0, 0, 0); __builtin_amdgcn_s_setprio(0); } while (0)
; #define PG8_WAIT_V(n) asm volatile("s_waitcnt vmcnt(" #n ")" ::: "memory")
; #define PG8_WAIT_L(n) asm volatile("s_waitcnt lgkmcnt(" #n ")" ::: "memory")
; #define PG8_BAR __builtin_amdgcn_s_barrier()
; #define PG8_SCHED __builtin_amdgcn_sched_barrier(0)
; template <class Epi, class Sched, bool ALIGN_EPI = false, bool SP2 = false>
; __device__ __forceinline__ void gemm_phase(PG8_LAS unsigned char* lds, const Gemm g, const Sched& S, const Epi& E, const int tid) {
;     ...
;             PG8_WAIT_V(8); PG8_WAIT_L(0); PG8_BAR; PG8_MMA(0, 0, At, B0); PG8_MMA(0, 1, At, B1); PG8_BAR; PG8_SCHED;
;             PG8_LDA(At, 0, 1); PG8_STAGE(PG8_SB(0, 0), b2, voffB); PG8_STAGE(PG8_SB(0, 1), b2 + hstep, voffB); PG8_STAGE(PG8_SA(0, 0), a2, voffA);
;             PG8_WAIT_V(8); PG8_WAIT_L(0); PG8_BAR; PG8_MMA(1, 0, At, B0); PG8_MMA(1, 1, At, B1); PG8_BAR; PG8_SCHED;
;             PG8_LDB(B0, 1, 0); PG8_LDB(B1, 1, 1); PG8_SCHED; PG8_LDA(At, 1, 0); PG8_STAGE(PG8_SA(0, 1), a2 + hstep, voffA);
;             PG8_WAIT_V(8); PG8_WAIT_L(0); PG8_BAR; PG8_MMA(0, 0, At, B0); PG8_MMA(0, 1, At, B1); PG8_BAR; PG8_SCHED;
	v_mfma_f32_16x16x32_bf16 v[62:65], v[142:145], v[174:177], v[62:65]
	v_mfma_f32_16x16x32_bf16 v[62:65], v[146:149], v[184:187], v[62:65]
	v_mfma_f32_16x16x32_bf16 v[54:57], v[150:153], v[174:177], v[54:57]
	v_mfma_f32_16x16x32_bf16 v[54:57], v[154:157], v[184:187], v[54:57]
	v_mfma_f32_16x16x32_bf16 v[46:49], v[142:145], v[188:191], v[46:49]
	v_mfma_f32_16x16x32_bf16 v[46:49], v[146:149], v[192:195], v[46:49]
	v_mfma_f32_16x16x32_bf16 v[38:41], v[150:153], v[188:191], v[38:41]
	v_mfma_f32_16x16x32_bf16 v[38:41], v[154:157], v[192:195], v[38:41]
	v_mfma_f32_16x16x32_bf16 v[30:33], v[142:145], v[196:199], v[30:33]
	v_mfma_f32_16x16x32_bf16 v[30:33], v[146:149], v[200:203], v[30:33]
	v_mfma_f32_16x16x32_bf16 v[22:25], v[150:153], v[196:199], v[22:25]
	v_mfma_f32_16x16x32_bf16 v[22:25], v[154:157], v[200:203], v[22:25]
	v_mfma_f32_16x16x32_bf16 v[14:17], v[142:145], v[204:207], v[14:17]
	v_mfma_f32_16x16x32_bf16 v[14:17], v[146:149], v[214:217], v[14:17]
	v_mfma_f32_16x16x32_bf16 v[6:9], v[150:153], v[204:207], v[6:9]
	v_mfma_f32_16x16x32_bf16 v[6:9], v[154:157], v[214:217], v[6:9]
	v_mfma_f32_16x16x32_bf16 v[58:61], v[158:161], v[174:177], v[58:61]
	v_mfma_f32_16x16x32_bf16 v[58:61], v[162:165], v[184:187], v[58:61]
	v_mfma_f32_16x16x32_bf16 v[50:53], v[166:169], v[174:177], v[50:53]
	v_mfma_f32_16x16x32_bf16 v[50:53], v[170:173], v[184:187], v[50:53]
	v_mfma_f32_16x16x32_bf16 v[42:45], v[158:161], v[188:191], v[42:45]
	v_mfma_f32_16x16x32_bf16 v[42:45], v[162:165], v[192:195], v[42:45]
	v_mfma_f32_16x16x32_bf16 v[34:37], v[166:169], v[188:191], v[34:37]
	v_mfma_f32_16x16x32_bf16 v[34:37], v[170:173], v[192:195], v[34:37]
	v_mfma_f32_16x16x32_bf16 v[26:29], v[158:161], v[196:199], v[26:29]
	v_mfma_f32_16x16x32_bf16 v[26:29], v[162:165], v[200:203], v[26:29]
	v_mfma_f32_16x16x32_bf16 v[18:21], v[166:169], v[196:199], v[18:21]
	v_mfma_f32_16x16x32_bf16 v[18:21], v[170:173], v[200:203], v[18:21]
	v_mfma_f32_16x16x32_bf16 v[10:13], v[158:161], v[204:207], v[10:13]
	v_mfma_f32_16x16x32_bf16 v[10:13], v[162:165], v[214:217], v[10:13]
	v_mfma_f32_16x16x32_bf16 v[2:5], v[166:169], v[204:207], v[2:5]
	v_mfma_f32_16x16x32_bf16 v[2:5], v[170:173], v[214:217], v[2:5]
	s_barrier
	ds_read_b128 v[142:145], v222 offset:32768
	ds_read_b128 v[146:149], v222 offset:33792
	ds_read_b128 v[150:153], v222 offset:34816
	ds_read_b128 v[154:157], v222 offset:35840
	ds_read_b128 v[158:161], v222 offset:49152
	ds_read_b128 v[162:165], v222 offset:50176
	ds_read_b128 v[166:169], v222 offset:51200
	ds_read_b128 v[170:173], v222 offset:52224
	s_add_u32 s86, s86, 0x40000
	s_addc_u32 s87, s87, 0
	s_mov_b32 m0, s35
	v_lshl_add_u64 v[220:221], s[86:87], 0, v[134:135]
	ds_read_b128 v[174:177], v140 offset:32768
	ds_read_b128 v[184:187], v140 offset:33792
	ds_read_b128 v[188:191], v140 offset:34816
	ds_read_b128 v[192:195], v140 offset:35840
	ds_read_b128 v[196:199], v140 offset:36864
	ds_read_b128 v[200:203], v140 offset:37888
	ds_read_b128 v[204:207], v140 offset:38912
	ds_read_b128 v[214:217], v140 offset:39936
	global_load_lds_dwordx4 v[220:221], off
	v_lshl_add_u64 v[220:221], s[86:87], 0, v[132:133]
	s_mov_b32 m0, s88
	s_nop 0
	global_load_lds_dwordx4 v[220:221], off
	s_waitcnt vmcnt(8)
	s_waitcnt lgkmcnt(0)
	s_barrier
	v_mfma_f32_16x16x32_bf16 v[126:129], v[142:145], v[174:177], v[126:129]
	v_mfma_f32_16x16x32_bf16 v[126:129], v[146:149], v[184:187], v[126:129]
	v_mfma_f32_16x16x32_bf16 v[118:121], v[150:153], v[174:177], v[118:121]
	v_mfma_f32_16x16x32_bf16 v[118:121], v[154:157], v[184:187], v[118:121]
	v_mfma_f32_16x16x32_bf16 v[110:113], v[142:145], v[188:191], v[110:113]
	v_mfma_f32_16x16x32_bf16 v[110:113], v[146:149], v[192:195], v[110:113]
	v_mfma_f32_16x16x32_bf16 v[102:105], v[150:153], v[188:191], v[102:105]
	v_mfma_f32_16x16x32_bf16 v[102:105], v[154:157], v[192:195], v[102:105]
	v_mfma_f32_16x16x32_bf16 v[94:97], v[142:145], v[196:199], v[94:97]
	v_mfma_f32_16x16x32_bf16 v[94:97], v[146:149], v[200:203], v[94:97]
	v_mfma_f32_16x16x32_bf16 v[86:89], v[150:153], v[196:199], v[86:89]
	v_mfma_f32_16x16x32_bf16 v[86:89], v[154:157], v[200:203], v[86:89]
	v_mfma_f32_16x16x32_bf16 v[78:81], v[142:145], v[204:207], v[78:81]
	v_mfma_f32_16x16x32_bf16 v[78:81], v[146:149], v[214:217], v[78:81]
	v_mfma_f32_16x16x32_bf16 v[70:73], v[150:153], v[204:207], v[70:73]
	v_mfma_f32_16x16x32_bf16 v[70:73], v[154:157], v[214:217], v[70:73]
	v_mfma_f32_16x16x32_bf16 v[122:125], v[158:161], v[174:177], v[122:125]
	v_mfma_f32_16x16x32_bf16 v[122:125], v[162:165], v[184:187], v[122:125]
	v_mfma_f32_16x16x32_bf16 v[114:117], v[166:169], v[174:177], v[114:117]
	v_mfma_f32_16x16x32_bf16 v[114:117], v[170:173], v[184:187], v[114:117]
	v_mfma_f32_16x16x32_bf16 v[106:109], v[158:161], v[188:191], v[106:109]
	v_mfma_f32_16x16x32_bf16 v[106:109], v[162:165], v[192:195], v[106:109]
	v_mfma_f32_16x16x32_bf16 v[98:101], v[166:169], v[188:191], v[98:101]
	v_mfma_f32_16x16x32_bf16 v[98:101], v[170:173], v[192:195], v[98:101]
	v_mfma_f32_16x16x32_bf16 v[90:93], v[158:161], v[196:199], v[90:93]
	v_mfma_f32_16x16x32_bf16 v[90:93], v[162:165], v[200:203], v[90:93]
	v_mfma_f32_16x16x32_bf16 v[82:85], v[166:169], v[196:199], v[82:85]
	v_mfma_f32_16x16x32_bf16 v[82:85], v[170:173], v[200:203], v[82:85]
	v_mfma_f32_16x16x32_bf16 v[74:77], v[158:161], v[204:207], v[74:77]
	v_mfma_f32_16x16x32_bf16 v[74:77], v[162:165], v[214:217], v[74:77]
	v_mfma_f32_16x16x32_bf16 v[66:69], v[166:169], v[204:207], v[66:69]
	v_mfma_f32_16x16x32_bf16 v[66:69], v[170:173], v[214:217], v[66:69]
	s_barrier
; #define PG8_STAGE(bufoff, gbase, voff) do { _Pragma("unroll") for (int _i = 0; _i < 2; ++_i) \
;         __builtin_amdgcn_global_load_lds((const unsigned*)((const char*)(gbase) + (voff)[_i]), (PG8_LAS unsigned*)(lds + (bufoff) + ldsw + _i * 8192), 16, 0, 0); } while (0)
; #define PG8_LDA(dst, b, h) do { _Pragma("unroll") for (int m = 0; m < 4; ++m) _Pragma("unroll") for (int k = 0; k < 2; ++k) dst[m][k] = *(const PG8_LAS bf16x8*)(lds + PG8_SA(b, h) + aoff + m * 2048 + k * 1024); } while (0)
; #define PG8_MMA(ai, bj, At, Bt) do { __builtin_amdgcn_s_setprio(1); _Pragma("unroll") for (int m = 0; m < 4; ++m) _Pragma("unroll") for (int n = 0; n < 2; ++n) _Pragma("unroll") for (int k = 0; k < 2; ++k) \
;         acc[ai][bj][m][n] = __builtin_amdgcn_mfma_f32_16x16x32_bf16(Bt[n][k], At[m][k], acc[ai][bj][m][n], 0, 0, 0); __builtin_amdgcn_s_setprio(0); } while (0)
; #define PG8_WAIT_V(n) asm volatile("s_waitcnt vmcnt(" #n ")" ::: "memory")
; #define PG8_WAIT_L(n) asm volatile("s_waitcnt lgkmcnt(" #n ")" ::: "memory")
; #define PG8_BAR __builtin_amdgcn_s_barrier()
; #define PG8_SCHED __builtin_amdgcn_sched_barrier(0)
; template <class Epi, class Sched, bool ALIGN_EPI = false, bool SP2 = false>
; __device__ __forceinline__ void gemm_phase(PG8_LAS unsigned char* lds, const Gemm g, const Sched& S, const Epi& E, const int tid) {
;     ...
;         for (int t = 0; t < nt; t += 2) {
;     ...
;             PG8_LDA(At, 1, 1); PG8_STAGE(PG8_SB(1, 0), b3, voffB); PG8_STAGE(PG8_SB(1, 1), b3 + hstep, voffB); PG8_STAGE(PG8_SA(1, 0), a3, voffA);
;             PG8_WAIT_V(8); PG8_WAIT_L(0); PG8_BAR; PG8_MMA(1, 0, At, B0); PG8_MMA(1, 1, At, B1); PG8_BAR; PG8_SCHED;
	s_mov_b32 m0, s0
	v_lshl_add_u64 v[178:179], v[178:179], 0, s[12:13]
	s_add_u32 s84, s84, 0x40080
	ds_read_b128 v[174:177], v140 offset:49152
	ds_read_b128 v[184:187], v140 offset:50176
	ds_read_b128 v[188:191], v140 offset:51200
	ds_read_b128 v[192:195], v140 offset:52224
	ds_read_b128 v[196:199], v140 offset:53248
	ds_read_b128 v[200:203], v140 offset:54272
	ds_read_b128 v[204:207], v140 offset:55296
	ds_read_b128 v[214:217], v140 offset:56320
	global_load_lds_dwordx4 v[178:179], off
	v_lshl_add_u64 v[178:179], v[180:181], 0, s[12:13]
	s_mov_b32 m0, s17
	s_addc_u32 s85, s85, 0
	global_load_lds_dwordx4 v[178:179], off
	v_lshl_add_u64 v[178:179], s[84:85], 0, v[0:1]
	s_mov_b32 m0, s51
	s_nop 0
	global_load_lds_dwordx4 v[178:179], off
	v_lshl_add_u64 v[178:179], s[84:85], 0, v[130:131]
	s_mov_b32 m0, s26
	s_nop 0
	global_load_lds_dwordx4 v[178:179], off
	v_lshl_add_u64 v[178:179], v[182:183], 0, s[12:13]
	s_mov_b32 m0, s91
	s_nop 0
	global_load_lds_dwordx4 v[178:179], off
	v_lshl_add_u64 v[178:179], v[218:219], 0, s[12:13]
	s_mov_b32 m0, s50
	s_nop 0
	global_load_lds_dwordx4 v[178:179], off
	s_waitcnt vmcnt(8)
	s_waitcnt lgkmcnt(0)
	s_barrier
	v_mfma_f32_16x16x32_bf16 v[62:65], v[142:145], v[174:177], v[62:65]
	v_mfma_f32_16x16x32_bf16 v[62:65], v[146:149], v[184:187], v[62:65]
	v_mfma_f32_16x16x32_bf16 v[54:57], v[150:153], v[174:177], v[54:57]
	v_mfma_f32_16x16x32_bf16 v[54:57], v[154:157], v[184:187], v[54:57]
	v_mfma_f32_16x16x32_bf16 v[46:49], v[142:145], v[188:191], v[46:49]
	v_mfma_f32_16x16x32_bf16 v[46:49], v[146:149], v[192:195], v[46:49]
	v_mfma_f32_16x16x32_bf16 v[38:41], v[150:153], v[188:191], v[38:41]
	v_mfma_f32_16x16x32_bf16 v[38:41], v[154:157], v[192:195], v[38:41]
	v_mfma_f32_16x16x32_bf16 v[30:33], v[142:145], v[196:199], v[30:33]
	v_mfma_f32_16x16x32_bf16 v[30:33], v[146:149], v[200:203], v[30:33]
	v_mfma_f32_16x16x32_bf16 v[22:25], v[150:153], v[196:199], v[22:25]
	v_mfma_f32_16x16x32_bf16 v[22:25], v[154:157], v[200:203], v[22:25]
	v_mfma_f32_16x16x32_bf16 v[14:17], v[142:145], v[204:207], v[14:17]
	v_mfma_f32_16x16x32_bf16 v[14:17], v[146:149], v[214:217], v[14:17]
	v_mfma_f32_16x16x32_bf16 v[6:9], v[150:153], v[204:207], v[6:9]
	v_mfma_f32_16x16x32_bf16 v[6:9], v[154:157], v[214:217], v[6:9]
	v_mfma_f32_16x16x32_bf16 v[58:61], v[158:161], v[174:177], v[58:61]
	v_mfma_f32_16x16x32_bf16 v[58:61], v[162:165], v[184:187], v[58:61]
	v_mfma_f32_16x16x32_bf16 v[50:53], v[166:169], v[174:177], v[50:53]
	v_mfma_f32_16x16x32_bf16 v[50:53], v[170:173], v[184:187], v[50:53]
	v_mfma_f32_16x16x32_bf16 v[42:45], v[158:161], v[188:191], v[42:45]
	v_mfma_f32_16x16x32_bf16 v[42:45], v[162:165], v[192:195], v[42:45]
	v_mfma_f32_16x16x32_bf16 v[34:37], v[166:169], v[188:191], v[34:37]
	v_mfma_f32_16x16x32_bf16 v[34:37], v[170:173], v[192:195], v[34:37]
	v_mfma_f32_16x16x32_bf16 v[26:29], v[158:161], v[196:199], v[26:29]
	v_mfma_f32_16x16x32_bf16 v[26:29], v[162:165], v[200:203], v[26:29]
	v_mfma_f32_16x16x32_bf16 v[18:21], v[166:169], v[196:199], v[18:21]
	v_mfma_f32_16x16x32_bf16 v[18:21], v[170:173], v[200:203], v[18:21]
	v_mfma_f32_16x16x32_bf16 v[10:13], v[158:161], v[204:207], v[10:13]
	v_mfma_f32_16x16x32_bf16 v[10:13], v[162:165], v[214:217], v[10:13]
	v_mfma_f32_16x16x32_bf16 v[2:5], v[166:169], v[204:207], v[2:5]
	v_mfma_f32_16x16x32_bf16 v[2:5], v[170:173], v[214:217], v[2:5]
	s_barrier
	s_add_i32 s43, s43, 2
	s_add_u32 s30, s30, 0x100
	s_addc_u32 s31, s31, 0
	s_add_u32 s24, s24, 0x100
	s_addc_u32 s41, s41, 0
	s_cmp_gt_u32 s43, 13
	s_cbranch_scc0 .LBB0_713
	s_and_b64 vcc, exec, s[38:39]
	s_cbranch_vccz .LBB0_716
	s_barrier
